# fgate: weight LDS-DMA issued before the x loads, counted vmcnt(9) before the barrier so the x-load latency overlaps barrier + LDS weight reads (strategy 1)
# baseline (speedup 1.0000x reference)
; __device__ __forceinline__ float lane_get(float v, int src_lane) { return __builtin_bit_cast(float, __builtin_amdgcn_ds_bpermute(src_lane << 2, __builtin_bit_cast(int, v))); }
; __device__ __forceinline__ void fgate_phase(const bfr* x, const float* wf, const float* bfg, float* cl, float* ctot, LAS float* scr, int bx, int G, int tid, int lane, int wave) {
;     ...
;         for (int j = 0; j < 8; j += 2) { const int row = chunk * 64 + wave * 8 + j; typedef unsigned u32x2 __attribute__((ext_vector_type(2))); const u32x2* xa = (const u32x2*)(x + (size_t)row * D) + lane; const u32x2* xb2 = xa + D / 4; f32x4 va[4], vb[4]; float r[18]; int zo = 0; asm volatile("" : "+v"(zo));
; #pragma unroll
;             for (int jj = 0; jj < 4; ++jj) { const u32x2 wa = xa[64 * jj], wb = xb2[64 * jj]; va[jj] = (f32x4){bf_lo(wa.x), bf_hi(wa.x), bf_lo(wa.y), bf_hi(wa.y)}; vb[jj] = (f32x4){bf_lo(wb.x), bf_hi(wb.x), bf_lo(wb.y), bf_hi(wb.y)}; }
;             r[16] = 0.f; r[17] = 0.f;
; #pragma unroll
;             for (int jj = 0; jj < 4; ++jj) { r[16] += (va[jj].x * va[jj].x + va[jj].y * va[jj].y) + (va[jj].z * va[jj].z + va[jj].w * va[jj].w); r[17] += (vb[jj].x * vb[jj].x + vb[jj].y * vb[jj].y) + (vb[jj].z * vb[jj].z + vb[jj].w * vb[jj].w); }
; #pragma unroll
;             for (int h = 0; h < NH; ++h) { const f32x4* wr = (const f32x4*)(wf + h * D) + lane + zo; float da = 0.f, db = 0.f;
; #pragma unroll
;                 for (int jj = 0; jj < 4; ++jj) { const f32x4 w = wr[64 * jj]; da += (va[jj].x * w.x + va[jj].y * w.y) + (va[jj].z * w.z + va[jj].w * w.w); db += (vb[jj].x * w.x + vb[jj].y * w.y) + (vb[jj].z * w.z + vb[jj].w * w.w); }
;                 r[h] = da; r[8 + h] = db; }
; #pragma unroll
;             for (int o = 1; o < 64; o <<= 1) {
; #pragma unroll
;                 for (int q = 0; q < 18; ++q) r[q] += lane_get(r[q], lane ^ o); }
;             const float rsa = rsqrtf(r[16] * (1.f / D) + EPS), rsb = rsqrtf(r[17] * (1.f / D) + EPS);
;             if (lane < 16) { const int h = lane & 7; float dsel = r[0];
; #pragma unroll
;                 for (int q = 1; q < 16; ++q) dsel = (lane == q) ? r[q] : dsel;
;                 const float zz = dsel * (lane < 8 ? rsa : rsb) + bfg[h]; const float lf = fminf(zz, 0.f) - 0.6931471805599453f * __builtin_amdgcn_logf(1.0f + __builtin_amdgcn_exp2f(-LOG2E * fabsf(zz)));
;                 scr[(wave * 8 + j + (lane >> 3)) * 8 + h] = lf; } }
.LBB0_424:
	s_mov_b32 s38, s33
	s_ashr_i32 s39, s33, 31
	s_lshl_b64 s[38:39], s[38:39], 11
	s_mov_b64 s[98:99], 0x1000
	s_mov_b64 s[100:101], 0x2000
	v_lshl_add_u64 v[38:39], v[28:29], 0, s[38:39]
	v_mov_b32_e32 v160, v158
	v_mov_b32_e32 v161, 0
	v_lshl_add_u64 v[38:39], v[160:161], 3, v[38:39]
	v_lshl_add_u64 v[98:99], v[38:39], 0, s[98:99]
	v_lshrrev_b32_e32 v62, 6, v128
	v_lshlrev_b32_e32 v63, 4, v158
	v_readfirstlane_b32 s20, v30
	v_readfirstlane_b32 s21, v31
	v_readfirstlane_b32 s66, v62
	s_lshl_b32 s66, s66, 12
	s_add_u32 s20, s20, s66
	s_addc_u32 s21, s21, 0
	s_add_i32 s66, s66, 0x1000
	s_mov_b32 m0, s66
	s_nop 0
	global_load_lds_dwordx4 v63, s[20:21]
	s_add_u32 s20, s20, 0x400
	s_addc_u32 s21, s21, 0
	s_add_i32 s66, s66, 0x400
	s_mov_b32 m0, s66
	s_nop 0
	global_load_lds_dwordx4 v63, s[20:21]
	s_add_u32 s20, s20, 0x400
	s_addc_u32 s21, s21, 0
	s_add_i32 s66, s66, 0x400
	s_mov_b32 m0, s66
	s_nop 0
	global_load_lds_dwordx4 v63, s[20:21]
	s_add_u32 s20, s20, 0x400
	s_addc_u32 s21, s21, 0
	s_add_i32 s66, s66, 0x400
	s_mov_b32 m0, s66
	s_nop 0
	global_load_lds_dwordx4 v63, s[20:21]
	global_load_dwordx4 v[112:115], v[38:39], off
	global_load_dwordx4 v[108:111], v[38:39], off offset:1024
	global_load_dwordx4 v[104:107], v[38:39], off offset:2048
	global_load_dwordx4 v[100:103], v[38:39], off offset:3072
	global_load_dwordx4 v[84:87], v[98:99], off
	global_load_dwordx4 v[80:83], v[98:99], off offset:1024
	global_load_dwordx4 v[76:79], v[98:99], off offset:2048
	global_load_dwordx4 v[72:75], v[98:99], off offset:3072
	global_load_dword v61, v[32:33], off
	s_waitcnt vmcnt(9)
	s_barrier
	v_lshlrev_b32_e32 v63, 5, v158
	ds_read_b128 v[248:251], v63 offset:4096
	ds_read_b128 v[244:247], v63 offset:4112
	ds_read_b128 v[240:243], v63 offset:6144
	ds_read_b128 v[236:239], v63 offset:6160
	ds_read_b128 v[232:235], v63 offset:8192
	ds_read_b128 v[228:231], v63 offset:8208
	ds_read_b128 v[224:227], v63 offset:10240
	ds_read_b128 v[220:223], v63 offset:10256
	ds_read_b128 v[216:219], v63 offset:12288
	ds_read_b128 v[212:215], v63 offset:12304
	ds_read_b128 v[208:211], v63 offset:14336
	ds_read_b128 v[204:207], v63 offset:14352
	ds_read_b128 v[200:203], v63 offset:16384
	ds_read_b128 v[196:199], v63 offset:16400
	ds_read_b128 v[192:195], v63 offset:18432
	ds_read_b128 v[188:191], v63 offset:18448
	ds_read_b128 v[182:185], v63 offset:20480
	ds_read_b128 v[178:181], v63 offset:20496
	ds_read_b128 v[174:177], v63 offset:22528
	ds_read_b128 v[170:173], v63 offset:22544
	ds_read_b128 v[166:169], v63 offset:24576
	ds_read_b128 v[162:165], v63 offset:24592
	ds_read_b128 v[154:157], v63 offset:26624
	ds_read_b128 v[150:153], v63 offset:26640
	ds_read_b128 v[146:149], v63 offset:28672
	ds_read_b128 v[142:145], v63 offset:28688
	ds_read_b128 v[138:141], v63 offset:30720
	ds_read_b128 v[134:137], v63 offset:30736
	ds_read_b128 v[130:133], v63 offset:32768
	ds_read_b128 v[124:127], v63 offset:32784
	ds_read_b128 v[120:123], v63 offset:34816
	ds_read_b128 v[116:119], v63 offset:34832
	v_and_b32_e32 v64, 7, v158
	v_cmp_eq_u32_e64 s[6:7], 1, v64
	v_cmp_eq_u32_e64 s[8:9], 2, v64
	v_cmp_eq_u32_e64 s[10:11], 3, v64
	v_cmp_eq_u32_e64 s[12:13], 4, v64
	v_cmp_eq_u32_e64 s[14:15], 5, v64
	v_cmp_eq_u32_e64 s[16:17], 6, v64
	v_cmp_eq_u32_e64 s[18:19], 7, v64
	v_lshrrev_b32_e32 v62, 4, v158
	v_lshlrev_b32_e32 v62, 5, v62
	v_sub_u32_e32 v65, v95, v62
	s_mov_b32 s40, 0xffff0000
	s_waitcnt vmcnt(0) lgkmcnt(0)
	v_lshlrev_b32_e32 v97, 16, v112
	v_and_b32_e32 v159, s40, v112
	v_lshlrev_b32_e32 v187, 16, v113
	v_and_b32_e32 v0, s40, v113
	v_lshlrev_b32_e32 v1, 16, v114
	v_and_b32_e32 v2, s40, v114
	v_lshlrev_b32_e32 v3, 16, v115
	v_and_b32_e32 v4, s40, v115
	v_lshlrev_b32_e32 v5, 16, v108
	v_and_b32_e32 v6, s40, v108
	v_lshlrev_b32_e32 v7, 16, v109
	v_and_b32_e32 v8, s40, v109
	v_lshlrev_b32_e32 v9, 16, v110
	v_and_b32_e32 v10, s40, v110
	v_lshlrev_b32_e32 v11, 16, v111
	v_and_b32_e32 v12, s40, v111
	v_lshl_add_u64 v[38:39], v[38:39], 0, s[100:101]
	v_lshl_add_u64 v[98:99], v[98:99], 0, s[100:101]
	global_load_dwordx4 v[112:115], v[38:39], off
	global_load_dwordx4 v[108:111], v[38:39], off offset:1024
	v_mul_f32_e32 v57, v97, v97
	v_mul_f32_e32 v13, v97, v248
	v_mul_f32_e32 v14, v97, v232
	v_mul_f32_e32 v15, v97, v216
	v_mul_f32_e32 v16, v97, v200
	v_mul_f32_e32 v17, v97, v182
	v_mul_f32_e32 v18, v97, v166
	v_mul_f32_e32 v19, v97, v146
	v_mul_f32_e32 v20, v97, v130
	v_fmac_f32_e32 v57, v159, v159
	v_fmac_f32_e32 v13, v159, v249
	v_fmac_f32_e32 v14, v159, v233
	v_fmac_f32_e32 v15, v159, v217
	v_fmac_f32_e32 v16, v159, v201
	v_fmac_f32_e32 v17, v159, v183
	v_fmac_f32_e32 v18, v159, v167
	v_fmac_f32_e32 v19, v159, v147
	v_fmac_f32_e32 v20, v159, v131
	v_fmac_f32_e32 v57, v187, v187
	v_fmac_f32_e32 v13, v187, v250
	v_fmac_f32_e32 v14, v187, v234
	v_fmac_f32_e32 v15, v187, v218
	v_fmac_f32_e32 v16, v187, v202
	v_fmac_f32_e32 v17, v187, v184
	v_fmac_f32_e32 v18, v187, v168
	v_fmac_f32_e32 v19, v187, v148
	v_fmac_f32_e32 v20, v187, v132
	v_fmac_f32_e32 v57, v0, v0
	v_fmac_f32_e32 v13, v0, v251
	v_fmac_f32_e32 v14, v0, v235
	v_fmac_f32_e32 v15, v0, v219
	v_fmac_f32_e32 v16, v0, v203
	v_fmac_f32_e32 v17, v0, v185
	v_fmac_f32_e32 v18, v0, v169
	v_fmac_f32_e32 v19, v0, v149
	v_fmac_f32_e32 v20, v0, v133
	v_fmac_f32_e32 v57, v1, v1
	v_fmac_f32_e32 v13, v1, v244
	v_fmac_f32_e32 v14, v1, v228
	v_fmac_f32_e32 v15, v1, v212
	v_fmac_f32_e32 v16, v1, v196
	v_fmac_f32_e32 v17, v1, v178
	v_fmac_f32_e32 v18, v1, v162
	v_fmac_f32_e32 v19, v1, v142
	v_fmac_f32_e32 v20, v1, v124
	v_fmac_f32_e32 v57, v2, v2
	v_fmac_f32_e32 v13, v2, v245
	v_fmac_f32_e32 v14, v2, v229
	v_fmac_f32_e32 v15, v2, v213
; __device__ __forceinline__ void fgate_phase(const bfr* x, const float* wf, const float* bfg, float* cl, float* ctot, LAS float* scr, int bx, int G, int tid, int lane, int wave) {
;     ...
;             for (int jj = 0; jj < 4; ++jj) { const u32x2 wa = xa[64 * jj], wb = xb2[64 * jj]; va[jj] = (f32x4){bf_lo(wa.x), bf_hi(wa.x), bf_lo(wa.y), bf_hi(wa.y)}; vb[jj] = (f32x4){bf_lo(wb.x), bf_hi(wb.x), bf_lo(wb.y), bf_hi(wb.y)}; }
;             r[16] = 0.f; r[17] = 0.f;
; #pragma unroll
;             for (int jj = 0; jj < 4; ++jj) { r[16] += (va[jj].x * va[jj].x + va[jj].y * va[jj].y) + (va[jj].z * va[jj].z + va[jj].w * va[jj].w); r[17] += (vb[jj].x * vb[jj].x + vb[jj].y * vb[jj].y) + (vb[jj].z * vb[jj].z + vb[jj].w * vb[jj].w); }
; #pragma unroll
;             for (int h = 0; h < NH; ++h) { const f32x4* wr = (const f32x4*)(wf + h * D) + lane + zo; float da = 0.f, db = 0.f;
; #pragma unroll
;                 for (int jj = 0; jj < 4; ++jj) { const f32x4 w = wr[64 * jj]; da += (va[jj].x * w.x + va[jj].y * w.y) + (va[jj].z * w.z + va[jj].w * w.w); db += (vb[jj].x * w.x + vb[jj].y * w.y) + (vb[jj].z * w.z + vb[jj].w * w.w); }
;                 r[h] = da; r[8 + h] = db; }
	v_fmac_f32_e32 v16, v2, v197
	v_fmac_f32_e32 v17, v2, v179
	v_fmac_f32_e32 v18, v2, v163
	v_fmac_f32_e32 v19, v2, v143
	v_fmac_f32_e32 v20, v2, v125
	v_fmac_f32_e32 v57, v3, v3
	v_fmac_f32_e32 v13, v3, v246
	v_fmac_f32_e32 v14, v3, v230
	v_fmac_f32_e32 v15, v3, v214
	v_fmac_f32_e32 v16, v3, v198
	v_fmac_f32_e32 v17, v3, v180
	v_fmac_f32_e32 v18, v3, v164
	v_fmac_f32_e32 v19, v3, v144
	v_fmac_f32_e32 v20, v3, v126
	v_fmac_f32_e32 v57, v4, v4
	v_fmac_f32_e32 v13, v4, v247
	v_fmac_f32_e32 v14, v4, v231
	v_fmac_f32_e32 v15, v4, v215
	v_fmac_f32_e32 v16, v4, v199
	v_fmac_f32_e32 v17, v4, v181
	v_fmac_f32_e32 v18, v4, v165
	v_fmac_f32_e32 v19, v4, v145
	v_fmac_f32_e32 v20, v4, v127
	v_fmac_f32_e32 v57, v5, v5
	v_fmac_f32_e32 v13, v5, v240
	v_fmac_f32_e32 v14, v5, v224
	v_fmac_f32_e32 v15, v5, v208
	v_fmac_f32_e32 v16, v5, v192
	v_fmac_f32_e32 v17, v5, v174
	v_fmac_f32_e32 v18, v5, v154
	v_fmac_f32_e32 v19, v5, v138
	v_fmac_f32_e32 v20, v5, v120
	v_fmac_f32_e32 v57, v6, v6
	v_fmac_f32_e32 v13, v6, v241
	v_fmac_f32_e32 v14, v6, v225
	v_fmac_f32_e32 v15, v6, v209
	v_fmac_f32_e32 v16, v6, v193
	v_fmac_f32_e32 v17, v6, v175
	v_fmac_f32_e32 v18, v6, v155
	v_fmac_f32_e32 v19, v6, v139
	v_fmac_f32_e32 v20, v6, v121
	v_fmac_f32_e32 v57, v7, v7
	v_fmac_f32_e32 v13, v7, v242
	v_fmac_f32_e32 v14, v7, v226
	v_fmac_f32_e32 v15, v7, v210
	v_fmac_f32_e32 v16, v7, v194
	v_fmac_f32_e32 v17, v7, v176
	v_fmac_f32_e32 v18, v7, v156
	v_fmac_f32_e32 v19, v7, v140
	v_fmac_f32_e32 v20, v7, v122
	v_fmac_f32_e32 v57, v8, v8
	v_fmac_f32_e32 v13, v8, v243
	v_fmac_f32_e32 v14, v8, v227
	v_fmac_f32_e32 v15, v8, v211
	v_fmac_f32_e32 v16, v8, v195
	v_fmac_f32_e32 v17, v8, v177
	v_fmac_f32_e32 v18, v8, v157
	v_fmac_f32_e32 v19, v8, v141
	v_fmac_f32_e32 v20, v8, v123
	v_fmac_f32_e32 v57, v9, v9
	v_fmac_f32_e32 v13, v9, v236
	v_fmac_f32_e32 v14, v9, v220
	v_fmac_f32_e32 v15, v9, v204
	v_fmac_f32_e32 v16, v9, v188
	v_fmac_f32_e32 v17, v9, v170
	v_fmac_f32_e32 v18, v9, v150
	v_fmac_f32_e32 v19, v9, v134
	v_fmac_f32_e32 v20, v9, v116
	v_fmac_f32_e32 v57, v10, v10
	v_fmac_f32_e32 v13, v10, v237
	v_fmac_f32_e32 v14, v10, v221
	v_fmac_f32_e32 v15, v10, v205
	v_fmac_f32_e32 v16, v10, v189
	v_fmac_f32_e32 v17, v10, v171
	v_fmac_f32_e32 v18, v10, v151
	v_fmac_f32_e32 v19, v10, v135
	v_fmac_f32_e32 v20, v10, v117
	v_fmac_f32_e32 v57, v11, v11
	v_fmac_f32_e32 v13, v11, v238
	v_fmac_f32_e32 v14, v11, v222
	v_fmac_f32_e32 v15, v11, v206
	v_fmac_f32_e32 v16, v11, v190
	v_fmac_f32_e32 v17, v11, v172
	v_fmac_f32_e32 v18, v11, v152
	v_fmac_f32_e32 v19, v11, v136
	v_fmac_f32_e32 v20, v11, v118
	v_fmac_f32_e32 v57, v12, v12
	v_fmac_f32_e32 v13, v12, v239
	v_fmac_f32_e32 v14, v12, v223
	v_fmac_f32_e32 v15, v12, v207
	v_fmac_f32_e32 v16, v12, v191
	v_fmac_f32_e32 v17, v12, v173
	v_fmac_f32_e32 v18, v12, v153
	v_fmac_f32_e32 v19, v12, v137
	v_fmac_f32_e32 v20, v12, v119
	v_lshlrev_b32_e32 v97, 16, v104
	v_and_b32_e32 v159, s40, v104
	v_lshlrev_b32_e32 v187, 16, v105
	v_and_b32_e32 v0, s40, v105
	v_lshlrev_b32_e32 v1, 16, v106
	v_and_b32_e32 v2, s40, v106
	v_lshlrev_b32_e32 v3, 16, v107
	v_and_b32_e32 v4, s40, v107
	v_lshlrev_b32_e32 v5, 16, v100
	v_and_b32_e32 v6, s40, v100
	v_lshlrev_b32_e32 v7, 16, v101
	v_and_b32_e32 v8, s40, v101
	v_lshlrev_b32_e32 v9, 16, v102
	v_and_b32_e32 v10, s40, v102
	v_lshlrev_b32_e32 v11, 16, v103
	v_and_b32_e32 v12, s40, v103
	global_load_dwordx4 v[104:107], v[38:39], off offset:2048
	global_load_dwordx4 v[100:103], v[38:39], off offset:3072
	v_mul_f32_e32 v58, v97, v97
	v_mul_f32_e32 v21, v97, v248
	v_mul_f32_e32 v22, v97, v232
	v_mul_f32_e32 v23, v97, v216
	v_mul_f32_e32 v24, v97, v200
	v_mul_f32_e32 v25, v97, v182
	v_mul_f32_e32 v26, v97, v166
	v_mul_f32_e32 v27, v97, v146
	v_mul_f32_e32 v40, v97, v130
	v_fmac_f32_e32 v58, v159, v159
	v_fmac_f32_e32 v21, v159, v249
	v_fmac_f32_e32 v22, v159, v233
	v_fmac_f32_e32 v23, v159, v217
	v_fmac_f32_e32 v24, v159, v201
	v_fmac_f32_e32 v25, v159, v183
	v_fmac_f32_e32 v26, v159, v167
	v_fmac_f32_e32 v27, v159, v147
	v_fmac_f32_e32 v40, v159, v131
	v_fmac_f32_e32 v58, v187, v187
	v_fmac_f32_e32 v21, v187, v250
	v_fmac_f32_e32 v22, v187, v234
	v_fmac_f32_e32 v23, v187, v218
	v_fmac_f32_e32 v24, v187, v202
	v_fmac_f32_e32 v25, v187, v184
	v_fmac_f32_e32 v26, v187, v168
	v_fmac_f32_e32 v27, v187, v148
	v_fmac_f32_e32 v40, v187, v132
	v_fmac_f32_e32 v58, v0, v0
	v_fmac_f32_e32 v21, v0, v251
	v_fmac_f32_e32 v22, v0, v235
	v_fmac_f32_e32 v23, v0, v219
	v_fmac_f32_e32 v24, v0, v203
	v_fmac_f32_e32 v25, v0, v185
	v_fmac_f32_e32 v26, v0, v169
	v_fmac_f32_e32 v27, v0, v149
	v_fmac_f32_e32 v40, v0, v133
	v_fmac_f32_e32 v58, v1, v1
	v_fmac_f32_e32 v21, v1, v244
	v_fmac_f32_e32 v22, v1, v228
	v_fmac_f32_e32 v23, v1, v212
	v_fmac_f32_e32 v24, v1, v196
	v_fmac_f32_e32 v25, v1, v178
	v_fmac_f32_e32 v26, v1, v162
	v_fmac_f32_e32 v27, v1, v142
	v_fmac_f32_e32 v40, v1, v124
	v_fmac_f32_e32 v58, v2, v2
	v_fmac_f32_e32 v21, v2, v245
	v_fmac_f32_e32 v22, v2, v229
	v_fmac_f32_e32 v23, v2, v213
	v_fmac_f32_e32 v24, v2, v197
	v_fmac_f32_e32 v25, v2, v179
	v_fmac_f32_e32 v26, v2, v163
	v_fmac_f32_e32 v27, v2, v143
	v_fmac_f32_e32 v40, v2, v125
	v_fmac_f32_e32 v58, v3, v3
	v_fmac_f32_e32 v21, v3, v246
	v_fmac_f32_e32 v22, v3, v230
	v_fmac_f32_e32 v23, v3, v214
	v_fmac_f32_e32 v24, v3, v198
	v_fmac_f32_e32 v25, v3, v180
	v_fmac_f32_e32 v26, v3, v164
	v_fmac_f32_e32 v27, v3, v144
	v_fmac_f32_e32 v40, v3, v126
	v_fmac_f32_e32 v58, v4, v4
	v_fmac_f32_e32 v21, v4, v247
	v_fmac_f32_e32 v22, v4, v231
	v_fmac_f32_e32 v23, v4, v215
	v_fmac_f32_e32 v24, v4, v199
	v_fmac_f32_e32 v25, v4, v181
	v_fmac_f32_e32 v26, v4, v165
	v_fmac_f32_e32 v27, v4, v145
; __device__ __forceinline__ void fgate_phase(const bfr* x, const float* wf, const float* bfg, float* cl, float* ctot, LAS float* scr, int bx, int G, int tid, int lane, int wave) {
;     ...
;             for (int jj = 0; jj < 4; ++jj) { const u32x2 wa = xa[64 * jj], wb = xb2[64 * jj]; va[jj] = (f32x4){bf_lo(wa.x), bf_hi(wa.x), bf_lo(wa.y), bf_hi(wa.y)}; vb[jj] = (f32x4){bf_lo(wb.x), bf_hi(wb.x), bf_lo(wb.y), bf_hi(wb.y)}; }
;             r[16] = 0.f; r[17] = 0.f;
; #pragma unroll
;             for (int jj = 0; jj < 4; ++jj) { r[16] += (va[jj].x * va[jj].x + va[jj].y * va[jj].y) + (va[jj].z * va[jj].z + va[jj].w * va[jj].w); r[17] += (vb[jj].x * vb[jj].x + vb[jj].y * vb[jj].y) + (vb[jj].z * vb[jj].z + vb[jj].w * vb[jj].w); }
; #pragma unroll
;             for (int h = 0; h < NH; ++h) { const f32x4* wr = (const f32x4*)(wf + h * D) + lane + zo; float da = 0.f, db = 0.f;
; #pragma unroll
;                 for (int jj = 0; jj < 4; ++jj) { const f32x4 w = wr[64 * jj]; da += (va[jj].x * w.x + va[jj].y * w.y) + (va[jj].z * w.z + va[jj].w * w.w); db += (vb[jj].x * w.x + vb[jj].y * w.y) + (vb[jj].z * w.z + vb[jj].w * w.w); }
;                 r[h] = da; r[8 + h] = db; }
	v_fmac_f32_e32 v40, v4, v127
	v_fmac_f32_e32 v58, v5, v5
	v_fmac_f32_e32 v21, v5, v240
	v_fmac_f32_e32 v22, v5, v224
	v_fmac_f32_e32 v23, v5, v208
	v_fmac_f32_e32 v24, v5, v192
	v_fmac_f32_e32 v25, v5, v174
	v_fmac_f32_e32 v26, v5, v154
	v_fmac_f32_e32 v27, v5, v138
	v_fmac_f32_e32 v40, v5, v120
	v_fmac_f32_e32 v58, v6, v6
	v_fmac_f32_e32 v21, v6, v241
	v_fmac_f32_e32 v22, v6, v225
	v_fmac_f32_e32 v23, v6, v209
	v_fmac_f32_e32 v24, v6, v193
	v_fmac_f32_e32 v25, v6, v175
	v_fmac_f32_e32 v26, v6, v155
	v_fmac_f32_e32 v27, v6, v139
	v_fmac_f32_e32 v40, v6, v121
	v_fmac_f32_e32 v58, v7, v7
	v_fmac_f32_e32 v21, v7, v242
	v_fmac_f32_e32 v22, v7, v226
	v_fmac_f32_e32 v23, v7, v210
	v_fmac_f32_e32 v24, v7, v194
	v_fmac_f32_e32 v25, v7, v176
	v_fmac_f32_e32 v26, v7, v156
	v_fmac_f32_e32 v27, v7, v140
	v_fmac_f32_e32 v40, v7, v122
	v_fmac_f32_e32 v58, v8, v8
	v_fmac_f32_e32 v21, v8, v243
	v_fmac_f32_e32 v22, v8, v227
	v_fmac_f32_e32 v23, v8, v211
	v_fmac_f32_e32 v24, v8, v195
	v_fmac_f32_e32 v25, v8, v177
	v_fmac_f32_e32 v26, v8, v157
	v_fmac_f32_e32 v27, v8, v141
	v_fmac_f32_e32 v40, v8, v123
	v_fmac_f32_e32 v58, v9, v9
	v_fmac_f32_e32 v21, v9, v236
	v_fmac_f32_e32 v22, v9, v220
	v_fmac_f32_e32 v23, v9, v204
	v_fmac_f32_e32 v24, v9, v188
	v_fmac_f32_e32 v25, v9, v170
	v_fmac_f32_e32 v26, v9, v150
	v_fmac_f32_e32 v27, v9, v134
	v_fmac_f32_e32 v40, v9, v116
	v_fmac_f32_e32 v58, v10, v10
	v_fmac_f32_e32 v21, v10, v237
	v_fmac_f32_e32 v22, v10, v221
	v_fmac_f32_e32 v23, v10, v205
	v_fmac_f32_e32 v24, v10, v189
	v_fmac_f32_e32 v25, v10, v171
	v_fmac_f32_e32 v26, v10, v151
	v_fmac_f32_e32 v27, v10, v135
	v_fmac_f32_e32 v40, v10, v117
	v_fmac_f32_e32 v58, v11, v11
	v_fmac_f32_e32 v21, v11, v238
	v_fmac_f32_e32 v22, v11, v222
	v_fmac_f32_e32 v23, v11, v206
	v_fmac_f32_e32 v24, v11, v190
	v_fmac_f32_e32 v25, v11, v172
	v_fmac_f32_e32 v26, v11, v152
	v_fmac_f32_e32 v27, v11, v136
	v_fmac_f32_e32 v40, v11, v118
	v_fmac_f32_e32 v58, v12, v12
	v_fmac_f32_e32 v21, v12, v239
	v_fmac_f32_e32 v22, v12, v223
	v_fmac_f32_e32 v23, v12, v207
	v_fmac_f32_e32 v24, v12, v191
	v_fmac_f32_e32 v25, v12, v173
	v_fmac_f32_e32 v26, v12, v153
	v_fmac_f32_e32 v27, v12, v137
	v_fmac_f32_e32 v40, v12, v119
	v_lshlrev_b32_e32 v97, 16, v84
	v_and_b32_e32 v159, s40, v84
	v_lshlrev_b32_e32 v187, 16, v85
	v_and_b32_e32 v0, s40, v85
	v_lshlrev_b32_e32 v1, 16, v86
	v_and_b32_e32 v2, s40, v86
	v_lshlrev_b32_e32 v3, 16, v87
	v_and_b32_e32 v4, s40, v87
	v_lshlrev_b32_e32 v5, 16, v80
	v_and_b32_e32 v6, s40, v80
	v_lshlrev_b32_e32 v7, 16, v81
	v_and_b32_e32 v8, s40, v81
	v_lshlrev_b32_e32 v9, 16, v82
	v_and_b32_e32 v10, s40, v82
	v_lshlrev_b32_e32 v11, 16, v83
	v_and_b32_e32 v12, s40, v83
	global_load_dwordx4 v[84:87], v[98:99], off
	global_load_dwordx4 v[80:83], v[98:99], off offset:1024
	v_mul_f32_e32 v59, v97, v97
	v_mul_f32_e32 v41, v97, v248
	v_mul_f32_e32 v42, v97, v232
	v_mul_f32_e32 v43, v97, v216
	v_mul_f32_e32 v44, v97, v200
	v_mul_f32_e32 v45, v97, v182
	v_mul_f32_e32 v46, v97, v166
	v_mul_f32_e32 v47, v97, v146
	v_mul_f32_e32 v48, v97, v130
	v_fmac_f32_e32 v59, v159, v159
	v_fmac_f32_e32 v41, v159, v249
	v_fmac_f32_e32 v42, v159, v233
	v_fmac_f32_e32 v43, v159, v217
	v_fmac_f32_e32 v44, v159, v201
	v_fmac_f32_e32 v45, v159, v183
	v_fmac_f32_e32 v46, v159, v167
	v_fmac_f32_e32 v47, v159, v147
	v_fmac_f32_e32 v48, v159, v131
	v_fmac_f32_e32 v59, v187, v187
	v_fmac_f32_e32 v41, v187, v250
	v_fmac_f32_e32 v42, v187, v234
	v_fmac_f32_e32 v43, v187, v218
	v_fmac_f32_e32 v44, v187, v202
	v_fmac_f32_e32 v45, v187, v184
	v_fmac_f32_e32 v46, v187, v168
	v_fmac_f32_e32 v47, v187, v148
	v_fmac_f32_e32 v48, v187, v132
	v_fmac_f32_e32 v59, v0, v0
	v_fmac_f32_e32 v41, v0, v251
	v_fmac_f32_e32 v42, v0, v235
	v_fmac_f32_e32 v43, v0, v219
	v_fmac_f32_e32 v44, v0, v203
	v_fmac_f32_e32 v45, v0, v185
	v_fmac_f32_e32 v46, v0, v169
	v_fmac_f32_e32 v47, v0, v149
	v_fmac_f32_e32 v48, v0, v133
	v_fmac_f32_e32 v59, v1, v1
	v_fmac_f32_e32 v41, v1, v244
	v_fmac_f32_e32 v42, v1, v228
	v_fmac_f32_e32 v43, v1, v212
	v_fmac_f32_e32 v44, v1, v196
	v_fmac_f32_e32 v45, v1, v178
	v_fmac_f32_e32 v46, v1, v162
	v_fmac_f32_e32 v47, v1, v142
	v_fmac_f32_e32 v48, v1, v124
	v_fmac_f32_e32 v59, v2, v2
	v_fmac_f32_e32 v41, v2, v245
	v_fmac_f32_e32 v42, v2, v229
	v_fmac_f32_e32 v43, v2, v213
	v_fmac_f32_e32 v44, v2, v197
	v_fmac_f32_e32 v45, v2, v179
	v_fmac_f32_e32 v46, v2, v163
	v_fmac_f32_e32 v47, v2, v143
	v_fmac_f32_e32 v48, v2, v125
	v_fmac_f32_e32 v59, v3, v3
	v_fmac_f32_e32 v41, v3, v246
	v_fmac_f32_e32 v42, v3, v230
	v_fmac_f32_e32 v43, v3, v214
	v_fmac_f32_e32 v44, v3, v198
	v_fmac_f32_e32 v45, v3, v180
	v_fmac_f32_e32 v46, v3, v164
	v_fmac_f32_e32 v47, v3, v144
	v_fmac_f32_e32 v48, v3, v126
	v_fmac_f32_e32 v59, v4, v4
	v_fmac_f32_e32 v41, v4, v247
	v_fmac_f32_e32 v42, v4, v231
	v_fmac_f32_e32 v43, v4, v215
	v_fmac_f32_e32 v44, v4, v199
	v_fmac_f32_e32 v45, v4, v181
	v_fmac_f32_e32 v46, v4, v165
	v_fmac_f32_e32 v47, v4, v145
	v_fmac_f32_e32 v48, v4, v127
	v_fmac_f32_e32 v59, v5, v5
	v_fmac_f32_e32 v41, v5, v240
	v_fmac_f32_e32 v42, v5, v224
	v_fmac_f32_e32 v43, v5, v208
	v_fmac_f32_e32 v44, v5, v192
	v_fmac_f32_e32 v45, v5, v174
	v_fmac_f32_e32 v46, v5, v154
	v_fmac_f32_e32 v47, v5, v138
	v_fmac_f32_e32 v48, v5, v120
	v_fmac_f32_e32 v59, v6, v6
	v_fmac_f32_e32 v41, v6, v241
	v_fmac_f32_e32 v42, v6, v225
	v_fmac_f32_e32 v43, v6, v209
	v_fmac_f32_e32 v44, v6, v193
	v_fmac_f32_e32 v45, v6, v175
	v_fmac_f32_e32 v46, v6, v155
	v_fmac_f32_e32 v47, v6, v139
	v_fmac_f32_e32 v48, v6, v121
	v_fmac_f32_e32 v59, v7, v7
	v_fmac_f32_e32 v41, v7, v242
	v_fmac_f32_e32 v42, v7, v226
	v_fmac_f32_e32 v43, v7, v210
; __device__ __forceinline__ void fgate_phase(const bfr* x, const float* wf, const float* bfg, float* cl, float* ctot, LAS float* scr, int bx, int G, int tid, int lane, int wave) {
;     ...
;             for (int jj = 0; jj < 4; ++jj) { const u32x2 wa = xa[64 * jj], wb = xb2[64 * jj]; va[jj] = (f32x4){bf_lo(wa.x), bf_hi(wa.x), bf_lo(wa.y), bf_hi(wa.y)}; vb[jj] = (f32x4){bf_lo(wb.x), bf_hi(wb.x), bf_lo(wb.y), bf_hi(wb.y)}; }
;             r[16] = 0.f; r[17] = 0.f;
; #pragma unroll
;             for (int jj = 0; jj < 4; ++jj) { r[16] += (va[jj].x * va[jj].x + va[jj].y * va[jj].y) + (va[jj].z * va[jj].z + va[jj].w * va[jj].w); r[17] += (vb[jj].x * vb[jj].x + vb[jj].y * vb[jj].y) + (vb[jj].z * vb[jj].z + vb[jj].w * vb[jj].w); }
; #pragma unroll
;             for (int h = 0; h < NH; ++h) { const f32x4* wr = (const f32x4*)(wf + h * D) + lane + zo; float da = 0.f, db = 0.f;
; #pragma unroll
;                 for (int jj = 0; jj < 4; ++jj) { const f32x4 w = wr[64 * jj]; da += (va[jj].x * w.x + va[jj].y * w.y) + (va[jj].z * w.z + va[jj].w * w.w); db += (vb[jj].x * w.x + vb[jj].y * w.y) + (vb[jj].z * w.z + vb[jj].w * w.w); }
;                 r[h] = da; r[8 + h] = db; }
	v_fmac_f32_e32 v44, v7, v194
	v_fmac_f32_e32 v45, v7, v176
	v_fmac_f32_e32 v46, v7, v156
	v_fmac_f32_e32 v47, v7, v140
	v_fmac_f32_e32 v48, v7, v122
	v_fmac_f32_e32 v59, v8, v8
	v_fmac_f32_e32 v41, v8, v243
	v_fmac_f32_e32 v42, v8, v227
	v_fmac_f32_e32 v43, v8, v211
	v_fmac_f32_e32 v44, v8, v195
	v_fmac_f32_e32 v45, v8, v177
	v_fmac_f32_e32 v46, v8, v157
	v_fmac_f32_e32 v47, v8, v141
	v_fmac_f32_e32 v48, v8, v123
	v_fmac_f32_e32 v59, v9, v9
	v_fmac_f32_e32 v41, v9, v236
	v_fmac_f32_e32 v42, v9, v220
	v_fmac_f32_e32 v43, v9, v204
	v_fmac_f32_e32 v44, v9, v188
	v_fmac_f32_e32 v45, v9, v170
	v_fmac_f32_e32 v46, v9, v150
	v_fmac_f32_e32 v47, v9, v134
	v_fmac_f32_e32 v48, v9, v116
	v_fmac_f32_e32 v59, v10, v10
	v_fmac_f32_e32 v41, v10, v237
	v_fmac_f32_e32 v42, v10, v221
	v_fmac_f32_e32 v43, v10, v205
	v_fmac_f32_e32 v44, v10, v189
	v_fmac_f32_e32 v45, v10, v171
	v_fmac_f32_e32 v46, v10, v151
	v_fmac_f32_e32 v47, v10, v135
	v_fmac_f32_e32 v48, v10, v117
	v_fmac_f32_e32 v59, v11, v11
	v_fmac_f32_e32 v41, v11, v238
	v_fmac_f32_e32 v42, v11, v222
	v_fmac_f32_e32 v43, v11, v206
	v_fmac_f32_e32 v44, v11, v190
	v_fmac_f32_e32 v45, v11, v172
	v_fmac_f32_e32 v46, v11, v152
	v_fmac_f32_e32 v47, v11, v136
	v_fmac_f32_e32 v48, v11, v118
	v_fmac_f32_e32 v59, v12, v12
	v_fmac_f32_e32 v41, v12, v239
	v_fmac_f32_e32 v42, v12, v223
	v_fmac_f32_e32 v43, v12, v207
	v_fmac_f32_e32 v44, v12, v191
	v_fmac_f32_e32 v45, v12, v173
	v_fmac_f32_e32 v46, v12, v153
	v_fmac_f32_e32 v47, v12, v137
	v_fmac_f32_e32 v48, v12, v119
	v_lshlrev_b32_e32 v97, 16, v76
	v_and_b32_e32 v159, s40, v76
	v_lshlrev_b32_e32 v187, 16, v77
	v_and_b32_e32 v0, s40, v77
	v_lshlrev_b32_e32 v1, 16, v78
	v_and_b32_e32 v2, s40, v78
	v_lshlrev_b32_e32 v3, 16, v79
	v_and_b32_e32 v4, s40, v79
	v_lshlrev_b32_e32 v5, 16, v72
	v_and_b32_e32 v6, s40, v72
	v_lshlrev_b32_e32 v7, 16, v73
	v_and_b32_e32 v8, s40, v73
	v_lshlrev_b32_e32 v9, 16, v74
	v_and_b32_e32 v10, s40, v74
	v_lshlrev_b32_e32 v11, 16, v75
	v_and_b32_e32 v12, s40, v75
	global_load_dwordx4 v[76:79], v[98:99], off offset:2048
	global_load_dwordx4 v[72:75], v[98:99], off offset:3072
	v_mul_f32_e32 v60, v97, v97
	v_mul_f32_e32 v49, v97, v248
	v_mul_f32_e32 v50, v97, v232
	v_mul_f32_e32 v51, v97, v216
	v_mul_f32_e32 v52, v97, v200
	v_mul_f32_e32 v53, v97, v182
	v_mul_f32_e32 v54, v97, v166
	v_mul_f32_e32 v55, v97, v146
	v_mul_f32_e32 v56, v97, v130
	v_fmac_f32_e32 v60, v159, v159
	v_fmac_f32_e32 v49, v159, v249
	v_fmac_f32_e32 v50, v159, v233
	v_fmac_f32_e32 v51, v159, v217
	v_fmac_f32_e32 v52, v159, v201
	v_fmac_f32_e32 v53, v159, v183
	v_fmac_f32_e32 v54, v159, v167
	v_fmac_f32_e32 v55, v159, v147
	v_fmac_f32_e32 v56, v159, v131
	v_fmac_f32_e32 v60, v187, v187
	v_fmac_f32_e32 v49, v187, v250
	v_fmac_f32_e32 v50, v187, v234
	v_fmac_f32_e32 v51, v187, v218
	v_fmac_f32_e32 v52, v187, v202
	v_fmac_f32_e32 v53, v187, v184
	v_fmac_f32_e32 v54, v187, v168
	v_fmac_f32_e32 v55, v187, v148
	v_fmac_f32_e32 v56, v187, v132
	v_fmac_f32_e32 v60, v0, v0
	v_fmac_f32_e32 v49, v0, v251
	v_fmac_f32_e32 v50, v0, v235
	v_fmac_f32_e32 v51, v0, v219
	v_fmac_f32_e32 v52, v0, v203
	v_fmac_f32_e32 v53, v0, v185
	v_fmac_f32_e32 v54, v0, v169
	v_fmac_f32_e32 v55, v0, v149
	v_fmac_f32_e32 v56, v0, v133
	v_fmac_f32_e32 v60, v1, v1
	v_fmac_f32_e32 v49, v1, v244
	v_fmac_f32_e32 v50, v1, v228
	v_fmac_f32_e32 v51, v1, v212
	v_fmac_f32_e32 v52, v1, v196
	v_fmac_f32_e32 v53, v1, v178
	v_fmac_f32_e32 v54, v1, v162
	v_fmac_f32_e32 v55, v1, v142
	v_fmac_f32_e32 v56, v1, v124
	v_fmac_f32_e32 v60, v2, v2
	v_fmac_f32_e32 v49, v2, v245
	v_fmac_f32_e32 v50, v2, v229
	v_fmac_f32_e32 v51, v2, v213
	v_fmac_f32_e32 v52, v2, v197
	v_fmac_f32_e32 v53, v2, v179
	v_fmac_f32_e32 v54, v2, v163
	v_fmac_f32_e32 v55, v2, v143
	v_fmac_f32_e32 v56, v2, v125
	v_fmac_f32_e32 v60, v3, v3
	v_fmac_f32_e32 v49, v3, v246
	v_fmac_f32_e32 v50, v3, v230
	v_fmac_f32_e32 v51, v3, v214
	v_fmac_f32_e32 v52, v3, v198
	v_fmac_f32_e32 v53, v3, v180
	v_fmac_f32_e32 v54, v3, v164
	v_fmac_f32_e32 v55, v3, v144
	v_fmac_f32_e32 v56, v3, v126
	v_fmac_f32_e32 v60, v4, v4
	v_fmac_f32_e32 v49, v4, v247
	v_fmac_f32_e32 v50, v4, v231
	v_fmac_f32_e32 v51, v4, v215
	v_fmac_f32_e32 v52, v4, v199
	v_fmac_f32_e32 v53, v4, v181
	v_fmac_f32_e32 v54, v4, v165
	v_fmac_f32_e32 v55, v4, v145
	v_fmac_f32_e32 v56, v4, v127
	v_fmac_f32_e32 v60, v5, v5
	v_fmac_f32_e32 v49, v5, v240
	v_fmac_f32_e32 v50, v5, v224
	v_fmac_f32_e32 v51, v5, v208
	v_fmac_f32_e32 v52, v5, v192
	v_fmac_f32_e32 v53, v5, v174
	v_fmac_f32_e32 v54, v5, v154
	v_fmac_f32_e32 v55, v5, v138
	v_fmac_f32_e32 v56, v5, v120
	v_fmac_f32_e32 v60, v6, v6
	v_fmac_f32_e32 v49, v6, v241
	v_fmac_f32_e32 v50, v6, v225
	v_fmac_f32_e32 v51, v6, v209
	v_fmac_f32_e32 v52, v6, v193
	v_fmac_f32_e32 v53, v6, v175
	v_fmac_f32_e32 v54, v6, v155
	v_fmac_f32_e32 v55, v6, v139
	v_fmac_f32_e32 v56, v6, v121
	v_fmac_f32_e32 v60, v7, v7
	v_fmac_f32_e32 v49, v7, v242
	v_fmac_f32_e32 v50, v7, v226
	v_fmac_f32_e32 v51, v7, v210
	v_fmac_f32_e32 v52, v7, v194
	v_fmac_f32_e32 v53, v7, v176
	v_fmac_f32_e32 v54, v7, v156
	v_fmac_f32_e32 v55, v7, v140
	v_fmac_f32_e32 v56, v7, v122
	v_fmac_f32_e32 v60, v8, v8
	v_fmac_f32_e32 v49, v8, v243
	v_fmac_f32_e32 v50, v8, v227
	v_fmac_f32_e32 v51, v8, v211
	v_fmac_f32_e32 v52, v8, v195
	v_fmac_f32_e32 v53, v8, v177
	v_fmac_f32_e32 v54, v8, v157
	v_fmac_f32_e32 v55, v8, v141
	v_fmac_f32_e32 v56, v8, v123
	v_fmac_f32_e32 v60, v9, v9
	v_fmac_f32_e32 v49, v9, v236
	v_fmac_f32_e32 v50, v9, v220
	v_fmac_f32_e32 v51, v9, v204
	v_fmac_f32_e32 v52, v9, v188
	v_fmac_f32_e32 v53, v9, v170
	v_fmac_f32_e32 v54, v9, v150
	v_fmac_f32_e32 v55, v9, v134
	v_fmac_f32_e32 v56, v9, v116
; __device__ __forceinline__ float lane_get(float v, int src_lane) { return __builtin_bit_cast(float, __builtin_amdgcn_ds_bpermute(src_lane << 2, __builtin_bit_cast(int, v))); }
; __device__ __forceinline__ void fgate_phase(const bfr* x, const float* wf, const float* bfg, float* cl, float* ctot, LAS float* scr, int bx, int G, int tid, int lane, int wave) {
;     ...
;             for (int o = 1; o < 64; o <<= 1) {
; #pragma unroll
;                 for (int q = 0; q < 18; ++q) r[q] += lane_get(r[q], lane ^ o); }
;             const float rsa = rsqrtf(r[16] * (1.f / D) + EPS), rsb = rsqrtf(r[17] * (1.f / D) + EPS);
;             if (lane < 16) { const int h = lane & 7; float dsel = r[0];
; #pragma unroll
;                 for (int q = 1; q < 16; ++q) dsel = (lane == q) ? r[q] : dsel;
;                 const float zz = dsel * (lane < 8 ? rsa : rsb) + bfg[h]; const float lf = fminf(zz, 0.f) - 0.6931471805599453f * __builtin_amdgcn_logf(1.0f + __builtin_amdgcn_exp2f(-LOG2E * fabsf(zz)));
;                 scr[(wave * 8 + j + (lane >> 3)) * 8 + h] = lf; } }
	v_fmac_f32_e32 v60, v10, v10
	v_fmac_f32_e32 v49, v10, v237
	v_fmac_f32_e32 v50, v10, v221
	v_fmac_f32_e32 v51, v10, v205
	v_fmac_f32_e32 v52, v10, v189
	v_fmac_f32_e32 v53, v10, v171
	v_fmac_f32_e32 v54, v10, v151
	v_fmac_f32_e32 v55, v10, v135
	v_fmac_f32_e32 v56, v10, v117
	v_fmac_f32_e32 v60, v11, v11
	v_fmac_f32_e32 v49, v11, v238
	v_fmac_f32_e32 v50, v11, v222
	v_fmac_f32_e32 v51, v11, v206
	v_fmac_f32_e32 v52, v11, v190
	v_fmac_f32_e32 v53, v11, v172
	v_fmac_f32_e32 v54, v11, v152
	v_fmac_f32_e32 v55, v11, v136
	v_fmac_f32_e32 v56, v11, v118
	v_fmac_f32_e32 v60, v12, v12
	v_fmac_f32_e32 v49, v12, v239
	v_fmac_f32_e32 v50, v12, v223
	v_fmac_f32_e32 v51, v12, v207
	v_fmac_f32_e32 v52, v12, v191
	v_fmac_f32_e32 v53, v12, v173
	v_fmac_f32_e32 v54, v12, v153
	v_fmac_f32_e32 v55, v12, v137
	v_fmac_f32_e32 v56, v12, v119
	s_nop 1
	v_permlane32_swap_b32_e32 v13, v41
	v_permlane32_swap_b32_e32 v14, v42
	v_permlane32_swap_b32_e32 v15, v43
	v_permlane32_swap_b32_e32 v16, v44
	v_permlane32_swap_b32_e32 v17, v45
	v_permlane32_swap_b32_e32 v18, v46
	v_permlane32_swap_b32_e32 v19, v47
	v_permlane32_swap_b32_e32 v20, v48
	v_permlane32_swap_b32_e32 v21, v49
	v_permlane32_swap_b32_e32 v22, v50
	v_permlane32_swap_b32_e32 v23, v51
	v_permlane32_swap_b32_e32 v24, v52
	v_permlane32_swap_b32_e32 v25, v53
	v_permlane32_swap_b32_e32 v26, v54
	v_permlane32_swap_b32_e32 v27, v55
	v_permlane32_swap_b32_e32 v40, v56
	v_permlane32_swap_b32_e32 v57, v59
	v_permlane32_swap_b32_e32 v58, v60
	s_nop 1
	v_add_f32_e32 v13, v13, v41
	v_add_f32_e32 v14, v14, v42
	v_add_f32_e32 v15, v15, v43
	v_add_f32_e32 v16, v16, v44
	v_add_f32_e32 v17, v17, v45
	v_add_f32_e32 v18, v18, v46
	v_add_f32_e32 v19, v19, v47
	v_add_f32_e32 v20, v20, v48
	v_add_f32_e32 v21, v21, v49
	v_add_f32_e32 v22, v22, v50
	v_add_f32_e32 v23, v23, v51
	v_add_f32_e32 v24, v24, v52
	v_add_f32_e32 v25, v25, v53
	v_add_f32_e32 v26, v26, v54
	v_add_f32_e32 v27, v27, v55
	v_add_f32_e32 v40, v40, v56
	v_add_f32_e32 v57, v57, v59
	v_add_f32_e32 v58, v58, v60
	s_nop 1
	v_permlane16_swap_b32_e32 v13, v21
	v_permlane16_swap_b32_e32 v14, v22
	v_permlane16_swap_b32_e32 v15, v23
	v_permlane16_swap_b32_e32 v16, v24
	v_permlane16_swap_b32_e32 v17, v25
	v_permlane16_swap_b32_e32 v18, v26
	v_permlane16_swap_b32_e32 v19, v27
	v_permlane16_swap_b32_e32 v20, v40
	v_permlane16_swap_b32_e32 v57, v58
	s_nop 1
	v_add_f32_e32 v13, v13, v21
	v_add_f32_e32 v14, v14, v22
	v_add_f32_e32 v15, v15, v23
	v_add_f32_e32 v16, v16, v24
	v_add_f32_e32 v17, v17, v25
	v_add_f32_e32 v18, v18, v26
	v_add_f32_e32 v19, v19, v27
	v_add_f32_e32 v20, v20, v40
	v_add_f32_e32 v57, v57, v58
	s_nop 1
	v_add_f32_dpp v13, v13, v13 quad_perm:[1,0,3,2] row_mask:0xf bank_mask:0xf
	v_add_f32_dpp v14, v14, v14 quad_perm:[1,0,3,2] row_mask:0xf bank_mask:0xf
	v_add_f32_dpp v15, v15, v15 quad_perm:[1,0,3,2] row_mask:0xf bank_mask:0xf
	v_add_f32_dpp v16, v16, v16 quad_perm:[1,0,3,2] row_mask:0xf bank_mask:0xf
	v_add_f32_dpp v17, v17, v17 quad_perm:[1,0,3,2] row_mask:0xf bank_mask:0xf
	v_add_f32_dpp v18, v18, v18 quad_perm:[1,0,3,2] row_mask:0xf bank_mask:0xf
	v_add_f32_dpp v19, v19, v19 quad_perm:[1,0,3,2] row_mask:0xf bank_mask:0xf
	v_add_f32_dpp v20, v20, v20 quad_perm:[1,0,3,2] row_mask:0xf bank_mask:0xf
	v_add_f32_dpp v57, v57, v57 quad_perm:[1,0,3,2] row_mask:0xf bank_mask:0xf
	s_nop 1
	v_add_f32_dpp v13, v13, v13 quad_perm:[2,3,0,1] row_mask:0xf bank_mask:0xf
	v_add_f32_dpp v14, v14, v14 quad_perm:[2,3,0,1] row_mask:0xf bank_mask:0xf
	v_add_f32_dpp v15, v15, v15 quad_perm:[2,3,0,1] row_mask:0xf bank_mask:0xf
	v_add_f32_dpp v16, v16, v16 quad_perm:[2,3,0,1] row_mask:0xf bank_mask:0xf
	v_add_f32_dpp v17, v17, v17 quad_perm:[2,3,0,1] row_mask:0xf bank_mask:0xf
	v_add_f32_dpp v18, v18, v18 quad_perm:[2,3,0,1] row_mask:0xf bank_mask:0xf
	v_add_f32_dpp v19, v19, v19 quad_perm:[2,3,0,1] row_mask:0xf bank_mask:0xf
	v_add_f32_dpp v20, v20, v20 quad_perm:[2,3,0,1] row_mask:0xf bank_mask:0xf
	v_add_f32_dpp v57, v57, v57 quad_perm:[2,3,0,1] row_mask:0xf bank_mask:0xf
	s_nop 1
	v_add_f32_dpp v13, v13, v13 row_half_mirror row_mask:0xf bank_mask:0xf
	v_add_f32_dpp v14, v14, v14 row_half_mirror row_mask:0xf bank_mask:0xf
	v_add_f32_dpp v15, v15, v15 row_half_mirror row_mask:0xf bank_mask:0xf
	v_add_f32_dpp v16, v16, v16 row_half_mirror row_mask:0xf bank_mask:0xf
	v_add_f32_dpp v17, v17, v17 row_half_mirror row_mask:0xf bank_mask:0xf
	v_add_f32_dpp v18, v18, v18 row_half_mirror row_mask:0xf bank_mask:0xf
	v_add_f32_dpp v19, v19, v19 row_half_mirror row_mask:0xf bank_mask:0xf
	v_add_f32_dpp v20, v20, v20 row_half_mirror row_mask:0xf bank_mask:0xf
	v_add_f32_dpp v57, v57, v57 row_half_mirror row_mask:0xf bank_mask:0xf
	s_nop 1
	v_add_f32_dpp v13, v13, v13 row_mirror row_mask:0xf bank_mask:0xf
	v_add_f32_dpp v14, v14, v14 row_mirror row_mask:0xf bank_mask:0xf
	v_add_f32_dpp v15, v15, v15 row_mirror row_mask:0xf bank_mask:0xf
	v_add_f32_dpp v16, v16, v16 row_mirror row_mask:0xf bank_mask:0xf
	v_add_f32_dpp v17, v17, v17 row_mirror row_mask:0xf bank_mask:0xf
	v_add_f32_dpp v18, v18, v18 row_mirror row_mask:0xf bank_mask:0xf
	v_add_f32_dpp v19, v19, v19 row_mirror row_mask:0xf bank_mask:0xf
	v_add_f32_dpp v20, v20, v20 row_mirror row_mask:0xf bank_mask:0xf
	v_add_f32_dpp v57, v57, v57 row_mirror row_mask:0xf bank_mask:0xf
	s_nop 1
	v_mov_b32_e32 v62, v13
	v_cndmask_b32_e64 v62, v62, v14, s[6:7]
	v_cndmask_b32_e64 v62, v62, v15, s[8:9]
	v_cndmask_b32_e64 v62, v62, v16, s[10:11]
	v_cndmask_b32_e64 v62, v62, v17, s[12:13]
	v_cndmask_b32_e64 v62, v62, v18, s[14:15]
	v_cndmask_b32_e64 v62, v62, v19, s[16:17]
	v_cndmask_b32_e64 v62, v62, v20, s[18:19]
	v_mul_f32_e32 v63, 0x3a800000, v57
	v_add_f32_e32 v63, 0x358637bd, v63
	v_rsq_f32_e32 v63, v63
	s_nop 0
	v_fma_f32 v62, v62, v63, v61
	v_mul_f32_e64 v63, |v62|, s65
	v_exp_f32_e32 v63, v63
	v_min_f32_e32 v62, 0, v62
	v_add_f32_e32 v63, 1.0, v63
	v_log_f32_e32 v63, v63
	s_nop 0
	v_fmac_f32_e32 v62, 0xbf317218, v63
	s_mov_b64 s[54:55], exec
	s_mov_b32 exec_lo, 0xff00ff
	s_mov_b32 exec_hi, 0xff00ff
	ds_write_b32 v65, v62
	s_mov_b64 exec, s[54:55]
	s_waitcnt vmcnt(0) lgkmcnt(0)
; __device__ __forceinline__ void fgate_phase(const bfr* x, const float* wf, const float* bfg, float* cl, float* ctot, LAS float* scr, int bx, int G, int tid, int lane, int wave) {
;     ...
;             for (int jj = 0; jj < 4; ++jj) { const u32x2 wa = xa[64 * jj], wb = xb2[64 * jj]; va[jj] = (f32x4){bf_lo(wa.x), bf_hi(wa.x), bf_lo(wa.y), bf_hi(wa.y)}; vb[jj] = (f32x4){bf_lo(wb.x), bf_hi(wb.x), bf_lo(wb.y), bf_hi(wb.y)}; }
;             r[16] = 0.f; r[17] = 0.f;
; #pragma unroll
;             for (int jj = 0; jj < 4; ++jj) { r[16] += (va[jj].x * va[jj].x + va[jj].y * va[jj].y) + (va[jj].z * va[jj].z + va[jj].w * va[jj].w); r[17] += (vb[jj].x * vb[jj].x + vb[jj].y * vb[jj].y) + (vb[jj].z * vb[jj].z + vb[jj].w * vb[jj].w); }
; #pragma unroll
;             for (int h = 0; h < NH; ++h) { const f32x4* wr = (const f32x4*)(wf + h * D) + lane + zo; float da = 0.f, db = 0.f;
; #pragma unroll
;                 for (int jj = 0; jj < 4; ++jj) { const f32x4 w = wr[64 * jj]; da += (va[jj].x * w.x + va[jj].y * w.y) + (va[jj].z * w.z + va[jj].w * w.w); db += (vb[jj].x * w.x + vb[jj].y * w.y) + (vb[jj].z * w.z + vb[jj].w * w.w); }
;                 r[h] = da; r[8 + h] = db; }
	v_lshlrev_b32_e32 v97, 16, v112
	v_and_b32_e32 v159, s40, v112
	v_lshlrev_b32_e32 v187, 16, v113
	v_and_b32_e32 v0, s40, v113
	v_lshlrev_b32_e32 v1, 16, v114
	v_and_b32_e32 v2, s40, v114
	v_lshlrev_b32_e32 v3, 16, v115
	v_and_b32_e32 v4, s40, v115
	v_lshlrev_b32_e32 v5, 16, v108
	v_and_b32_e32 v6, s40, v108
	v_lshlrev_b32_e32 v7, 16, v109
	v_and_b32_e32 v8, s40, v109
	v_lshlrev_b32_e32 v9, 16, v110
	v_and_b32_e32 v10, s40, v110
	v_lshlrev_b32_e32 v11, 16, v111
	v_and_b32_e32 v12, s40, v111
	v_mul_f32_e32 v57, v97, v97
	v_mul_f32_e32 v13, v97, v248
	v_mul_f32_e32 v14, v97, v232
	v_mul_f32_e32 v15, v97, v216
	v_mul_f32_e32 v16, v97, v200
	v_mul_f32_e32 v17, v97, v182
	v_mul_f32_e32 v18, v97, v166
	v_mul_f32_e32 v19, v97, v146
	v_mul_f32_e32 v20, v97, v130
	v_fmac_f32_e32 v57, v159, v159
	v_fmac_f32_e32 v13, v159, v249
	v_fmac_f32_e32 v14, v159, v233
	v_fmac_f32_e32 v15, v159, v217
	v_fmac_f32_e32 v16, v159, v201
	v_fmac_f32_e32 v17, v159, v183
	v_fmac_f32_e32 v18, v159, v167
	v_fmac_f32_e32 v19, v159, v147
	v_fmac_f32_e32 v20, v159, v131
	v_fmac_f32_e32 v57, v187, v187
	v_fmac_f32_e32 v13, v187, v250
	v_fmac_f32_e32 v14, v187, v234
	v_fmac_f32_e32 v15, v187, v218
	v_fmac_f32_e32 v16, v187, v202
	v_fmac_f32_e32 v17, v187, v184
	v_fmac_f32_e32 v18, v187, v168
	v_fmac_f32_e32 v19, v187, v148
	v_fmac_f32_e32 v20, v187, v132
	v_fmac_f32_e32 v57, v0, v0
	v_fmac_f32_e32 v13, v0, v251
	v_fmac_f32_e32 v14, v0, v235
	v_fmac_f32_e32 v15, v0, v219
	v_fmac_f32_e32 v16, v0, v203
	v_fmac_f32_e32 v17, v0, v185
	v_fmac_f32_e32 v18, v0, v169
	v_fmac_f32_e32 v19, v0, v149
	v_fmac_f32_e32 v20, v0, v133
	v_fmac_f32_e32 v57, v1, v1
	v_fmac_f32_e32 v13, v1, v244
	v_fmac_f32_e32 v14, v1, v228
	v_fmac_f32_e32 v15, v1, v212
	v_fmac_f32_e32 v16, v1, v196
	v_fmac_f32_e32 v17, v1, v178
	v_fmac_f32_e32 v18, v1, v162
	v_fmac_f32_e32 v19, v1, v142
	v_fmac_f32_e32 v20, v1, v124
	v_fmac_f32_e32 v57, v2, v2
	v_fmac_f32_e32 v13, v2, v245
	v_fmac_f32_e32 v14, v2, v229
	v_fmac_f32_e32 v15, v2, v213
	v_fmac_f32_e32 v16, v2, v197
	v_fmac_f32_e32 v17, v2, v179
	v_fmac_f32_e32 v18, v2, v163
	v_fmac_f32_e32 v19, v2, v143
	v_fmac_f32_e32 v20, v2, v125
	v_fmac_f32_e32 v57, v3, v3
	v_fmac_f32_e32 v13, v3, v246
	v_fmac_f32_e32 v14, v3, v230
	v_fmac_f32_e32 v15, v3, v214
	v_fmac_f32_e32 v16, v3, v198
	v_fmac_f32_e32 v17, v3, v180
	v_fmac_f32_e32 v18, v3, v164
	v_fmac_f32_e32 v19, v3, v144
	v_fmac_f32_e32 v20, v3, v126
	v_fmac_f32_e32 v57, v4, v4
	v_fmac_f32_e32 v13, v4, v247
	v_fmac_f32_e32 v14, v4, v231
	v_fmac_f32_e32 v15, v4, v215
	v_fmac_f32_e32 v16, v4, v199
	v_fmac_f32_e32 v17, v4, v181
	v_fmac_f32_e32 v18, v4, v165
	v_fmac_f32_e32 v19, v4, v145
	v_fmac_f32_e32 v20, v4, v127
	v_fmac_f32_e32 v57, v5, v5
	v_fmac_f32_e32 v13, v5, v240
	v_fmac_f32_e32 v14, v5, v224
	v_fmac_f32_e32 v15, v5, v208
	v_fmac_f32_e32 v16, v5, v192
	v_fmac_f32_e32 v17, v5, v174
	v_fmac_f32_e32 v18, v5, v154
	v_fmac_f32_e32 v19, v5, v138
	v_fmac_f32_e32 v20, v5, v120
	v_fmac_f32_e32 v57, v6, v6
	v_fmac_f32_e32 v13, v6, v241
	v_fmac_f32_e32 v14, v6, v225
	v_fmac_f32_e32 v15, v6, v209
	v_fmac_f32_e32 v16, v6, v193
	v_fmac_f32_e32 v17, v6, v175
	v_fmac_f32_e32 v18, v6, v155
	v_fmac_f32_e32 v19, v6, v139
	v_fmac_f32_e32 v20, v6, v121
	v_fmac_f32_e32 v57, v7, v7
	v_fmac_f32_e32 v13, v7, v242
	v_fmac_f32_e32 v14, v7, v226
	v_fmac_f32_e32 v15, v7, v210
	v_fmac_f32_e32 v16, v7, v194
	v_fmac_f32_e32 v17, v7, v176
	v_fmac_f32_e32 v18, v7, v156
	v_fmac_f32_e32 v19, v7, v140
	v_fmac_f32_e32 v20, v7, v122
	v_fmac_f32_e32 v57, v8, v8
	v_fmac_f32_e32 v13, v8, v243
	v_fmac_f32_e32 v14, v8, v227
	v_fmac_f32_e32 v15, v8, v211
	v_fmac_f32_e32 v16, v8, v195
	v_fmac_f32_e32 v17, v8, v177
	v_fmac_f32_e32 v18, v8, v157
	v_fmac_f32_e32 v19, v8, v141
	v_fmac_f32_e32 v20, v8, v123
	v_fmac_f32_e32 v57, v9, v9
	v_fmac_f32_e32 v13, v9, v236
	v_fmac_f32_e32 v14, v9, v220
	v_fmac_f32_e32 v15, v9, v204
	v_fmac_f32_e32 v16, v9, v188
	v_fmac_f32_e32 v17, v9, v170
	v_fmac_f32_e32 v18, v9, v150
	v_fmac_f32_e32 v19, v9, v134
	v_fmac_f32_e32 v20, v9, v116
	v_fmac_f32_e32 v57, v10, v10
	v_fmac_f32_e32 v13, v10, v237
	v_fmac_f32_e32 v14, v10, v221
	v_fmac_f32_e32 v15, v10, v205
	v_fmac_f32_e32 v16, v10, v189
	v_fmac_f32_e32 v17, v10, v171
	v_fmac_f32_e32 v18, v10, v151
	v_fmac_f32_e32 v19, v10, v135
	v_fmac_f32_e32 v20, v10, v117
	v_fmac_f32_e32 v57, v11, v11
	v_fmac_f32_e32 v13, v11, v238
	v_fmac_f32_e32 v14, v11, v222
	v_fmac_f32_e32 v15, v11, v206
	v_fmac_f32_e32 v16, v11, v190
	v_fmac_f32_e32 v17, v11, v172
	v_fmac_f32_e32 v18, v11, v152
	v_fmac_f32_e32 v19, v11, v136
	v_fmac_f32_e32 v20, v11, v118
	v_fmac_f32_e32 v57, v12, v12
	v_fmac_f32_e32 v13, v12, v239
	v_fmac_f32_e32 v14, v12, v223
	v_fmac_f32_e32 v15, v12, v207
	v_fmac_f32_e32 v16, v12, v191
	v_fmac_f32_e32 v17, v12, v173
	v_fmac_f32_e32 v18, v12, v153
	v_fmac_f32_e32 v19, v12, v137
	v_fmac_f32_e32 v20, v12, v119
	v_lshlrev_b32_e32 v97, 16, v104
	v_and_b32_e32 v159, s40, v104
	v_lshlrev_b32_e32 v187, 16, v105
	v_and_b32_e32 v0, s40, v105
	v_lshlrev_b32_e32 v1, 16, v106
	v_and_b32_e32 v2, s40, v106
	v_lshlrev_b32_e32 v3, 16, v107
	v_and_b32_e32 v4, s40, v107
	v_lshlrev_b32_e32 v5, 16, v100
	v_and_b32_e32 v6, s40, v100
	v_lshlrev_b32_e32 v7, 16, v101
	v_and_b32_e32 v8, s40, v101
	v_lshlrev_b32_e32 v9, 16, v102
	v_and_b32_e32 v10, s40, v102
	v_lshlrev_b32_e32 v11, 16, v103
	v_and_b32_e32 v12, s40, v103
	v_mul_f32_e32 v58, v97, v97
	v_mul_f32_e32 v21, v97, v248
	v_mul_f32_e32 v22, v97, v232
	v_mul_f32_e32 v23, v97, v216
	v_mul_f32_e32 v24, v97, v200
	v_mul_f32_e32 v25, v97, v182
	v_mul_f32_e32 v26, v97, v166
	v_mul_f32_e32 v27, v97, v146
	v_mul_f32_e32 v40, v97, v130
	v_fmac_f32_e32 v58, v159, v159
; __device__ __forceinline__ void fgate_phase(const bfr* x, const float* wf, const float* bfg, float* cl, float* ctot, LAS float* scr, int bx, int G, int tid, int lane, int wave) {
;     ...
;             for (int jj = 0; jj < 4; ++jj) { const u32x2 wa = xa[64 * jj], wb = xb2[64 * jj]; va[jj] = (f32x4){bf_lo(wa.x), bf_hi(wa.x), bf_lo(wa.y), bf_hi(wa.y)}; vb[jj] = (f32x4){bf_lo(wb.x), bf_hi(wb.x), bf_lo(wb.y), bf_hi(wb.y)}; }
;             r[16] = 0.f; r[17] = 0.f;
; #pragma unroll
;             for (int jj = 0; jj < 4; ++jj) { r[16] += (va[jj].x * va[jj].x + va[jj].y * va[jj].y) + (va[jj].z * va[jj].z + va[jj].w * va[jj].w); r[17] += (vb[jj].x * vb[jj].x + vb[jj].y * vb[jj].y) + (vb[jj].z * vb[jj].z + vb[jj].w * vb[jj].w); }
; #pragma unroll
;             for (int h = 0; h < NH; ++h) { const f32x4* wr = (const f32x4*)(wf + h * D) + lane + zo; float da = 0.f, db = 0.f;
; #pragma unroll
;                 for (int jj = 0; jj < 4; ++jj) { const f32x4 w = wr[64 * jj]; da += (va[jj].x * w.x + va[jj].y * w.y) + (va[jj].z * w.z + va[jj].w * w.w); db += (vb[jj].x * w.x + vb[jj].y * w.y) + (vb[jj].z * w.z + vb[jj].w * w.w); }
;                 r[h] = da; r[8 + h] = db; }
	v_fmac_f32_e32 v21, v159, v249
	v_fmac_f32_e32 v22, v159, v233
	v_fmac_f32_e32 v23, v159, v217
	v_fmac_f32_e32 v24, v159, v201
	v_fmac_f32_e32 v25, v159, v183
	v_fmac_f32_e32 v26, v159, v167
	v_fmac_f32_e32 v27, v159, v147
	v_fmac_f32_e32 v40, v159, v131
	v_fmac_f32_e32 v58, v187, v187
	v_fmac_f32_e32 v21, v187, v250
	v_fmac_f32_e32 v22, v187, v234
	v_fmac_f32_e32 v23, v187, v218
	v_fmac_f32_e32 v24, v187, v202
	v_fmac_f32_e32 v25, v187, v184
	v_fmac_f32_e32 v26, v187, v168
	v_fmac_f32_e32 v27, v187, v148
	v_fmac_f32_e32 v40, v187, v132
	v_fmac_f32_e32 v58, v0, v0
	v_fmac_f32_e32 v21, v0, v251
	v_fmac_f32_e32 v22, v0, v235
	v_fmac_f32_e32 v23, v0, v219
	v_fmac_f32_e32 v24, v0, v203
	v_fmac_f32_e32 v25, v0, v185
	v_fmac_f32_e32 v26, v0, v169
	v_fmac_f32_e32 v27, v0, v149
	v_fmac_f32_e32 v40, v0, v133
	v_fmac_f32_e32 v58, v1, v1
	v_fmac_f32_e32 v21, v1, v244
	v_fmac_f32_e32 v22, v1, v228
	v_fmac_f32_e32 v23, v1, v212
	v_fmac_f32_e32 v24, v1, v196
	v_fmac_f32_e32 v25, v1, v178
	v_fmac_f32_e32 v26, v1, v162
	v_fmac_f32_e32 v27, v1, v142
	v_fmac_f32_e32 v40, v1, v124
	v_fmac_f32_e32 v58, v2, v2
	v_fmac_f32_e32 v21, v2, v245
	v_fmac_f32_e32 v22, v2, v229
	v_fmac_f32_e32 v23, v2, v213
	v_fmac_f32_e32 v24, v2, v197
	v_fmac_f32_e32 v25, v2, v179
	v_fmac_f32_e32 v26, v2, v163
	v_fmac_f32_e32 v27, v2, v143
	v_fmac_f32_e32 v40, v2, v125
	v_fmac_f32_e32 v58, v3, v3
	v_fmac_f32_e32 v21, v3, v246
	v_fmac_f32_e32 v22, v3, v230
	v_fmac_f32_e32 v23, v3, v214
	v_fmac_f32_e32 v24, v3, v198
	v_fmac_f32_e32 v25, v3, v180
	v_fmac_f32_e32 v26, v3, v164
	v_fmac_f32_e32 v27, v3, v144
	v_fmac_f32_e32 v40, v3, v126
	v_fmac_f32_e32 v58, v4, v4
	v_fmac_f32_e32 v21, v4, v247
	v_fmac_f32_e32 v22, v4, v231
	v_fmac_f32_e32 v23, v4, v215
	v_fmac_f32_e32 v24, v4, v199
	v_fmac_f32_e32 v25, v4, v181
	v_fmac_f32_e32 v26, v4, v165
	v_fmac_f32_e32 v27, v4, v145
	v_fmac_f32_e32 v40, v4, v127
	v_fmac_f32_e32 v58, v5, v5
	v_fmac_f32_e32 v21, v5, v240
	v_fmac_f32_e32 v22, v5, v224
	v_fmac_f32_e32 v23, v5, v208
	v_fmac_f32_e32 v24, v5, v192
	v_fmac_f32_e32 v25, v5, v174
	v_fmac_f32_e32 v26, v5, v154
	v_fmac_f32_e32 v27, v5, v138
	v_fmac_f32_e32 v40, v5, v120
	v_fmac_f32_e32 v58, v6, v6
	v_fmac_f32_e32 v21, v6, v241
	v_fmac_f32_e32 v22, v6, v225
	v_fmac_f32_e32 v23, v6, v209
	v_fmac_f32_e32 v24, v6, v193
	v_fmac_f32_e32 v25, v6, v175
	v_fmac_f32_e32 v26, v6, v155
	v_fmac_f32_e32 v27, v6, v139
	v_fmac_f32_e32 v40, v6, v121
	v_fmac_f32_e32 v58, v7, v7
	v_fmac_f32_e32 v21, v7, v242
	v_fmac_f32_e32 v22, v7, v226
	v_fmac_f32_e32 v23, v7, v210
	v_fmac_f32_e32 v24, v7, v194
	v_fmac_f32_e32 v25, v7, v176
	v_fmac_f32_e32 v26, v7, v156
	v_fmac_f32_e32 v27, v7, v140
	v_fmac_f32_e32 v40, v7, v122
	v_fmac_f32_e32 v58, v8, v8
	v_fmac_f32_e32 v21, v8, v243
	v_fmac_f32_e32 v22, v8, v227
	v_fmac_f32_e32 v23, v8, v211
	v_fmac_f32_e32 v24, v8, v195
	v_fmac_f32_e32 v25, v8, v177
	v_fmac_f32_e32 v26, v8, v157
	v_fmac_f32_e32 v27, v8, v141
	v_fmac_f32_e32 v40, v8, v123
	v_fmac_f32_e32 v58, v9, v9
	v_fmac_f32_e32 v21, v9, v236
	v_fmac_f32_e32 v22, v9, v220
	v_fmac_f32_e32 v23, v9, v204
	v_fmac_f32_e32 v24, v9, v188
	v_fmac_f32_e32 v25, v9, v170
	v_fmac_f32_e32 v26, v9, v150
	v_fmac_f32_e32 v27, v9, v134
	v_fmac_f32_e32 v40, v9, v116
	v_fmac_f32_e32 v58, v10, v10
	v_fmac_f32_e32 v21, v10, v237
	v_fmac_f32_e32 v22, v10, v221
	v_fmac_f32_e32 v23, v10, v205
	v_fmac_f32_e32 v24, v10, v189
	v_fmac_f32_e32 v25, v10, v171
	v_fmac_f32_e32 v26, v10, v151
	v_fmac_f32_e32 v27, v10, v135
	v_fmac_f32_e32 v40, v10, v117
	v_fmac_f32_e32 v58, v11, v11
	v_fmac_f32_e32 v21, v11, v238
	v_fmac_f32_e32 v22, v11, v222
	v_fmac_f32_e32 v23, v11, v206
	v_fmac_f32_e32 v24, v11, v190
	v_fmac_f32_e32 v25, v11, v172
	v_fmac_f32_e32 v26, v11, v152
	v_fmac_f32_e32 v27, v11, v136
	v_fmac_f32_e32 v40, v11, v118
	v_fmac_f32_e32 v58, v12, v12
	v_fmac_f32_e32 v21, v12, v239
	v_fmac_f32_e32 v22, v12, v223
	v_fmac_f32_e32 v23, v12, v207
	v_fmac_f32_e32 v24, v12, v191
	v_fmac_f32_e32 v25, v12, v173
	v_fmac_f32_e32 v26, v12, v153
	v_fmac_f32_e32 v27, v12, v137
	v_fmac_f32_e32 v40, v12, v119
	v_lshlrev_b32_e32 v97, 16, v84
	v_and_b32_e32 v159, s40, v84
	v_lshlrev_b32_e32 v187, 16, v85
	v_and_b32_e32 v0, s40, v85
	v_lshlrev_b32_e32 v1, 16, v86
	v_and_b32_e32 v2, s40, v86
	v_lshlrev_b32_e32 v3, 16, v87
	v_and_b32_e32 v4, s40, v87
	v_lshlrev_b32_e32 v5, 16, v80
	v_and_b32_e32 v6, s40, v80
	v_lshlrev_b32_e32 v7, 16, v81
	v_and_b32_e32 v8, s40, v81
	v_lshlrev_b32_e32 v9, 16, v82
	v_and_b32_e32 v10, s40, v82
	v_lshlrev_b32_e32 v11, 16, v83
	v_and_b32_e32 v12, s40, v83
	v_mul_f32_e32 v59, v97, v97
	v_mul_f32_e32 v41, v97, v248
	v_mul_f32_e32 v42, v97, v232
	v_mul_f32_e32 v43, v97, v216
	v_mul_f32_e32 v44, v97, v200
	v_mul_f32_e32 v45, v97, v182
	v_mul_f32_e32 v46, v97, v166
	v_mul_f32_e32 v47, v97, v146
	v_mul_f32_e32 v48, v97, v130
	v_fmac_f32_e32 v59, v159, v159
	v_fmac_f32_e32 v41, v159, v249
	v_fmac_f32_e32 v42, v159, v233
	v_fmac_f32_e32 v43, v159, v217
	v_fmac_f32_e32 v44, v159, v201
	v_fmac_f32_e32 v45, v159, v183
	v_fmac_f32_e32 v46, v159, v167
	v_fmac_f32_e32 v47, v159, v147
	v_fmac_f32_e32 v48, v159, v131
	v_fmac_f32_e32 v59, v187, v187
	v_fmac_f32_e32 v41, v187, v250
	v_fmac_f32_e32 v42, v187, v234
	v_fmac_f32_e32 v43, v187, v218
	v_fmac_f32_e32 v44, v187, v202
	v_fmac_f32_e32 v45, v187, v184
	v_fmac_f32_e32 v46, v187, v168
	v_fmac_f32_e32 v47, v187, v148
	v_fmac_f32_e32 v48, v187, v132
	v_fmac_f32_e32 v59, v0, v0
	v_fmac_f32_e32 v41, v0, v251
	v_fmac_f32_e32 v42, v0, v235
	v_fmac_f32_e32 v43, v0, v219
	v_fmac_f32_e32 v44, v0, v203
	v_fmac_f32_e32 v45, v0, v185
	v_fmac_f32_e32 v46, v0, v169
	v_fmac_f32_e32 v47, v0, v149
	v_fmac_f32_e32 v48, v0, v133
; __device__ __forceinline__ void fgate_phase(const bfr* x, const float* wf, const float* bfg, float* cl, float* ctot, LAS float* scr, int bx, int G, int tid, int lane, int wave) {
;     ...
;             for (int jj = 0; jj < 4; ++jj) { const u32x2 wa = xa[64 * jj], wb = xb2[64 * jj]; va[jj] = (f32x4){bf_lo(wa.x), bf_hi(wa.x), bf_lo(wa.y), bf_hi(wa.y)}; vb[jj] = (f32x4){bf_lo(wb.x), bf_hi(wb.x), bf_lo(wb.y), bf_hi(wb.y)}; }
;             r[16] = 0.f; r[17] = 0.f;
; #pragma unroll
;             for (int jj = 0; jj < 4; ++jj) { r[16] += (va[jj].x * va[jj].x + va[jj].y * va[jj].y) + (va[jj].z * va[jj].z + va[jj].w * va[jj].w); r[17] += (vb[jj].x * vb[jj].x + vb[jj].y * vb[jj].y) + (vb[jj].z * vb[jj].z + vb[jj].w * vb[jj].w); }
; #pragma unroll
;             for (int h = 0; h < NH; ++h) { const f32x4* wr = (const f32x4*)(wf + h * D) + lane + zo; float da = 0.f, db = 0.f;
; #pragma unroll
;                 for (int jj = 0; jj < 4; ++jj) { const f32x4 w = wr[64 * jj]; da += (va[jj].x * w.x + va[jj].y * w.y) + (va[jj].z * w.z + va[jj].w * w.w); db += (vb[jj].x * w.x + vb[jj].y * w.y) + (vb[jj].z * w.z + vb[jj].w * w.w); }
;                 r[h] = da; r[8 + h] = db; }
	v_fmac_f32_e32 v59, v1, v1
	v_fmac_f32_e32 v41, v1, v244
	v_fmac_f32_e32 v42, v1, v228
	v_fmac_f32_e32 v43, v1, v212
	v_fmac_f32_e32 v44, v1, v196
	v_fmac_f32_e32 v45, v1, v178
	v_fmac_f32_e32 v46, v1, v162
	v_fmac_f32_e32 v47, v1, v142
	v_fmac_f32_e32 v48, v1, v124
	v_fmac_f32_e32 v59, v2, v2
	v_fmac_f32_e32 v41, v2, v245
	v_fmac_f32_e32 v42, v2, v229
	v_fmac_f32_e32 v43, v2, v213
	v_fmac_f32_e32 v44, v2, v197
	v_fmac_f32_e32 v45, v2, v179
	v_fmac_f32_e32 v46, v2, v163
	v_fmac_f32_e32 v47, v2, v143
	v_fmac_f32_e32 v48, v2, v125
	v_fmac_f32_e32 v59, v3, v3
	v_fmac_f32_e32 v41, v3, v246
	v_fmac_f32_e32 v42, v3, v230
	v_fmac_f32_e32 v43, v3, v214
	v_fmac_f32_e32 v44, v3, v198
	v_fmac_f32_e32 v45, v3, v180
	v_fmac_f32_e32 v46, v3, v164
	v_fmac_f32_e32 v47, v3, v144
	v_fmac_f32_e32 v48, v3, v126
	v_fmac_f32_e32 v59, v4, v4
	v_fmac_f32_e32 v41, v4, v247
	v_fmac_f32_e32 v42, v4, v231
	v_fmac_f32_e32 v43, v4, v215
	v_fmac_f32_e32 v44, v4, v199
	v_fmac_f32_e32 v45, v4, v181
	v_fmac_f32_e32 v46, v4, v165
	v_fmac_f32_e32 v47, v4, v145
	v_fmac_f32_e32 v48, v4, v127
	v_fmac_f32_e32 v59, v5, v5
	v_fmac_f32_e32 v41, v5, v240
	v_fmac_f32_e32 v42, v5, v224
	v_fmac_f32_e32 v43, v5, v208
	v_fmac_f32_e32 v44, v5, v192
	v_fmac_f32_e32 v45, v5, v174
	v_fmac_f32_e32 v46, v5, v154
	v_fmac_f32_e32 v47, v5, v138
	v_fmac_f32_e32 v48, v5, v120
	v_fmac_f32_e32 v59, v6, v6
	v_fmac_f32_e32 v41, v6, v241
	v_fmac_f32_e32 v42, v6, v225
	v_fmac_f32_e32 v43, v6, v209
	v_fmac_f32_e32 v44, v6, v193
	v_fmac_f32_e32 v45, v6, v175
	v_fmac_f32_e32 v46, v6, v155
	v_fmac_f32_e32 v47, v6, v139
	v_fmac_f32_e32 v48, v6, v121
	v_fmac_f32_e32 v59, v7, v7
	v_fmac_f32_e32 v41, v7, v242
	v_fmac_f32_e32 v42, v7, v226
	v_fmac_f32_e32 v43, v7, v210
	v_fmac_f32_e32 v44, v7, v194
	v_fmac_f32_e32 v45, v7, v176
	v_fmac_f32_e32 v46, v7, v156
	v_fmac_f32_e32 v47, v7, v140
	v_fmac_f32_e32 v48, v7, v122
	v_fmac_f32_e32 v59, v8, v8
	v_fmac_f32_e32 v41, v8, v243
	v_fmac_f32_e32 v42, v8, v227
	v_fmac_f32_e32 v43, v8, v211
	v_fmac_f32_e32 v44, v8, v195
	v_fmac_f32_e32 v45, v8, v177
	v_fmac_f32_e32 v46, v8, v157
	v_fmac_f32_e32 v47, v8, v141
	v_fmac_f32_e32 v48, v8, v123
	v_fmac_f32_e32 v59, v9, v9
	v_fmac_f32_e32 v41, v9, v236
	v_fmac_f32_e32 v42, v9, v220
	v_fmac_f32_e32 v43, v9, v204
	v_fmac_f32_e32 v44, v9, v188
	v_fmac_f32_e32 v45, v9, v170
	v_fmac_f32_e32 v46, v9, v150
	v_fmac_f32_e32 v47, v9, v134
	v_fmac_f32_e32 v48, v9, v116
	v_fmac_f32_e32 v59, v10, v10
	v_fmac_f32_e32 v41, v10, v237
	v_fmac_f32_e32 v42, v10, v221
	v_fmac_f32_e32 v43, v10, v205
	v_fmac_f32_e32 v44, v10, v189
	v_fmac_f32_e32 v45, v10, v171
	v_fmac_f32_e32 v46, v10, v151
	v_fmac_f32_e32 v47, v10, v135
	v_fmac_f32_e32 v48, v10, v117
	v_fmac_f32_e32 v59, v11, v11
	v_fmac_f32_e32 v41, v11, v238
	v_fmac_f32_e32 v42, v11, v222
	v_fmac_f32_e32 v43, v11, v206
	v_fmac_f32_e32 v44, v11, v190
	v_fmac_f32_e32 v45, v11, v172
	v_fmac_f32_e32 v46, v11, v152
	v_fmac_f32_e32 v47, v11, v136
	v_fmac_f32_e32 v48, v11, v118
	v_fmac_f32_e32 v59, v12, v12
	v_fmac_f32_e32 v41, v12, v239
	v_fmac_f32_e32 v42, v12, v223
	v_fmac_f32_e32 v43, v12, v207
	v_fmac_f32_e32 v44, v12, v191
	v_fmac_f32_e32 v45, v12, v173
	v_fmac_f32_e32 v46, v12, v153
	v_fmac_f32_e32 v47, v12, v137
	v_fmac_f32_e32 v48, v12, v119
	v_lshlrev_b32_e32 v97, 16, v76
	v_and_b32_e32 v159, s40, v76
	v_lshlrev_b32_e32 v187, 16, v77
	v_and_b32_e32 v0, s40, v77
	v_lshlrev_b32_e32 v1, 16, v78
	v_and_b32_e32 v2, s40, v78
	v_lshlrev_b32_e32 v3, 16, v79
	v_and_b32_e32 v4, s40, v79
	v_lshlrev_b32_e32 v5, 16, v72
	v_and_b32_e32 v6, s40, v72
	v_lshlrev_b32_e32 v7, 16, v73
	v_and_b32_e32 v8, s40, v73
	v_lshlrev_b32_e32 v9, 16, v74
	v_and_b32_e32 v10, s40, v74
	v_lshlrev_b32_e32 v11, 16, v75
	v_and_b32_e32 v12, s40, v75
	v_mul_f32_e32 v60, v97, v97
	v_mul_f32_e32 v49, v97, v248
	v_mul_f32_e32 v50, v97, v232
	v_mul_f32_e32 v51, v97, v216
	v_mul_f32_e32 v52, v97, v200
	v_mul_f32_e32 v53, v97, v182
	v_mul_f32_e32 v54, v97, v166
	v_mul_f32_e32 v55, v97, v146
	v_mul_f32_e32 v56, v97, v130
	v_fmac_f32_e32 v60, v159, v159
	v_fmac_f32_e32 v49, v159, v249
	v_fmac_f32_e32 v50, v159, v233
	v_fmac_f32_e32 v51, v159, v217
	v_fmac_f32_e32 v52, v159, v201
	v_fmac_f32_e32 v53, v159, v183
	v_fmac_f32_e32 v54, v159, v167
	v_fmac_f32_e32 v55, v159, v147
	v_fmac_f32_e32 v56, v159, v131
	v_fmac_f32_e32 v60, v187, v187
	v_fmac_f32_e32 v49, v187, v250
	v_fmac_f32_e32 v50, v187, v234
	v_fmac_f32_e32 v51, v187, v218
	v_fmac_f32_e32 v52, v187, v202
	v_fmac_f32_e32 v53, v187, v184
	v_fmac_f32_e32 v54, v187, v168
	v_fmac_f32_e32 v55, v187, v148
	v_fmac_f32_e32 v56, v187, v132
	v_fmac_f32_e32 v60, v0, v0
	v_fmac_f32_e32 v49, v0, v251
	v_fmac_f32_e32 v50, v0, v235
	v_fmac_f32_e32 v51, v0, v219
	v_fmac_f32_e32 v52, v0, v203
	v_fmac_f32_e32 v53, v0, v185
	v_fmac_f32_e32 v54, v0, v169
	v_fmac_f32_e32 v55, v0, v149
	v_fmac_f32_e32 v56, v0, v133
	v_fmac_f32_e32 v60, v1, v1
	v_fmac_f32_e32 v49, v1, v244
	v_fmac_f32_e32 v50, v1, v228
	v_fmac_f32_e32 v51, v1, v212
	v_fmac_f32_e32 v52, v1, v196
	v_fmac_f32_e32 v53, v1, v178
	v_fmac_f32_e32 v54, v1, v162
	v_fmac_f32_e32 v55, v1, v142
	v_fmac_f32_e32 v56, v1, v124
	v_fmac_f32_e32 v60, v2, v2
	v_fmac_f32_e32 v49, v2, v245
	v_fmac_f32_e32 v50, v2, v229
	v_fmac_f32_e32 v51, v2, v213
	v_fmac_f32_e32 v52, v2, v197
	v_fmac_f32_e32 v53, v2, v179
	v_fmac_f32_e32 v54, v2, v163
	v_fmac_f32_e32 v55, v2, v143
	v_fmac_f32_e32 v56, v2, v125
	v_fmac_f32_e32 v60, v3, v3
	v_fmac_f32_e32 v49, v3, v246
	v_fmac_f32_e32 v50, v3, v230
	v_fmac_f32_e32 v51, v3, v214
	v_fmac_f32_e32 v52, v3, v198
	v_fmac_f32_e32 v53, v3, v180
	v_fmac_f32_e32 v54, v3, v164
	v_fmac_f32_e32 v55, v3, v144
	v_fmac_f32_e32 v56, v3, v126
; __device__ __forceinline__ float lane_get(float v, int src_lane) { return __builtin_bit_cast(float, __builtin_amdgcn_ds_bpermute(src_lane << 2, __builtin_bit_cast(int, v))); }
; __device__ __forceinline__ void fgate_phase(const bfr* x, const float* wf, const float* bfg, float* cl, float* ctot, LAS float* scr, int bx, int G, int tid, int lane, int wave) {
;     ...
;             for (int o = 1; o < 64; o <<= 1) {
; #pragma unroll
;                 for (int q = 0; q < 18; ++q) r[q] += lane_get(r[q], lane ^ o); }
	v_fmac_f32_e32 v60, v4, v4
	v_fmac_f32_e32 v49, v4, v247
	v_fmac_f32_e32 v50, v4, v231
	v_fmac_f32_e32 v51, v4, v215
	v_fmac_f32_e32 v52, v4, v199
	v_fmac_f32_e32 v53, v4, v181
	v_fmac_f32_e32 v54, v4, v165
	v_fmac_f32_e32 v55, v4, v145
	v_fmac_f32_e32 v56, v4, v127
	v_fmac_f32_e32 v60, v5, v5
	v_fmac_f32_e32 v49, v5, v240
	v_fmac_f32_e32 v50, v5, v224
	v_fmac_f32_e32 v51, v5, v208
	v_fmac_f32_e32 v52, v5, v192
	v_fmac_f32_e32 v53, v5, v174
	v_fmac_f32_e32 v54, v5, v154
	v_fmac_f32_e32 v55, v5, v138
	v_fmac_f32_e32 v56, v5, v120
	v_fmac_f32_e32 v60, v6, v6
	v_fmac_f32_e32 v49, v6, v241
	v_fmac_f32_e32 v50, v6, v225
	v_fmac_f32_e32 v51, v6, v209
	v_fmac_f32_e32 v52, v6, v193
	v_fmac_f32_e32 v53, v6, v175
	v_fmac_f32_e32 v54, v6, v155
	v_fmac_f32_e32 v55, v6, v139
	v_fmac_f32_e32 v56, v6, v121
	v_fmac_f32_e32 v60, v7, v7
	v_fmac_f32_e32 v49, v7, v242
	v_fmac_f32_e32 v50, v7, v226
	v_fmac_f32_e32 v51, v7, v210
	v_fmac_f32_e32 v52, v7, v194
	v_fmac_f32_e32 v53, v7, v176
	v_fmac_f32_e32 v54, v7, v156
	v_fmac_f32_e32 v55, v7, v140
	v_fmac_f32_e32 v56, v7, v122
	v_fmac_f32_e32 v60, v8, v8
	v_fmac_f32_e32 v49, v8, v243
	v_fmac_f32_e32 v50, v8, v227
	v_fmac_f32_e32 v51, v8, v211
	v_fmac_f32_e32 v52, v8, v195
	v_fmac_f32_e32 v53, v8, v177
	v_fmac_f32_e32 v54, v8, v157
	v_fmac_f32_e32 v55, v8, v141
	v_fmac_f32_e32 v56, v8, v123
	v_fmac_f32_e32 v60, v9, v9
	v_fmac_f32_e32 v49, v9, v236
	v_fmac_f32_e32 v50, v9, v220
	v_fmac_f32_e32 v51, v9, v204
	v_fmac_f32_e32 v52, v9, v188
	v_fmac_f32_e32 v53, v9, v170
	v_fmac_f32_e32 v54, v9, v150
	v_fmac_f32_e32 v55, v9, v134
	v_fmac_f32_e32 v56, v9, v116
	v_fmac_f32_e32 v60, v10, v10
	v_fmac_f32_e32 v49, v10, v237
	v_fmac_f32_e32 v50, v10, v221
	v_fmac_f32_e32 v51, v10, v205
	v_fmac_f32_e32 v52, v10, v189
	v_fmac_f32_e32 v53, v10, v171
	v_fmac_f32_e32 v54, v10, v151
	v_fmac_f32_e32 v55, v10, v135
	v_fmac_f32_e32 v56, v10, v117
	v_fmac_f32_e32 v60, v11, v11
	v_fmac_f32_e32 v49, v11, v238
	v_fmac_f32_e32 v50, v11, v222
	v_fmac_f32_e32 v51, v11, v206
	v_fmac_f32_e32 v52, v11, v190
	v_fmac_f32_e32 v53, v11, v172
	v_fmac_f32_e32 v54, v11, v152
	v_fmac_f32_e32 v55, v11, v136
	v_fmac_f32_e32 v56, v11, v118
	v_fmac_f32_e32 v60, v12, v12
	v_fmac_f32_e32 v49, v12, v239
	v_fmac_f32_e32 v50, v12, v223
	v_fmac_f32_e32 v51, v12, v207
	v_fmac_f32_e32 v52, v12, v191
	v_fmac_f32_e32 v53, v12, v173
	v_fmac_f32_e32 v54, v12, v153
	v_fmac_f32_e32 v55, v12, v137
	v_fmac_f32_e32 v56, v12, v119
	s_nop 1
	v_permlane32_swap_b32_e32 v13, v41
	v_permlane32_swap_b32_e32 v14, v42
	v_permlane32_swap_b32_e32 v15, v43
	v_permlane32_swap_b32_e32 v16, v44
	v_permlane32_swap_b32_e32 v17, v45
	v_permlane32_swap_b32_e32 v18, v46
	v_permlane32_swap_b32_e32 v19, v47
	v_permlane32_swap_b32_e32 v20, v48
	v_permlane32_swap_b32_e32 v21, v49
	v_permlane32_swap_b32_e32 v22, v50
	v_permlane32_swap_b32_e32 v23, v51
	v_permlane32_swap_b32_e32 v24, v52
	v_permlane32_swap_b32_e32 v25, v53
	v_permlane32_swap_b32_e32 v26, v54
	v_permlane32_swap_b32_e32 v27, v55
	v_permlane32_swap_b32_e32 v40, v56
	v_permlane32_swap_b32_e32 v57, v59
	v_permlane32_swap_b32_e32 v58, v60
	s_nop 1
	v_add_f32_e32 v13, v13, v41
	v_add_f32_e32 v14, v14, v42
	v_add_f32_e32 v15, v15, v43
	v_add_f32_e32 v16, v16, v44
	v_add_f32_e32 v17, v17, v45
	v_add_f32_e32 v18, v18, v46
	v_add_f32_e32 v19, v19, v47
	v_add_f32_e32 v20, v20, v48
	v_add_f32_e32 v21, v21, v49
	v_add_f32_e32 v22, v22, v50
	v_add_f32_e32 v23, v23, v51
	v_add_f32_e32 v24, v24, v52
	v_add_f32_e32 v25, v25, v53
	v_add_f32_e32 v26, v26, v54
	v_add_f32_e32 v27, v27, v55
	v_add_f32_e32 v40, v40, v56
	v_add_f32_e32 v57, v57, v59
	v_add_f32_e32 v58, v58, v60
	s_nop 1
	v_permlane16_swap_b32_e32 v13, v21
	v_permlane16_swap_b32_e32 v14, v22
	v_permlane16_swap_b32_e32 v15, v23
	v_permlane16_swap_b32_e32 v16, v24
	v_permlane16_swap_b32_e32 v17, v25
	v_permlane16_swap_b32_e32 v18, v26
; __device__ __forceinline__ float lane_get(float v, int src_lane) { return __builtin_bit_cast(float, __builtin_amdgcn_ds_bpermute(src_lane << 2, __builtin_bit_cast(int, v))); }
; __device__ __forceinline__ void fgate_phase(const bfr* x, const float* wf, const float* bfg, float* cl, float* ctot, LAS float* scr, int bx, int G, int tid, int lane, int wave) {
;     ...
;             for (int o = 1; o < 64; o <<= 1) {
; #pragma unroll
;                 for (int q = 0; q < 18; ++q) r[q] += lane_get(r[q], lane ^ o); }
;             const float rsa = rsqrtf(r[16] * (1.f / D) + EPS), rsb = rsqrtf(r[17] * (1.f / D) + EPS);
;             if (lane < 16) { const int h = lane & 7; float dsel = r[0];
; #pragma unroll
;                 for (int q = 1; q < 16; ++q) dsel = (lane == q) ? r[q] : dsel;
;                 const float zz = dsel * (lane < 8 ? rsa : rsb) + bfg[h]; const float lf = fminf(zz, 0.f) - 0.6931471805599453f * __builtin_amdgcn_logf(1.0f + __builtin_amdgcn_exp2f(-LOG2E * fabsf(zz)));
;                 scr[(wave * 8 + j + (lane >> 3)) * 8 + h] = lf; } }
	v_permlane16_swap_b32_e32 v19, v27
	v_permlane16_swap_b32_e32 v20, v40
	v_permlane16_swap_b32_e32 v57, v58
	s_nop 1
	v_add_f32_e32 v13, v13, v21
	v_add_f32_e32 v14, v14, v22
	v_add_f32_e32 v15, v15, v23
	v_add_f32_e32 v16, v16, v24
	v_add_f32_e32 v17, v17, v25
	v_add_f32_e32 v18, v18, v26
	v_add_f32_e32 v19, v19, v27
	v_add_f32_e32 v20, v20, v40
	v_add_f32_e32 v57, v57, v58
	s_nop 1
	v_add_f32_dpp v13, v13, v13 quad_perm:[1,0,3,2] row_mask:0xf bank_mask:0xf
	v_add_f32_dpp v14, v14, v14 quad_perm:[1,0,3,2] row_mask:0xf bank_mask:0xf
	v_add_f32_dpp v15, v15, v15 quad_perm:[1,0,3,2] row_mask:0xf bank_mask:0xf
	v_add_f32_dpp v16, v16, v16 quad_perm:[1,0,3,2] row_mask:0xf bank_mask:0xf
	v_add_f32_dpp v17, v17, v17 quad_perm:[1,0,3,2] row_mask:0xf bank_mask:0xf
	v_add_f32_dpp v18, v18, v18 quad_perm:[1,0,3,2] row_mask:0xf bank_mask:0xf
	v_add_f32_dpp v19, v19, v19 quad_perm:[1,0,3,2] row_mask:0xf bank_mask:0xf
	v_add_f32_dpp v20, v20, v20 quad_perm:[1,0,3,2] row_mask:0xf bank_mask:0xf
	v_add_f32_dpp v57, v57, v57 quad_perm:[1,0,3,2] row_mask:0xf bank_mask:0xf
	s_nop 1
	v_add_f32_dpp v13, v13, v13 quad_perm:[2,3,0,1] row_mask:0xf bank_mask:0xf
	v_add_f32_dpp v14, v14, v14 quad_perm:[2,3,0,1] row_mask:0xf bank_mask:0xf
	v_add_f32_dpp v15, v15, v15 quad_perm:[2,3,0,1] row_mask:0xf bank_mask:0xf
	v_add_f32_dpp v16, v16, v16 quad_perm:[2,3,0,1] row_mask:0xf bank_mask:0xf
	v_add_f32_dpp v17, v17, v17 quad_perm:[2,3,0,1] row_mask:0xf bank_mask:0xf
	v_add_f32_dpp v18, v18, v18 quad_perm:[2,3,0,1] row_mask:0xf bank_mask:0xf
	v_add_f32_dpp v19, v19, v19 quad_perm:[2,3,0,1] row_mask:0xf bank_mask:0xf
	v_add_f32_dpp v20, v20, v20 quad_perm:[2,3,0,1] row_mask:0xf bank_mask:0xf
	v_add_f32_dpp v57, v57, v57 quad_perm:[2,3,0,1] row_mask:0xf bank_mask:0xf
	s_nop 1
	v_add_f32_dpp v13, v13, v13 row_half_mirror row_mask:0xf bank_mask:0xf
	v_add_f32_dpp v14, v14, v14 row_half_mirror row_mask:0xf bank_mask:0xf
	v_add_f32_dpp v15, v15, v15 row_half_mirror row_mask:0xf bank_mask:0xf
	v_add_f32_dpp v16, v16, v16 row_half_mirror row_mask:0xf bank_mask:0xf
	v_add_f32_dpp v17, v17, v17 row_half_mirror row_mask:0xf bank_mask:0xf
	v_add_f32_dpp v18, v18, v18 row_half_mirror row_mask:0xf bank_mask:0xf
	v_add_f32_dpp v19, v19, v19 row_half_mirror row_mask:0xf bank_mask:0xf
	v_add_f32_dpp v20, v20, v20 row_half_mirror row_mask:0xf bank_mask:0xf
	v_add_f32_dpp v57, v57, v57 row_half_mirror row_mask:0xf bank_mask:0xf
	s_nop 1
	v_add_f32_dpp v13, v13, v13 row_mirror row_mask:0xf bank_mask:0xf
	v_add_f32_dpp v14, v14, v14 row_mirror row_mask:0xf bank_mask:0xf
	v_add_f32_dpp v15, v15, v15 row_mirror row_mask:0xf bank_mask:0xf
	v_add_f32_dpp v16, v16, v16 row_mirror row_mask:0xf bank_mask:0xf
	v_add_f32_dpp v17, v17, v17 row_mirror row_mask:0xf bank_mask:0xf
	v_add_f32_dpp v18, v18, v18 row_mirror row_mask:0xf bank_mask:0xf
	v_add_f32_dpp v19, v19, v19 row_mirror row_mask:0xf bank_mask:0xf
	v_add_f32_dpp v20, v20, v20 row_mirror row_mask:0xf bank_mask:0xf
	v_add_f32_dpp v57, v57, v57 row_mirror row_mask:0xf bank_mask:0xf
	s_nop 1
	v_mov_b32_e32 v62, v13
	v_cndmask_b32_e64 v62, v62, v14, s[6:7]
	v_cndmask_b32_e64 v62, v62, v15, s[8:9]
	v_cndmask_b32_e64 v62, v62, v16, s[10:11]
	v_cndmask_b32_e64 v62, v62, v17, s[12:13]
	v_cndmask_b32_e64 v62, v62, v18, s[14:15]
	v_cndmask_b32_e64 v62, v62, v19, s[16:17]
	v_cndmask_b32_e64 v62, v62, v20, s[18:19]
	v_mul_f32_e32 v63, 0x3a800000, v57
	v_add_f32_e32 v63, 0x358637bd, v63
	v_rsq_f32_e32 v63, v63
	s_nop 0
	v_fma_f32 v62, v62, v63, v61
	v_mul_f32_e64 v63, |v62|, s65
	v_exp_f32_e32 v63, v63
	v_min_f32_e32 v62, 0, v62
	v_add_f32_e32 v63, 1.0, v63
	v_log_f32_e32 v63, v63
	s_nop 0
	v_fmac_f32_e32 v62, 0xbf317218, v63
	s_mov_b64 s[54:55], exec
	s_mov_b32 exec_lo, 0xff00ff
	s_mov_b32 exec_hi, 0xff00ff
	ds_write_b32 v65, v62 offset:128
	s_mov_b64 exec, s[54:55]

; __device__ __forceinline__ float lane_get(float v, int src_lane) { return __builtin_bit_cast(float, __builtin_amdgcn_ds_bpermute(src_lane << 2, __builtin_bit_cast(int, v))); }
; __device__ __forceinline__ void fgate_phase(const bfr* x, const float* wf, const float* bfg, float* cl, float* ctot, LAS float* scr, int bx, int G, int tid, int lane, int wave) {
;     ...
;         for (int j = 0; j < 8; j += 2) { const int row = chunk * 64 + wave * 8 + j; typedef unsigned u32x2 __attribute__((ext_vector_type(2))); const u32x2* xa = (const u32x2*)(x + (size_t)row * D) + lane; const u32x2* xb2 = xa + D / 4; f32x4 va[4], vb[4]; float r[18]; int zo = 0; asm volatile("" : "+v"(zo));
; #pragma unroll
;             for (int jj = 0; jj < 4; ++jj) { const u32x2 wa = xa[64 * jj], wb = xb2[64 * jj]; va[jj] = (f32x4){bf_lo(wa.x), bf_hi(wa.x), bf_lo(wa.y), bf_hi(wa.y)}; vb[jj] = (f32x4){bf_lo(wb.x), bf_hi(wb.x), bf_lo(wb.y), bf_hi(wb.y)}; }
;             r[16] = 0.f; r[17] = 0.f;
; #pragma unroll
;             for (int jj = 0; jj < 4; ++jj) { r[16] += (va[jj].x * va[jj].x + va[jj].y * va[jj].y) + (va[jj].z * va[jj].z + va[jj].w * va[jj].w); r[17] += (vb[jj].x * vb[jj].x + vb[jj].y * vb[jj].y) + (vb[jj].z * vb[jj].z + vb[jj].w * vb[jj].w); }
; #pragma unroll
;             for (int h = 0; h < NH; ++h) { const f32x4* wr = (const f32x4*)(wf + h * D) + lane + zo; float da = 0.f, db = 0.f;
; #pragma unroll
;                 for (int jj = 0; jj < 4; ++jj) { const f32x4 w = wr[64 * jj]; da += (va[jj].x * w.x + va[jj].y * w.y) + (va[jj].z * w.z + va[jj].w * w.w); db += (vb[jj].x * w.x + vb[jj].y * w.y) + (vb[jj].z * w.z + vb[jj].w * w.w); }
;                 r[h] = da; r[8 + h] = db; }
; #pragma unroll
;             for (int o = 1; o < 64; o <<= 1) {
; #pragma unroll
;                 for (int q = 0; q < 18; ++q) r[q] += lane_get(r[q], lane ^ o); }
;             const float rsa = rsqrtf(r[16] * (1.f / D) + EPS), rsb = rsqrtf(r[17] * (1.f / D) + EPS);
;             if (lane < 16) { const int h = lane & 7; float dsel = r[0];
; #pragma unroll
;                 for (int q = 1; q < 16; ++q) dsel = (lane == q) ? r[q] : dsel;
;                 const float zz = dsel * (lane < 8 ? rsa : rsb) + bfg[h]; const float lf = fminf(zz, 0.f) - 0.6931471805599453f * __builtin_amdgcn_logf(1.0f + __builtin_amdgcn_exp2f(-LOG2E * fabsf(zz)));
;                 scr[(wave * 8 + j + (lane >> 3)) * 8 + h] = lf; } }
.LBB0_1459:
	s_mov_b32 s38, s33
	s_ashr_i32 s39, s33, 31
	s_lshl_b64 s[38:39], s[38:39], 11
	s_mov_b64 s[98:99], 0x1000
	s_mov_b64 s[100:101], 0x2000
	v_lshl_add_u64 v[38:39], v[28:29], 0, s[38:39]
	v_mov_b32_e32 v160, v158
	v_mov_b32_e32 v161, 0
	v_lshl_add_u64 v[38:39], v[160:161], 3, v[38:39]
	v_lshl_add_u64 v[98:99], v[38:39], 0, s[98:99]
	v_lshrrev_b32_e32 v62, 6, v128
	v_lshlrev_b32_e32 v63, 4, v158
	v_readfirstlane_b32 s20, v30
	v_readfirstlane_b32 s21, v31
	v_readfirstlane_b32 s66, v62
	s_lshl_b32 s66, s66, 12
	s_add_u32 s20, s20, s66
	s_addc_u32 s21, s21, 0
	s_add_i32 s66, s66, 0x1000
	s_mov_b32 m0, s66
	s_nop 0
	global_load_lds_dwordx4 v63, s[20:21]
	s_add_u32 s20, s20, 0x400
	s_addc_u32 s21, s21, 0
	s_add_i32 s66, s66, 0x400
	s_mov_b32 m0, s66
	s_nop 0
	global_load_lds_dwordx4 v63, s[20:21]
	s_add_u32 s20, s20, 0x400
	s_addc_u32 s21, s21, 0
	s_add_i32 s66, s66, 0x400
	s_mov_b32 m0, s66
	s_nop 0
	global_load_lds_dwordx4 v63, s[20:21]
	s_add_u32 s20, s20, 0x400
	s_addc_u32 s21, s21, 0
	s_add_i32 s66, s66, 0x400
	s_mov_b32 m0, s66
	s_nop 0
	global_load_lds_dwordx4 v63, s[20:21]
	global_load_dwordx4 v[112:115], v[38:39], off
	global_load_dwordx4 v[108:111], v[38:39], off offset:1024
	global_load_dwordx4 v[104:107], v[38:39], off offset:2048
	global_load_dwordx4 v[100:103], v[38:39], off offset:3072
	global_load_dwordx4 v[84:87], v[98:99], off
	global_load_dwordx4 v[80:83], v[98:99], off offset:1024
	global_load_dwordx4 v[76:79], v[98:99], off offset:2048
	global_load_dwordx4 v[72:75], v[98:99], off offset:3072
	global_load_dword v61, v[32:33], off offset:32
	s_waitcnt vmcnt(9)
	s_barrier
	v_lshlrev_b32_e32 v63, 5, v158
	ds_read_b128 v[248:251], v63 offset:4096
	ds_read_b128 v[244:247], v63 offset:4112
	ds_read_b128 v[240:243], v63 offset:6144
	ds_read_b128 v[236:239], v63 offset:6160
	ds_read_b128 v[232:235], v63 offset:8192
	ds_read_b128 v[228:231], v63 offset:8208
	ds_read_b128 v[224:227], v63 offset:10240
	ds_read_b128 v[220:223], v63 offset:10256
	ds_read_b128 v[216:219], v63 offset:12288
	ds_read_b128 v[212:215], v63 offset:12304
	ds_read_b128 v[208:211], v63 offset:14336
	ds_read_b128 v[204:207], v63 offset:14352
	ds_read_b128 v[200:203], v63 offset:16384
	ds_read_b128 v[196:199], v63 offset:16400
	ds_read_b128 v[192:195], v63 offset:18432
	ds_read_b128 v[188:191], v63 offset:18448
	ds_read_b128 v[182:185], v63 offset:20480
	ds_read_b128 v[178:181], v63 offset:20496
	ds_read_b128 v[174:177], v63 offset:22528
	ds_read_b128 v[170:173], v63 offset:22544
	ds_read_b128 v[166:169], v63 offset:24576
	ds_read_b128 v[162:165], v63 offset:24592
	ds_read_b128 v[154:157], v63 offset:26624
	ds_read_b128 v[150:153], v63 offset:26640
	ds_read_b128 v[146:149], v63 offset:28672
	ds_read_b128 v[142:145], v63 offset:28688
	ds_read_b128 v[138:141], v63 offset:30720
	ds_read_b128 v[134:137], v63 offset:30736
	ds_read_b128 v[130:133], v63 offset:32768
	ds_read_b128 v[124:127], v63 offset:32784
	ds_read_b128 v[120:123], v63 offset:34816
	ds_read_b128 v[116:119], v63 offset:34832
	v_and_b32_e32 v64, 7, v158
	v_cmp_eq_u32_e64 s[6:7], 1, v64
	v_cmp_eq_u32_e64 s[8:9], 2, v64
	v_cmp_eq_u32_e64 s[10:11], 3, v64
	v_cmp_eq_u32_e64 s[12:13], 4, v64
	v_cmp_eq_u32_e64 s[14:15], 5, v64
	v_cmp_eq_u32_e64 s[16:17], 6, v64
	v_cmp_eq_u32_e64 s[18:19], 7, v64
	v_lshrrev_b32_e32 v62, 4, v158
	v_lshlrev_b32_e32 v62, 5, v62
	v_sub_u32_e32 v65, v95, v62
	s_mov_b32 s40, 0xffff0000
	s_waitcnt vmcnt(0) lgkmcnt(0)
	v_lshlrev_b32_e32 v97, 16, v112
	v_and_b32_e32 v159, s40, v112
	v_lshlrev_b32_e32 v187, 16, v113
	v_and_b32_e32 v0, s40, v113
	v_lshlrev_b32_e32 v1, 16, v114
	v_and_b32_e32 v2, s40, v114
	v_lshlrev_b32_e32 v3, 16, v115
	v_and_b32_e32 v4, s40, v115
	v_lshlrev_b32_e32 v5, 16, v108
	v_and_b32_e32 v6, s40, v108
	v_lshlrev_b32_e32 v7, 16, v109
	v_and_b32_e32 v8, s40, v109
	v_lshlrev_b32_e32 v9, 16, v110
	v_and_b32_e32 v10, s40, v110
	v_lshlrev_b32_e32 v11, 16, v111
	v_and_b32_e32 v12, s40, v111
	v_lshl_add_u64 v[38:39], v[38:39], 0, s[100:101]
	v_lshl_add_u64 v[98:99], v[98:99], 0, s[100:101]
	global_load_dwordx4 v[112:115], v[38:39], off
	global_load_dwordx4 v[108:111], v[38:39], off offset:1024
	v_mul_f32_e32 v57, v97, v97
	v_mul_f32_e32 v13, v97, v248
	v_mul_f32_e32 v14, v97, v232
	v_mul_f32_e32 v15, v97, v216
	v_mul_f32_e32 v16, v97, v200
	v_mul_f32_e32 v17, v97, v182
	v_mul_f32_e32 v18, v97, v166
	v_mul_f32_e32 v19, v97, v146
	v_mul_f32_e32 v20, v97, v130
	v_fmac_f32_e32 v57, v159, v159
	v_fmac_f32_e32 v13, v159, v249
	v_fmac_f32_e32 v14, v159, v233
	v_fmac_f32_e32 v15, v159, v217
	v_fmac_f32_e32 v16, v159, v201
	v_fmac_f32_e32 v17, v159, v183
	v_fmac_f32_e32 v18, v159, v167
	v_fmac_f32_e32 v19, v159, v147
	v_fmac_f32_e32 v20, v159, v131
	v_fmac_f32_e32 v57, v187, v187
	v_fmac_f32_e32 v13, v187, v250
	v_fmac_f32_e32 v14, v187, v234
	v_fmac_f32_e32 v15, v187, v218
	v_fmac_f32_e32 v16, v187, v202
	v_fmac_f32_e32 v17, v187, v184
	v_fmac_f32_e32 v18, v187, v168
	v_fmac_f32_e32 v19, v187, v148
	v_fmac_f32_e32 v20, v187, v132
	v_fmac_f32_e32 v57, v0, v0
	v_fmac_f32_e32 v13, v0, v251
	v_fmac_f32_e32 v14, v0, v235
	v_fmac_f32_e32 v15, v0, v219
	v_fmac_f32_e32 v16, v0, v203
	v_fmac_f32_e32 v17, v0, v185
	v_fmac_f32_e32 v18, v0, v169
	v_fmac_f32_e32 v19, v0, v149
	v_fmac_f32_e32 v20, v0, v133
	v_fmac_f32_e32 v57, v1, v1
	v_fmac_f32_e32 v13, v1, v244
	v_fmac_f32_e32 v14, v1, v228
	v_fmac_f32_e32 v15, v1, v212
	v_fmac_f32_e32 v16, v1, v196
	v_fmac_f32_e32 v17, v1, v178
	v_fmac_f32_e32 v18, v1, v162
	v_fmac_f32_e32 v19, v1, v142
	v_fmac_f32_e32 v20, v1, v124
	v_fmac_f32_e32 v57, v2, v2
	v_fmac_f32_e32 v13, v2, v245
	v_fmac_f32_e32 v14, v2, v229
	v_fmac_f32_e32 v15, v2, v213
; __device__ __forceinline__ void fgate_phase(const bfr* x, const float* wf, const float* bfg, float* cl, float* ctot, LAS float* scr, int bx, int G, int tid, int lane, int wave) {
;     ...
;             for (int jj = 0; jj < 4; ++jj) { const u32x2 wa = xa[64 * jj], wb = xb2[64 * jj]; va[jj] = (f32x4){bf_lo(wa.x), bf_hi(wa.x), bf_lo(wa.y), bf_hi(wa.y)}; vb[jj] = (f32x4){bf_lo(wb.x), bf_hi(wb.x), bf_lo(wb.y), bf_hi(wb.y)}; }
;             r[16] = 0.f; r[17] = 0.f;
; #pragma unroll
;             for (int jj = 0; jj < 4; ++jj) { r[16] += (va[jj].x * va[jj].x + va[jj].y * va[jj].y) + (va[jj].z * va[jj].z + va[jj].w * va[jj].w); r[17] += (vb[jj].x * vb[jj].x + vb[jj].y * vb[jj].y) + (vb[jj].z * vb[jj].z + vb[jj].w * vb[jj].w); }
; #pragma unroll
;             for (int h = 0; h < NH; ++h) { const f32x4* wr = (const f32x4*)(wf + h * D) + lane + zo; float da = 0.f, db = 0.f;
; #pragma unroll
;                 for (int jj = 0; jj < 4; ++jj) { const f32x4 w = wr[64 * jj]; da += (va[jj].x * w.x + va[jj].y * w.y) + (va[jj].z * w.z + va[jj].w * w.w); db += (vb[jj].x * w.x + vb[jj].y * w.y) + (vb[jj].z * w.z + vb[jj].w * w.w); }
;                 r[h] = da; r[8 + h] = db; }
	v_fmac_f32_e32 v16, v2, v197
	v_fmac_f32_e32 v17, v2, v179
	v_fmac_f32_e32 v18, v2, v163
	v_fmac_f32_e32 v19, v2, v143
	v_fmac_f32_e32 v20, v2, v125
	v_fmac_f32_e32 v57, v3, v3
	v_fmac_f32_e32 v13, v3, v246
	v_fmac_f32_e32 v14, v3, v230
	v_fmac_f32_e32 v15, v3, v214
	v_fmac_f32_e32 v16, v3, v198
	v_fmac_f32_e32 v17, v3, v180
	v_fmac_f32_e32 v18, v3, v164
	v_fmac_f32_e32 v19, v3, v144
	v_fmac_f32_e32 v20, v3, v126
	v_fmac_f32_e32 v57, v4, v4
	v_fmac_f32_e32 v13, v4, v247
	v_fmac_f32_e32 v14, v4, v231
	v_fmac_f32_e32 v15, v4, v215
	v_fmac_f32_e32 v16, v4, v199
	v_fmac_f32_e32 v17, v4, v181
	v_fmac_f32_e32 v18, v4, v165
	v_fmac_f32_e32 v19, v4, v145
	v_fmac_f32_e32 v20, v4, v127
	v_fmac_f32_e32 v57, v5, v5
	v_fmac_f32_e32 v13, v5, v240
	v_fmac_f32_e32 v14, v5, v224
	v_fmac_f32_e32 v15, v5, v208
	v_fmac_f32_e32 v16, v5, v192
	v_fmac_f32_e32 v17, v5, v174
	v_fmac_f32_e32 v18, v5, v154
	v_fmac_f32_e32 v19, v5, v138
	v_fmac_f32_e32 v20, v5, v120
	v_fmac_f32_e32 v57, v6, v6
	v_fmac_f32_e32 v13, v6, v241
	v_fmac_f32_e32 v14, v6, v225
	v_fmac_f32_e32 v15, v6, v209
	v_fmac_f32_e32 v16, v6, v193
	v_fmac_f32_e32 v17, v6, v175
	v_fmac_f32_e32 v18, v6, v155
	v_fmac_f32_e32 v19, v6, v139
	v_fmac_f32_e32 v20, v6, v121
	v_fmac_f32_e32 v57, v7, v7
	v_fmac_f32_e32 v13, v7, v242
	v_fmac_f32_e32 v14, v7, v226
	v_fmac_f32_e32 v15, v7, v210
	v_fmac_f32_e32 v16, v7, v194
	v_fmac_f32_e32 v17, v7, v176
	v_fmac_f32_e32 v18, v7, v156
	v_fmac_f32_e32 v19, v7, v140
	v_fmac_f32_e32 v20, v7, v122
	v_fmac_f32_e32 v57, v8, v8
	v_fmac_f32_e32 v13, v8, v243
	v_fmac_f32_e32 v14, v8, v227
	v_fmac_f32_e32 v15, v8, v211
	v_fmac_f32_e32 v16, v8, v195
	v_fmac_f32_e32 v17, v8, v177
	v_fmac_f32_e32 v18, v8, v157
	v_fmac_f32_e32 v19, v8, v141
	v_fmac_f32_e32 v20, v8, v123
	v_fmac_f32_e32 v57, v9, v9
	v_fmac_f32_e32 v13, v9, v236
	v_fmac_f32_e32 v14, v9, v220
	v_fmac_f32_e32 v15, v9, v204
	v_fmac_f32_e32 v16, v9, v188
	v_fmac_f32_e32 v17, v9, v170
	v_fmac_f32_e32 v18, v9, v150
	v_fmac_f32_e32 v19, v9, v134
	v_fmac_f32_e32 v20, v9, v116
	v_fmac_f32_e32 v57, v10, v10
	v_fmac_f32_e32 v13, v10, v237
	v_fmac_f32_e32 v14, v10, v221
	v_fmac_f32_e32 v15, v10, v205
	v_fmac_f32_e32 v16, v10, v189
	v_fmac_f32_e32 v17, v10, v171
	v_fmac_f32_e32 v18, v10, v151
	v_fmac_f32_e32 v19, v10, v135
	v_fmac_f32_e32 v20, v10, v117
	v_fmac_f32_e32 v57, v11, v11
	v_fmac_f32_e32 v13, v11, v238
	v_fmac_f32_e32 v14, v11, v222
	v_fmac_f32_e32 v15, v11, v206
	v_fmac_f32_e32 v16, v11, v190
	v_fmac_f32_e32 v17, v11, v172
	v_fmac_f32_e32 v18, v11, v152
	v_fmac_f32_e32 v19, v11, v136
	v_fmac_f32_e32 v20, v11, v118
	v_fmac_f32_e32 v57, v12, v12
	v_fmac_f32_e32 v13, v12, v239
	v_fmac_f32_e32 v14, v12, v223
	v_fmac_f32_e32 v15, v12, v207
	v_fmac_f32_e32 v16, v12, v191
	v_fmac_f32_e32 v17, v12, v173
	v_fmac_f32_e32 v18, v12, v153
	v_fmac_f32_e32 v19, v12, v137
	v_fmac_f32_e32 v20, v12, v119
	v_lshlrev_b32_e32 v97, 16, v104
	v_and_b32_e32 v159, s40, v104
	v_lshlrev_b32_e32 v187, 16, v105
	v_and_b32_e32 v0, s40, v105
	v_lshlrev_b32_e32 v1, 16, v106
	v_and_b32_e32 v2, s40, v106
	v_lshlrev_b32_e32 v3, 16, v107
	v_and_b32_e32 v4, s40, v107
	v_lshlrev_b32_e32 v5, 16, v100
	v_and_b32_e32 v6, s40, v100
	v_lshlrev_b32_e32 v7, 16, v101
	v_and_b32_e32 v8, s40, v101
	v_lshlrev_b32_e32 v9, 16, v102
	v_and_b32_e32 v10, s40, v102
	v_lshlrev_b32_e32 v11, 16, v103
	v_and_b32_e32 v12, s40, v103
	global_load_dwordx4 v[104:107], v[38:39], off offset:2048
	global_load_dwordx4 v[100:103], v[38:39], off offset:3072
	v_mul_f32_e32 v58, v97, v97
	v_mul_f32_e32 v21, v97, v248
	v_mul_f32_e32 v22, v97, v232
	v_mul_f32_e32 v23, v97, v216
	v_mul_f32_e32 v24, v97, v200
	v_mul_f32_e32 v25, v97, v182
	v_mul_f32_e32 v26, v97, v166
	v_mul_f32_e32 v27, v97, v146
	v_mul_f32_e32 v40, v97, v130
	v_fmac_f32_e32 v58, v159, v159
	v_fmac_f32_e32 v21, v159, v249
	v_fmac_f32_e32 v22, v159, v233
	v_fmac_f32_e32 v23, v159, v217
	v_fmac_f32_e32 v24, v159, v201
	v_fmac_f32_e32 v25, v159, v183
	v_fmac_f32_e32 v26, v159, v167
	v_fmac_f32_e32 v27, v159, v147
	v_fmac_f32_e32 v40, v159, v131
	v_fmac_f32_e32 v58, v187, v187
	v_fmac_f32_e32 v21, v187, v250
	v_fmac_f32_e32 v22, v187, v234
	v_fmac_f32_e32 v23, v187, v218
	v_fmac_f32_e32 v24, v187, v202
	v_fmac_f32_e32 v25, v187, v184
	v_fmac_f32_e32 v26, v187, v168
	v_fmac_f32_e32 v27, v187, v148
	v_fmac_f32_e32 v40, v187, v132
	v_fmac_f32_e32 v58, v0, v0
	v_fmac_f32_e32 v21, v0, v251
	v_fmac_f32_e32 v22, v0, v235
	v_fmac_f32_e32 v23, v0, v219
	v_fmac_f32_e32 v24, v0, v203
	v_fmac_f32_e32 v25, v0, v185
	v_fmac_f32_e32 v26, v0, v169
	v_fmac_f32_e32 v27, v0, v149
	v_fmac_f32_e32 v40, v0, v133
	v_fmac_f32_e32 v58, v1, v1
	v_fmac_f32_e32 v21, v1, v244
	v_fmac_f32_e32 v22, v1, v228
	v_fmac_f32_e32 v23, v1, v212
	v_fmac_f32_e32 v24, v1, v196
	v_fmac_f32_e32 v25, v1, v178
	v_fmac_f32_e32 v26, v1, v162
	v_fmac_f32_e32 v27, v1, v142
	v_fmac_f32_e32 v40, v1, v124
	v_fmac_f32_e32 v58, v2, v2
	v_fmac_f32_e32 v21, v2, v245
	v_fmac_f32_e32 v22, v2, v229
	v_fmac_f32_e32 v23, v2, v213
	v_fmac_f32_e32 v24, v2, v197
	v_fmac_f32_e32 v25, v2, v179
	v_fmac_f32_e32 v26, v2, v163
	v_fmac_f32_e32 v27, v2, v143
	v_fmac_f32_e32 v40, v2, v125
	v_fmac_f32_e32 v58, v3, v3
	v_fmac_f32_e32 v21, v3, v246
	v_fmac_f32_e32 v22, v3, v230
	v_fmac_f32_e32 v23, v3, v214
	v_fmac_f32_e32 v24, v3, v198
	v_fmac_f32_e32 v25, v3, v180
	v_fmac_f32_e32 v26, v3, v164
	v_fmac_f32_e32 v27, v3, v144
	v_fmac_f32_e32 v40, v3, v126
	v_fmac_f32_e32 v58, v4, v4
	v_fmac_f32_e32 v21, v4, v247
	v_fmac_f32_e32 v22, v4, v231
	v_fmac_f32_e32 v23, v4, v215
	v_fmac_f32_e32 v24, v4, v199
	v_fmac_f32_e32 v25, v4, v181
	v_fmac_f32_e32 v26, v4, v165
	v_fmac_f32_e32 v27, v4, v145
; __device__ __forceinline__ void fgate_phase(const bfr* x, const float* wf, const float* bfg, float* cl, float* ctot, LAS float* scr, int bx, int G, int tid, int lane, int wave) {
;     ...
;             for (int jj = 0; jj < 4; ++jj) { const u32x2 wa = xa[64 * jj], wb = xb2[64 * jj]; va[jj] = (f32x4){bf_lo(wa.x), bf_hi(wa.x), bf_lo(wa.y), bf_hi(wa.y)}; vb[jj] = (f32x4){bf_lo(wb.x), bf_hi(wb.x), bf_lo(wb.y), bf_hi(wb.y)}; }
;             r[16] = 0.f; r[17] = 0.f;
; #pragma unroll
;             for (int jj = 0; jj < 4; ++jj) { r[16] += (va[jj].x * va[jj].x + va[jj].y * va[jj].y) + (va[jj].z * va[jj].z + va[jj].w * va[jj].w); r[17] += (vb[jj].x * vb[jj].x + vb[jj].y * vb[jj].y) + (vb[jj].z * vb[jj].z + vb[jj].w * vb[jj].w); }
; #pragma unroll
;             for (int h = 0; h < NH; ++h) { const f32x4* wr = (const f32x4*)(wf + h * D) + lane + zo; float da = 0.f, db = 0.f;
; #pragma unroll
;                 for (int jj = 0; jj < 4; ++jj) { const f32x4 w = wr[64 * jj]; da += (va[jj].x * w.x + va[jj].y * w.y) + (va[jj].z * w.z + va[jj].w * w.w); db += (vb[jj].x * w.x + vb[jj].y * w.y) + (vb[jj].z * w.z + vb[jj].w * w.w); }
;                 r[h] = da; r[8 + h] = db; }
	v_fmac_f32_e32 v40, v4, v127
	v_fmac_f32_e32 v58, v5, v5
	v_fmac_f32_e32 v21, v5, v240
	v_fmac_f32_e32 v22, v5, v224
	v_fmac_f32_e32 v23, v5, v208
	v_fmac_f32_e32 v24, v5, v192
	v_fmac_f32_e32 v25, v5, v174
	v_fmac_f32_e32 v26, v5, v154
	v_fmac_f32_e32 v27, v5, v138
	v_fmac_f32_e32 v40, v5, v120
	v_fmac_f32_e32 v58, v6, v6
	v_fmac_f32_e32 v21, v6, v241
	v_fmac_f32_e32 v22, v6, v225
	v_fmac_f32_e32 v23, v6, v209
	v_fmac_f32_e32 v24, v6, v193
	v_fmac_f32_e32 v25, v6, v175
	v_fmac_f32_e32 v26, v6, v155
	v_fmac_f32_e32 v27, v6, v139
	v_fmac_f32_e32 v40, v6, v121
	v_fmac_f32_e32 v58, v7, v7
	v_fmac_f32_e32 v21, v7, v242
	v_fmac_f32_e32 v22, v7, v226
	v_fmac_f32_e32 v23, v7, v210
	v_fmac_f32_e32 v24, v7, v194
	v_fmac_f32_e32 v25, v7, v176
	v_fmac_f32_e32 v26, v7, v156
	v_fmac_f32_e32 v27, v7, v140
	v_fmac_f32_e32 v40, v7, v122
	v_fmac_f32_e32 v58, v8, v8
	v_fmac_f32_e32 v21, v8, v243
	v_fmac_f32_e32 v22, v8, v227
	v_fmac_f32_e32 v23, v8, v211
	v_fmac_f32_e32 v24, v8, v195
	v_fmac_f32_e32 v25, v8, v177
	v_fmac_f32_e32 v26, v8, v157
	v_fmac_f32_e32 v27, v8, v141
	v_fmac_f32_e32 v40, v8, v123
	v_fmac_f32_e32 v58, v9, v9
	v_fmac_f32_e32 v21, v9, v236
	v_fmac_f32_e32 v22, v9, v220
	v_fmac_f32_e32 v23, v9, v204
	v_fmac_f32_e32 v24, v9, v188
	v_fmac_f32_e32 v25, v9, v170
	v_fmac_f32_e32 v26, v9, v150
	v_fmac_f32_e32 v27, v9, v134
	v_fmac_f32_e32 v40, v9, v116
	v_fmac_f32_e32 v58, v10, v10
	v_fmac_f32_e32 v21, v10, v237
	v_fmac_f32_e32 v22, v10, v221
	v_fmac_f32_e32 v23, v10, v205
	v_fmac_f32_e32 v24, v10, v189
	v_fmac_f32_e32 v25, v10, v171
	v_fmac_f32_e32 v26, v10, v151
	v_fmac_f32_e32 v27, v10, v135
	v_fmac_f32_e32 v40, v10, v117
	v_fmac_f32_e32 v58, v11, v11
	v_fmac_f32_e32 v21, v11, v238
	v_fmac_f32_e32 v22, v11, v222
	v_fmac_f32_e32 v23, v11, v206
	v_fmac_f32_e32 v24, v11, v190
	v_fmac_f32_e32 v25, v11, v172
	v_fmac_f32_e32 v26, v11, v152
	v_fmac_f32_e32 v27, v11, v136
	v_fmac_f32_e32 v40, v11, v118
	v_fmac_f32_e32 v58, v12, v12
	v_fmac_f32_e32 v21, v12, v239
	v_fmac_f32_e32 v22, v12, v223
	v_fmac_f32_e32 v23, v12, v207
	v_fmac_f32_e32 v24, v12, v191
	v_fmac_f32_e32 v25, v12, v173
	v_fmac_f32_e32 v26, v12, v153
	v_fmac_f32_e32 v27, v12, v137
	v_fmac_f32_e32 v40, v12, v119
	v_lshlrev_b32_e32 v97, 16, v84
	v_and_b32_e32 v159, s40, v84
	v_lshlrev_b32_e32 v187, 16, v85
	v_and_b32_e32 v0, s40, v85
	v_lshlrev_b32_e32 v1, 16, v86
	v_and_b32_e32 v2, s40, v86
	v_lshlrev_b32_e32 v3, 16, v87
	v_and_b32_e32 v4, s40, v87
	v_lshlrev_b32_e32 v5, 16, v80
	v_and_b32_e32 v6, s40, v80
	v_lshlrev_b32_e32 v7, 16, v81
	v_and_b32_e32 v8, s40, v81
	v_lshlrev_b32_e32 v9, 16, v82
	v_and_b32_e32 v10, s40, v82
	v_lshlrev_b32_e32 v11, 16, v83
	v_and_b32_e32 v12, s40, v83
	global_load_dwordx4 v[84:87], v[98:99], off
	global_load_dwordx4 v[80:83], v[98:99], off offset:1024
	v_mul_f32_e32 v59, v97, v97
	v_mul_f32_e32 v41, v97, v248
	v_mul_f32_e32 v42, v97, v232
	v_mul_f32_e32 v43, v97, v216
	v_mul_f32_e32 v44, v97, v200
	v_mul_f32_e32 v45, v97, v182
	v_mul_f32_e32 v46, v97, v166
	v_mul_f32_e32 v47, v97, v146
	v_mul_f32_e32 v48, v97, v130
	v_fmac_f32_e32 v59, v159, v159
	v_fmac_f32_e32 v41, v159, v249
	v_fmac_f32_e32 v42, v159, v233
	v_fmac_f32_e32 v43, v159, v217
	v_fmac_f32_e32 v44, v159, v201
	v_fmac_f32_e32 v45, v159, v183
	v_fmac_f32_e32 v46, v159, v167
	v_fmac_f32_e32 v47, v159, v147
	v_fmac_f32_e32 v48, v159, v131
	v_fmac_f32_e32 v59, v187, v187
	v_fmac_f32_e32 v41, v187, v250
	v_fmac_f32_e32 v42, v187, v234
	v_fmac_f32_e32 v43, v187, v218
	v_fmac_f32_e32 v44, v187, v202
	v_fmac_f32_e32 v45, v187, v184
	v_fmac_f32_e32 v46, v187, v168
	v_fmac_f32_e32 v47, v187, v148
	v_fmac_f32_e32 v48, v187, v132
	v_fmac_f32_e32 v59, v0, v0
	v_fmac_f32_e32 v41, v0, v251
	v_fmac_f32_e32 v42, v0, v235
	v_fmac_f32_e32 v43, v0, v219
	v_fmac_f32_e32 v44, v0, v203
	v_fmac_f32_e32 v45, v0, v185
	v_fmac_f32_e32 v46, v0, v169
	v_fmac_f32_e32 v47, v0, v149
	v_fmac_f32_e32 v48, v0, v133
	v_fmac_f32_e32 v59, v1, v1
	v_fmac_f32_e32 v41, v1, v244
	v_fmac_f32_e32 v42, v1, v228
	v_fmac_f32_e32 v43, v1, v212
	v_fmac_f32_e32 v44, v1, v196
	v_fmac_f32_e32 v45, v1, v178
	v_fmac_f32_e32 v46, v1, v162
	v_fmac_f32_e32 v47, v1, v142
	v_fmac_f32_e32 v48, v1, v124
	v_fmac_f32_e32 v59, v2, v2
	v_fmac_f32_e32 v41, v2, v245
	v_fmac_f32_e32 v42, v2, v229
	v_fmac_f32_e32 v43, v2, v213
	v_fmac_f32_e32 v44, v2, v197
	v_fmac_f32_e32 v45, v2, v179
	v_fmac_f32_e32 v46, v2, v163
	v_fmac_f32_e32 v47, v2, v143
	v_fmac_f32_e32 v48, v2, v125
	v_fmac_f32_e32 v59, v3, v3
	v_fmac_f32_e32 v41, v3, v246
	v_fmac_f32_e32 v42, v3, v230
	v_fmac_f32_e32 v43, v3, v214
	v_fmac_f32_e32 v44, v3, v198
	v_fmac_f32_e32 v45, v3, v180
	v_fmac_f32_e32 v46, v3, v164
	v_fmac_f32_e32 v47, v3, v144
	v_fmac_f32_e32 v48, v3, v126
	v_fmac_f32_e32 v59, v4, v4
	v_fmac_f32_e32 v41, v4, v247
	v_fmac_f32_e32 v42, v4, v231
	v_fmac_f32_e32 v43, v4, v215
	v_fmac_f32_e32 v44, v4, v199
	v_fmac_f32_e32 v45, v4, v181
	v_fmac_f32_e32 v46, v4, v165
	v_fmac_f32_e32 v47, v4, v145
	v_fmac_f32_e32 v48, v4, v127
	v_fmac_f32_e32 v59, v5, v5
	v_fmac_f32_e32 v41, v5, v240
	v_fmac_f32_e32 v42, v5, v224
	v_fmac_f32_e32 v43, v5, v208
	v_fmac_f32_e32 v44, v5, v192
	v_fmac_f32_e32 v45, v5, v174
	v_fmac_f32_e32 v46, v5, v154
	v_fmac_f32_e32 v47, v5, v138
	v_fmac_f32_e32 v48, v5, v120
	v_fmac_f32_e32 v59, v6, v6
	v_fmac_f32_e32 v41, v6, v241
	v_fmac_f32_e32 v42, v6, v225
	v_fmac_f32_e32 v43, v6, v209
	v_fmac_f32_e32 v44, v6, v193
	v_fmac_f32_e32 v45, v6, v175
	v_fmac_f32_e32 v46, v6, v155
	v_fmac_f32_e32 v47, v6, v139
	v_fmac_f32_e32 v48, v6, v121
	v_fmac_f32_e32 v59, v7, v7
	v_fmac_f32_e32 v41, v7, v242
	v_fmac_f32_e32 v42, v7, v226
	v_fmac_f32_e32 v43, v7, v210
; __device__ __forceinline__ void fgate_phase(const bfr* x, const float* wf, const float* bfg, float* cl, float* ctot, LAS float* scr, int bx, int G, int tid, int lane, int wave) {
;     ...
;             for (int jj = 0; jj < 4; ++jj) { const u32x2 wa = xa[64 * jj], wb = xb2[64 * jj]; va[jj] = (f32x4){bf_lo(wa.x), bf_hi(wa.x), bf_lo(wa.y), bf_hi(wa.y)}; vb[jj] = (f32x4){bf_lo(wb.x), bf_hi(wb.x), bf_lo(wb.y), bf_hi(wb.y)}; }
;             r[16] = 0.f; r[17] = 0.f;
; #pragma unroll
;             for (int jj = 0; jj < 4; ++jj) { r[16] += (va[jj].x * va[jj].x + va[jj].y * va[jj].y) + (va[jj].z * va[jj].z + va[jj].w * va[jj].w); r[17] += (vb[jj].x * vb[jj].x + vb[jj].y * vb[jj].y) + (vb[jj].z * vb[jj].z + vb[jj].w * vb[jj].w); }
; #pragma unroll
;             for (int h = 0; h < NH; ++h) { const f32x4* wr = (const f32x4*)(wf + h * D) + lane + zo; float da = 0.f, db = 0.f;
; #pragma unroll
;                 for (int jj = 0; jj < 4; ++jj) { const f32x4 w = wr[64 * jj]; da += (va[jj].x * w.x + va[jj].y * w.y) + (va[jj].z * w.z + va[jj].w * w.w); db += (vb[jj].x * w.x + vb[jj].y * w.y) + (vb[jj].z * w.z + vb[jj].w * w.w); }
;                 r[h] = da; r[8 + h] = db; }
	v_fmac_f32_e32 v44, v7, v194
	v_fmac_f32_e32 v45, v7, v176
	v_fmac_f32_e32 v46, v7, v156
	v_fmac_f32_e32 v47, v7, v140
	v_fmac_f32_e32 v48, v7, v122
	v_fmac_f32_e32 v59, v8, v8
	v_fmac_f32_e32 v41, v8, v243
	v_fmac_f32_e32 v42, v8, v227
	v_fmac_f32_e32 v43, v8, v211
	v_fmac_f32_e32 v44, v8, v195
	v_fmac_f32_e32 v45, v8, v177
	v_fmac_f32_e32 v46, v8, v157
	v_fmac_f32_e32 v47, v8, v141
	v_fmac_f32_e32 v48, v8, v123
	v_fmac_f32_e32 v59, v9, v9
	v_fmac_f32_e32 v41, v9, v236
	v_fmac_f32_e32 v42, v9, v220
	v_fmac_f32_e32 v43, v9, v204
	v_fmac_f32_e32 v44, v9, v188
	v_fmac_f32_e32 v45, v9, v170
	v_fmac_f32_e32 v46, v9, v150
	v_fmac_f32_e32 v47, v9, v134
	v_fmac_f32_e32 v48, v9, v116
	v_fmac_f32_e32 v59, v10, v10
	v_fmac_f32_e32 v41, v10, v237
	v_fmac_f32_e32 v42, v10, v221
	v_fmac_f32_e32 v43, v10, v205
	v_fmac_f32_e32 v44, v10, v189
	v_fmac_f32_e32 v45, v10, v171
	v_fmac_f32_e32 v46, v10, v151
	v_fmac_f32_e32 v47, v10, v135
	v_fmac_f32_e32 v48, v10, v117
	v_fmac_f32_e32 v59, v11, v11
	v_fmac_f32_e32 v41, v11, v238
	v_fmac_f32_e32 v42, v11, v222
	v_fmac_f32_e32 v43, v11, v206
	v_fmac_f32_e32 v44, v11, v190
	v_fmac_f32_e32 v45, v11, v172
	v_fmac_f32_e32 v46, v11, v152
	v_fmac_f32_e32 v47, v11, v136
	v_fmac_f32_e32 v48, v11, v118
	v_fmac_f32_e32 v59, v12, v12
	v_fmac_f32_e32 v41, v12, v239
	v_fmac_f32_e32 v42, v12, v223
	v_fmac_f32_e32 v43, v12, v207
	v_fmac_f32_e32 v44, v12, v191
	v_fmac_f32_e32 v45, v12, v173
	v_fmac_f32_e32 v46, v12, v153
	v_fmac_f32_e32 v47, v12, v137
	v_fmac_f32_e32 v48, v12, v119
	v_lshlrev_b32_e32 v97, 16, v76
	v_and_b32_e32 v159, s40, v76
	v_lshlrev_b32_e32 v187, 16, v77
	v_and_b32_e32 v0, s40, v77
	v_lshlrev_b32_e32 v1, 16, v78
	v_and_b32_e32 v2, s40, v78
	v_lshlrev_b32_e32 v3, 16, v79
	v_and_b32_e32 v4, s40, v79
	v_lshlrev_b32_e32 v5, 16, v72
	v_and_b32_e32 v6, s40, v72
	v_lshlrev_b32_e32 v7, 16, v73
	v_and_b32_e32 v8, s40, v73
	v_lshlrev_b32_e32 v9, 16, v74
	v_and_b32_e32 v10, s40, v74
	v_lshlrev_b32_e32 v11, 16, v75
	v_and_b32_e32 v12, s40, v75
	global_load_dwordx4 v[76:79], v[98:99], off offset:2048
	global_load_dwordx4 v[72:75], v[98:99], off offset:3072
	v_mul_f32_e32 v60, v97, v97
	v_mul_f32_e32 v49, v97, v248
	v_mul_f32_e32 v50, v97, v232
	v_mul_f32_e32 v51, v97, v216
	v_mul_f32_e32 v52, v97, v200
	v_mul_f32_e32 v53, v97, v182
	v_mul_f32_e32 v54, v97, v166
	v_mul_f32_e32 v55, v97, v146
	v_mul_f32_e32 v56, v97, v130
	v_fmac_f32_e32 v60, v159, v159
	v_fmac_f32_e32 v49, v159, v249
	v_fmac_f32_e32 v50, v159, v233
	v_fmac_f32_e32 v51, v159, v217
	v_fmac_f32_e32 v52, v159, v201
	v_fmac_f32_e32 v53, v159, v183
	v_fmac_f32_e32 v54, v159, v167
	v_fmac_f32_e32 v55, v159, v147
	v_fmac_f32_e32 v56, v159, v131
	v_fmac_f32_e32 v60, v187, v187
	v_fmac_f32_e32 v49, v187, v250
	v_fmac_f32_e32 v50, v187, v234
	v_fmac_f32_e32 v51, v187, v218
	v_fmac_f32_e32 v52, v187, v202
	v_fmac_f32_e32 v53, v187, v184
	v_fmac_f32_e32 v54, v187, v168
	v_fmac_f32_e32 v55, v187, v148
	v_fmac_f32_e32 v56, v187, v132
	v_fmac_f32_e32 v60, v0, v0
	v_fmac_f32_e32 v49, v0, v251
	v_fmac_f32_e32 v50, v0, v235
	v_fmac_f32_e32 v51, v0, v219
	v_fmac_f32_e32 v52, v0, v203
	v_fmac_f32_e32 v53, v0, v185
	v_fmac_f32_e32 v54, v0, v169
	v_fmac_f32_e32 v55, v0, v149
	v_fmac_f32_e32 v56, v0, v133
	v_fmac_f32_e32 v60, v1, v1
	v_fmac_f32_e32 v49, v1, v244
	v_fmac_f32_e32 v50, v1, v228
	v_fmac_f32_e32 v51, v1, v212
	v_fmac_f32_e32 v52, v1, v196
	v_fmac_f32_e32 v53, v1, v178
	v_fmac_f32_e32 v54, v1, v162
	v_fmac_f32_e32 v55, v1, v142
	v_fmac_f32_e32 v56, v1, v124
	v_fmac_f32_e32 v60, v2, v2
	v_fmac_f32_e32 v49, v2, v245
	v_fmac_f32_e32 v50, v2, v229
	v_fmac_f32_e32 v51, v2, v213
	v_fmac_f32_e32 v52, v2, v197
	v_fmac_f32_e32 v53, v2, v179
	v_fmac_f32_e32 v54, v2, v163
	v_fmac_f32_e32 v55, v2, v143
	v_fmac_f32_e32 v56, v2, v125
	v_fmac_f32_e32 v60, v3, v3
	v_fmac_f32_e32 v49, v3, v246
	v_fmac_f32_e32 v50, v3, v230
	v_fmac_f32_e32 v51, v3, v214
	v_fmac_f32_e32 v52, v3, v198
	v_fmac_f32_e32 v53, v3, v180
	v_fmac_f32_e32 v54, v3, v164
	v_fmac_f32_e32 v55, v3, v144
	v_fmac_f32_e32 v56, v3, v126
	v_fmac_f32_e32 v60, v4, v4
	v_fmac_f32_e32 v49, v4, v247
	v_fmac_f32_e32 v50, v4, v231
	v_fmac_f32_e32 v51, v4, v215
	v_fmac_f32_e32 v52, v4, v199
	v_fmac_f32_e32 v53, v4, v181
	v_fmac_f32_e32 v54, v4, v165
	v_fmac_f32_e32 v55, v4, v145
	v_fmac_f32_e32 v56, v4, v127
	v_fmac_f32_e32 v60, v5, v5
	v_fmac_f32_e32 v49, v5, v240
	v_fmac_f32_e32 v50, v5, v224
	v_fmac_f32_e32 v51, v5, v208
	v_fmac_f32_e32 v52, v5, v192
	v_fmac_f32_e32 v53, v5, v174
	v_fmac_f32_e32 v54, v5, v154
	v_fmac_f32_e32 v55, v5, v138
	v_fmac_f32_e32 v56, v5, v120
	v_fmac_f32_e32 v60, v6, v6
	v_fmac_f32_e32 v49, v6, v241
	v_fmac_f32_e32 v50, v6, v225
	v_fmac_f32_e32 v51, v6, v209
	v_fmac_f32_e32 v52, v6, v193
	v_fmac_f32_e32 v53, v6, v175
	v_fmac_f32_e32 v54, v6, v155
	v_fmac_f32_e32 v55, v6, v139
	v_fmac_f32_e32 v56, v6, v121
	v_fmac_f32_e32 v60, v7, v7
	v_fmac_f32_e32 v49, v7, v242
	v_fmac_f32_e32 v50, v7, v226
	v_fmac_f32_e32 v51, v7, v210
	v_fmac_f32_e32 v52, v7, v194
	v_fmac_f32_e32 v53, v7, v176
	v_fmac_f32_e32 v54, v7, v156
	v_fmac_f32_e32 v55, v7, v140
	v_fmac_f32_e32 v56, v7, v122
	v_fmac_f32_e32 v60, v8, v8
	v_fmac_f32_e32 v49, v8, v243
	v_fmac_f32_e32 v50, v8, v227
	v_fmac_f32_e32 v51, v8, v211
	v_fmac_f32_e32 v52, v8, v195
	v_fmac_f32_e32 v53, v8, v177
	v_fmac_f32_e32 v54, v8, v157
	v_fmac_f32_e32 v55, v8, v141
	v_fmac_f32_e32 v56, v8, v123
	v_fmac_f32_e32 v60, v9, v9
	v_fmac_f32_e32 v49, v9, v236
	v_fmac_f32_e32 v50, v9, v220
	v_fmac_f32_e32 v51, v9, v204
	v_fmac_f32_e32 v52, v9, v188
	v_fmac_f32_e32 v53, v9, v170
	v_fmac_f32_e32 v54, v9, v150
	v_fmac_f32_e32 v55, v9, v134
	v_fmac_f32_e32 v56, v9, v116
; __device__ __forceinline__ float lane_get(float v, int src_lane) { return __builtin_bit_cast(float, __builtin_amdgcn_ds_bpermute(src_lane << 2, __builtin_bit_cast(int, v))); }
; __device__ __forceinline__ void fgate_phase(const bfr* x, const float* wf, const float* bfg, float* cl, float* ctot, LAS float* scr, int bx, int G, int tid, int lane, int wave) {
;     ...
;             for (int o = 1; o < 64; o <<= 1) {
; #pragma unroll
;                 for (int q = 0; q < 18; ++q) r[q] += lane_get(r[q], lane ^ o); }
;             const float rsa = rsqrtf(r[16] * (1.f / D) + EPS), rsb = rsqrtf(r[17] * (1.f / D) + EPS);
;             if (lane < 16) { const int h = lane & 7; float dsel = r[0];
; #pragma unroll
;                 for (int q = 1; q < 16; ++q) dsel = (lane == q) ? r[q] : dsel;
;                 const float zz = dsel * (lane < 8 ? rsa : rsb) + bfg[h]; const float lf = fminf(zz, 0.f) - 0.6931471805599453f * __builtin_amdgcn_logf(1.0f + __builtin_amdgcn_exp2f(-LOG2E * fabsf(zz)));
;                 scr[(wave * 8 + j + (lane >> 3)) * 8 + h] = lf; } }
	v_fmac_f32_e32 v60, v10, v10
	v_fmac_f32_e32 v49, v10, v237
	v_fmac_f32_e32 v50, v10, v221
	v_fmac_f32_e32 v51, v10, v205
	v_fmac_f32_e32 v52, v10, v189
	v_fmac_f32_e32 v53, v10, v171
	v_fmac_f32_e32 v54, v10, v151
	v_fmac_f32_e32 v55, v10, v135
	v_fmac_f32_e32 v56, v10, v117
	v_fmac_f32_e32 v60, v11, v11
	v_fmac_f32_e32 v49, v11, v238
	v_fmac_f32_e32 v50, v11, v222
	v_fmac_f32_e32 v51, v11, v206
	v_fmac_f32_e32 v52, v11, v190
	v_fmac_f32_e32 v53, v11, v172
	v_fmac_f32_e32 v54, v11, v152
	v_fmac_f32_e32 v55, v11, v136
	v_fmac_f32_e32 v56, v11, v118
	v_fmac_f32_e32 v60, v12, v12
	v_fmac_f32_e32 v49, v12, v239
	v_fmac_f32_e32 v50, v12, v223
	v_fmac_f32_e32 v51, v12, v207
	v_fmac_f32_e32 v52, v12, v191
	v_fmac_f32_e32 v53, v12, v173
	v_fmac_f32_e32 v54, v12, v153
	v_fmac_f32_e32 v55, v12, v137
	v_fmac_f32_e32 v56, v12, v119
	s_nop 1
	v_permlane32_swap_b32_e32 v13, v41
	v_permlane32_swap_b32_e32 v14, v42
	v_permlane32_swap_b32_e32 v15, v43
	v_permlane32_swap_b32_e32 v16, v44
	v_permlane32_swap_b32_e32 v17, v45
	v_permlane32_swap_b32_e32 v18, v46
	v_permlane32_swap_b32_e32 v19, v47
	v_permlane32_swap_b32_e32 v20, v48
	v_permlane32_swap_b32_e32 v21, v49
	v_permlane32_swap_b32_e32 v22, v50
	v_permlane32_swap_b32_e32 v23, v51
	v_permlane32_swap_b32_e32 v24, v52
	v_permlane32_swap_b32_e32 v25, v53
	v_permlane32_swap_b32_e32 v26, v54
	v_permlane32_swap_b32_e32 v27, v55
	v_permlane32_swap_b32_e32 v40, v56
	v_permlane32_swap_b32_e32 v57, v59
	v_permlane32_swap_b32_e32 v58, v60
	s_nop 1
	v_add_f32_e32 v13, v13, v41
	v_add_f32_e32 v14, v14, v42
	v_add_f32_e32 v15, v15, v43
	v_add_f32_e32 v16, v16, v44
	v_add_f32_e32 v17, v17, v45
	v_add_f32_e32 v18, v18, v46
	v_add_f32_e32 v19, v19, v47
	v_add_f32_e32 v20, v20, v48
	v_add_f32_e32 v21, v21, v49
	v_add_f32_e32 v22, v22, v50
	v_add_f32_e32 v23, v23, v51
	v_add_f32_e32 v24, v24, v52
	v_add_f32_e32 v25, v25, v53
	v_add_f32_e32 v26, v26, v54
	v_add_f32_e32 v27, v27, v55
	v_add_f32_e32 v40, v40, v56
	v_add_f32_e32 v57, v57, v59
	v_add_f32_e32 v58, v58, v60
	s_nop 1
	v_permlane16_swap_b32_e32 v13, v21
	v_permlane16_swap_b32_e32 v14, v22
	v_permlane16_swap_b32_e32 v15, v23
	v_permlane16_swap_b32_e32 v16, v24
	v_permlane16_swap_b32_e32 v17, v25
	v_permlane16_swap_b32_e32 v18, v26
	v_permlane16_swap_b32_e32 v19, v27
	v_permlane16_swap_b32_e32 v20, v40
	v_permlane16_swap_b32_e32 v57, v58
	s_nop 1
	v_add_f32_e32 v13, v13, v21
	v_add_f32_e32 v14, v14, v22
	v_add_f32_e32 v15, v15, v23
	v_add_f32_e32 v16, v16, v24
	v_add_f32_e32 v17, v17, v25
	v_add_f32_e32 v18, v18, v26
	v_add_f32_e32 v19, v19, v27
	v_add_f32_e32 v20, v20, v40
	v_add_f32_e32 v57, v57, v58
	s_nop 1
	v_add_f32_dpp v13, v13, v13 quad_perm:[1,0,3,2] row_mask:0xf bank_mask:0xf
	v_add_f32_dpp v14, v14, v14 quad_perm:[1,0,3,2] row_mask:0xf bank_mask:0xf
	v_add_f32_dpp v15, v15, v15 quad_perm:[1,0,3,2] row_mask:0xf bank_mask:0xf
	v_add_f32_dpp v16, v16, v16 quad_perm:[1,0,3,2] row_mask:0xf bank_mask:0xf
	v_add_f32_dpp v17, v17, v17 quad_perm:[1,0,3,2] row_mask:0xf bank_mask:0xf
	v_add_f32_dpp v18, v18, v18 quad_perm:[1,0,3,2] row_mask:0xf bank_mask:0xf
	v_add_f32_dpp v19, v19, v19 quad_perm:[1,0,3,2] row_mask:0xf bank_mask:0xf
	v_add_f32_dpp v20, v20, v20 quad_perm:[1,0,3,2] row_mask:0xf bank_mask:0xf
	v_add_f32_dpp v57, v57, v57 quad_perm:[1,0,3,2] row_mask:0xf bank_mask:0xf
	s_nop 1
	v_add_f32_dpp v13, v13, v13 quad_perm:[2,3,0,1] row_mask:0xf bank_mask:0xf
	v_add_f32_dpp v14, v14, v14 quad_perm:[2,3,0,1] row_mask:0xf bank_mask:0xf
	v_add_f32_dpp v15, v15, v15 quad_perm:[2,3,0,1] row_mask:0xf bank_mask:0xf
	v_add_f32_dpp v16, v16, v16 quad_perm:[2,3,0,1] row_mask:0xf bank_mask:0xf
	v_add_f32_dpp v17, v17, v17 quad_perm:[2,3,0,1] row_mask:0xf bank_mask:0xf
	v_add_f32_dpp v18, v18, v18 quad_perm:[2,3,0,1] row_mask:0xf bank_mask:0xf
	v_add_f32_dpp v19, v19, v19 quad_perm:[2,3,0,1] row_mask:0xf bank_mask:0xf
	v_add_f32_dpp v20, v20, v20 quad_perm:[2,3,0,1] row_mask:0xf bank_mask:0xf
	v_add_f32_dpp v57, v57, v57 quad_perm:[2,3,0,1] row_mask:0xf bank_mask:0xf
	s_nop 1
	v_add_f32_dpp v13, v13, v13 row_half_mirror row_mask:0xf bank_mask:0xf
	v_add_f32_dpp v14, v14, v14 row_half_mirror row_mask:0xf bank_mask:0xf
	v_add_f32_dpp v15, v15, v15 row_half_mirror row_mask:0xf bank_mask:0xf
	v_add_f32_dpp v16, v16, v16 row_half_mirror row_mask:0xf bank_mask:0xf
	v_add_f32_dpp v17, v17, v17 row_half_mirror row_mask:0xf bank_mask:0xf
	v_add_f32_dpp v18, v18, v18 row_half_mirror row_mask:0xf bank_mask:0xf
	v_add_f32_dpp v19, v19, v19 row_half_mirror row_mask:0xf bank_mask:0xf
	v_add_f32_dpp v20, v20, v20 row_half_mirror row_mask:0xf bank_mask:0xf
	v_add_f32_dpp v57, v57, v57 row_half_mirror row_mask:0xf bank_mask:0xf
	s_nop 1
	v_add_f32_dpp v13, v13, v13 row_mirror row_mask:0xf bank_mask:0xf
	v_add_f32_dpp v14, v14, v14 row_mirror row_mask:0xf bank_mask:0xf
	v_add_f32_dpp v15, v15, v15 row_mirror row_mask:0xf bank_mask:0xf
	v_add_f32_dpp v16, v16, v16 row_mirror row_mask:0xf bank_mask:0xf
	v_add_f32_dpp v17, v17, v17 row_mirror row_mask:0xf bank_mask:0xf
	v_add_f32_dpp v18, v18, v18 row_mirror row_mask:0xf bank_mask:0xf
	v_add_f32_dpp v19, v19, v19 row_mirror row_mask:0xf bank_mask:0xf
	v_add_f32_dpp v20, v20, v20 row_mirror row_mask:0xf bank_mask:0xf
	v_add_f32_dpp v57, v57, v57 row_mirror row_mask:0xf bank_mask:0xf
	s_nop 1
	v_mov_b32_e32 v62, v13
	v_cndmask_b32_e64 v62, v62, v14, s[6:7]
	v_cndmask_b32_e64 v62, v62, v15, s[8:9]
	v_cndmask_b32_e64 v62, v62, v16, s[10:11]
	v_cndmask_b32_e64 v62, v62, v17, s[12:13]
	v_cndmask_b32_e64 v62, v62, v18, s[14:15]
	v_cndmask_b32_e64 v62, v62, v19, s[16:17]
	v_cndmask_b32_e64 v62, v62, v20, s[18:19]
	v_mul_f32_e32 v63, 0x3a800000, v57
	v_add_f32_e32 v63, 0x358637bd, v63
	v_rsq_f32_e32 v63, v63
	s_nop 0
	v_fma_f32 v62, v62, v63, v61
	v_mul_f32_e64 v63, |v62|, s65
	v_exp_f32_e32 v63, v63
	v_min_f32_e32 v62, 0, v62
	v_add_f32_e32 v63, 1.0, v63
	v_log_f32_e32 v63, v63
	s_nop 0
	v_fmac_f32_e32 v62, 0xbf317218, v63
	s_mov_b64 s[54:55], exec
	s_mov_b32 exec_lo, 0xff00ff
	s_mov_b32 exec_hi, 0xff00ff
	ds_write_b32 v65, v62
	s_mov_b64 exec, s[54:55]
	s_waitcnt vmcnt(0) lgkmcnt(0)
; __device__ __forceinline__ void fgate_phase(const bfr* x, const float* wf, const float* bfg, float* cl, float* ctot, LAS float* scr, int bx, int G, int tid, int lane, int wave) {
;     ...
;         for (int j = 0; j < 8; j += 2) { const int row = chunk * 64 + wave * 8 + j; typedef unsigned u32x2 __attribute__((ext_vector_type(2))); const u32x2* xa = (const u32x2*)(x + (size_t)row * D) + lane; const u32x2* xb2 = xa + D / 4; f32x4 va[4], vb[4]; float r[18]; int zo = 0; asm volatile("" : "+v"(zo));
; #pragma unroll
;             for (int jj = 0; jj < 4; ++jj) { const u32x2 wa = xa[64 * jj], wb = xb2[64 * jj]; va[jj] = (f32x4){bf_lo(wa.x), bf_hi(wa.x), bf_lo(wa.y), bf_hi(wa.y)}; vb[jj] = (f32x4){bf_lo(wb.x), bf_hi(wb.x), bf_lo(wb.y), bf_hi(wb.y)}; }
;             r[16] = 0.f; r[17] = 0.f;
; #pragma unroll
;             for (int jj = 0; jj < 4; ++jj) { r[16] += (va[jj].x * va[jj].x + va[jj].y * va[jj].y) + (va[jj].z * va[jj].z + va[jj].w * va[jj].w); r[17] += (vb[jj].x * vb[jj].x + vb[jj].y * vb[jj].y) + (vb[jj].z * vb[jj].z + vb[jj].w * vb[jj].w); }
; #pragma unroll
;             for (int h = 0; h < NH; ++h) { const f32x4* wr = (const f32x4*)(wf + h * D) + lane + zo; float da = 0.f, db = 0.f;
; #pragma unroll
;                 for (int jj = 0; jj < 4; ++jj) { const f32x4 w = wr[64 * jj]; da += (va[jj].x * w.x + va[jj].y * w.y) + (va[jj].z * w.z + va[jj].w * w.w); db += (vb[jj].x * w.x + vb[jj].y * w.y) + (vb[jj].z * w.z + vb[jj].w * w.w); }
;                 r[h] = da; r[8 + h] = db; }
	v_lshlrev_b32_e32 v97, 16, v112
	v_and_b32_e32 v159, s40, v112
	v_lshlrev_b32_e32 v187, 16, v113
	v_and_b32_e32 v0, s40, v113
	v_lshlrev_b32_e32 v1, 16, v114
	v_and_b32_e32 v2, s40, v114
	v_lshlrev_b32_e32 v3, 16, v115
	v_and_b32_e32 v4, s40, v115
	v_lshlrev_b32_e32 v5, 16, v108
	v_and_b32_e32 v6, s40, v108
	v_lshlrev_b32_e32 v7, 16, v109
	v_and_b32_e32 v8, s40, v109
	v_lshlrev_b32_e32 v9, 16, v110
	v_and_b32_e32 v10, s40, v110
	v_lshlrev_b32_e32 v11, 16, v111
	v_and_b32_e32 v12, s40, v111
	v_mul_f32_e32 v57, v97, v97
	v_mul_f32_e32 v13, v97, v248
	v_mul_f32_e32 v14, v97, v232
	v_mul_f32_e32 v15, v97, v216
	v_mul_f32_e32 v16, v97, v200
	v_mul_f32_e32 v17, v97, v182
	v_mul_f32_e32 v18, v97, v166
	v_mul_f32_e32 v19, v97, v146
	v_mul_f32_e32 v20, v97, v130
	v_fmac_f32_e32 v57, v159, v159
	v_fmac_f32_e32 v13, v159, v249
	v_fmac_f32_e32 v14, v159, v233
	v_fmac_f32_e32 v15, v159, v217
	v_fmac_f32_e32 v16, v159, v201
	v_fmac_f32_e32 v17, v159, v183
	v_fmac_f32_e32 v18, v159, v167
	v_fmac_f32_e32 v19, v159, v147
	v_fmac_f32_e32 v20, v159, v131
	v_fmac_f32_e32 v57, v187, v187
	v_fmac_f32_e32 v13, v187, v250
	v_fmac_f32_e32 v14, v187, v234
	v_fmac_f32_e32 v15, v187, v218
	v_fmac_f32_e32 v16, v187, v202
	v_fmac_f32_e32 v17, v187, v184
	v_fmac_f32_e32 v18, v187, v168
	v_fmac_f32_e32 v19, v187, v148
	v_fmac_f32_e32 v20, v187, v132
	v_fmac_f32_e32 v57, v0, v0
	v_fmac_f32_e32 v13, v0, v251
	v_fmac_f32_e32 v14, v0, v235
	v_fmac_f32_e32 v15, v0, v219
	v_fmac_f32_e32 v16, v0, v203
	v_fmac_f32_e32 v17, v0, v185
	v_fmac_f32_e32 v18, v0, v169
	v_fmac_f32_e32 v19, v0, v149
	v_fmac_f32_e32 v20, v0, v133
	v_fmac_f32_e32 v57, v1, v1
	v_fmac_f32_e32 v13, v1, v244
	v_fmac_f32_e32 v14, v1, v228
	v_fmac_f32_e32 v15, v1, v212
	v_fmac_f32_e32 v16, v1, v196
	v_fmac_f32_e32 v17, v1, v178
	v_fmac_f32_e32 v18, v1, v162
	v_fmac_f32_e32 v19, v1, v142
	v_fmac_f32_e32 v20, v1, v124
	v_fmac_f32_e32 v57, v2, v2
	v_fmac_f32_e32 v13, v2, v245
	v_fmac_f32_e32 v14, v2, v229
	v_fmac_f32_e32 v15, v2, v213
	v_fmac_f32_e32 v16, v2, v197
	v_fmac_f32_e32 v17, v2, v179
	v_fmac_f32_e32 v18, v2, v163
	v_fmac_f32_e32 v19, v2, v143
	v_fmac_f32_e32 v20, v2, v125
	v_fmac_f32_e32 v57, v3, v3
	v_fmac_f32_e32 v13, v3, v246
	v_fmac_f32_e32 v14, v3, v230
	v_fmac_f32_e32 v15, v3, v214
	v_fmac_f32_e32 v16, v3, v198
	v_fmac_f32_e32 v17, v3, v180
	v_fmac_f32_e32 v18, v3, v164
	v_fmac_f32_e32 v19, v3, v144
	v_fmac_f32_e32 v20, v3, v126
	v_fmac_f32_e32 v57, v4, v4
	v_fmac_f32_e32 v13, v4, v247
	v_fmac_f32_e32 v14, v4, v231
	v_fmac_f32_e32 v15, v4, v215
	v_fmac_f32_e32 v16, v4, v199
	v_fmac_f32_e32 v17, v4, v181
	v_fmac_f32_e32 v18, v4, v165
	v_fmac_f32_e32 v19, v4, v145
	v_fmac_f32_e32 v20, v4, v127
	v_fmac_f32_e32 v57, v5, v5
	v_fmac_f32_e32 v13, v5, v240
	v_fmac_f32_e32 v14, v5, v224
	v_fmac_f32_e32 v15, v5, v208
	v_fmac_f32_e32 v16, v5, v192
	v_fmac_f32_e32 v17, v5, v174
	v_fmac_f32_e32 v18, v5, v154
	v_fmac_f32_e32 v19, v5, v138
	v_fmac_f32_e32 v20, v5, v120
	v_fmac_f32_e32 v57, v6, v6
	v_fmac_f32_e32 v13, v6, v241
	v_fmac_f32_e32 v14, v6, v225
	v_fmac_f32_e32 v15, v6, v209
	v_fmac_f32_e32 v16, v6, v193
	v_fmac_f32_e32 v17, v6, v175
	v_fmac_f32_e32 v18, v6, v155
	v_fmac_f32_e32 v19, v6, v139
	v_fmac_f32_e32 v20, v6, v121
	v_fmac_f32_e32 v57, v7, v7
	v_fmac_f32_e32 v13, v7, v242
	v_fmac_f32_e32 v14, v7, v226
	v_fmac_f32_e32 v15, v7, v210
	v_fmac_f32_e32 v16, v7, v194
	v_fmac_f32_e32 v17, v7, v176
	v_fmac_f32_e32 v18, v7, v156
	v_fmac_f32_e32 v19, v7, v140
	v_fmac_f32_e32 v20, v7, v122
	v_fmac_f32_e32 v57, v8, v8
	v_fmac_f32_e32 v13, v8, v243
	v_fmac_f32_e32 v14, v8, v227
	v_fmac_f32_e32 v15, v8, v211
	v_fmac_f32_e32 v16, v8, v195
	v_fmac_f32_e32 v17, v8, v177
	v_fmac_f32_e32 v18, v8, v157
	v_fmac_f32_e32 v19, v8, v141
	v_fmac_f32_e32 v20, v8, v123
	v_fmac_f32_e32 v57, v9, v9
	v_fmac_f32_e32 v13, v9, v236
	v_fmac_f32_e32 v14, v9, v220
	v_fmac_f32_e32 v15, v9, v204
	v_fmac_f32_e32 v16, v9, v188
	v_fmac_f32_e32 v17, v9, v170
	v_fmac_f32_e32 v18, v9, v150
	v_fmac_f32_e32 v19, v9, v134
	v_fmac_f32_e32 v20, v9, v116
	v_fmac_f32_e32 v57, v10, v10
	v_fmac_f32_e32 v13, v10, v237
	v_fmac_f32_e32 v14, v10, v221
	v_fmac_f32_e32 v15, v10, v205
	v_fmac_f32_e32 v16, v10, v189
	v_fmac_f32_e32 v17, v10, v171
	v_fmac_f32_e32 v18, v10, v151
	v_fmac_f32_e32 v19, v10, v135
	v_fmac_f32_e32 v20, v10, v117
	v_fmac_f32_e32 v57, v11, v11
	v_fmac_f32_e32 v13, v11, v238
	v_fmac_f32_e32 v14, v11, v222
	v_fmac_f32_e32 v15, v11, v206
	v_fmac_f32_e32 v16, v11, v190
	v_fmac_f32_e32 v17, v11, v172
	v_fmac_f32_e32 v18, v11, v152
	v_fmac_f32_e32 v19, v11, v136
	v_fmac_f32_e32 v20, v11, v118
	v_fmac_f32_e32 v57, v12, v12
	v_fmac_f32_e32 v13, v12, v239
	v_fmac_f32_e32 v14, v12, v223
	v_fmac_f32_e32 v15, v12, v207
	v_fmac_f32_e32 v16, v12, v191
	v_fmac_f32_e32 v17, v12, v173
	v_fmac_f32_e32 v18, v12, v153
	v_fmac_f32_e32 v19, v12, v137
	v_fmac_f32_e32 v20, v12, v119
	v_lshlrev_b32_e32 v97, 16, v104
	v_and_b32_e32 v159, s40, v104
	v_lshlrev_b32_e32 v187, 16, v105
	v_and_b32_e32 v0, s40, v105
	v_lshlrev_b32_e32 v1, 16, v106
	v_and_b32_e32 v2, s40, v106
	v_lshlrev_b32_e32 v3, 16, v107
	v_and_b32_e32 v4, s40, v107
	v_lshlrev_b32_e32 v5, 16, v100
	v_and_b32_e32 v6, s40, v100
	v_lshlrev_b32_e32 v7, 16, v101
	v_and_b32_e32 v8, s40, v101
	v_lshlrev_b32_e32 v9, 16, v102
	v_and_b32_e32 v10, s40, v102
	v_lshlrev_b32_e32 v11, 16, v103
	v_and_b32_e32 v12, s40, v103
	v_mul_f32_e32 v58, v97, v97
	v_mul_f32_e32 v21, v97, v248
	v_mul_f32_e32 v22, v97, v232
	v_mul_f32_e32 v23, v97, v216
	v_mul_f32_e32 v24, v97, v200
	v_mul_f32_e32 v25, v97, v182
	v_mul_f32_e32 v26, v97, v166
	v_mul_f32_e32 v27, v97, v146
	v_mul_f32_e32 v40, v97, v130
	v_fmac_f32_e32 v58, v159, v159
; __device__ __forceinline__ void fgate_phase(const bfr* x, const float* wf, const float* bfg, float* cl, float* ctot, LAS float* scr, int bx, int G, int tid, int lane, int wave) {
;     ...
;             for (int jj = 0; jj < 4; ++jj) { const u32x2 wa = xa[64 * jj], wb = xb2[64 * jj]; va[jj] = (f32x4){bf_lo(wa.x), bf_hi(wa.x), bf_lo(wa.y), bf_hi(wa.y)}; vb[jj] = (f32x4){bf_lo(wb.x), bf_hi(wb.x), bf_lo(wb.y), bf_hi(wb.y)}; }
;             r[16] = 0.f; r[17] = 0.f;
; #pragma unroll
;             for (int jj = 0; jj < 4; ++jj) { r[16] += (va[jj].x * va[jj].x + va[jj].y * va[jj].y) + (va[jj].z * va[jj].z + va[jj].w * va[jj].w); r[17] += (vb[jj].x * vb[jj].x + vb[jj].y * vb[jj].y) + (vb[jj].z * vb[jj].z + vb[jj].w * vb[jj].w); }
; #pragma unroll
;             for (int h = 0; h < NH; ++h) { const f32x4* wr = (const f32x4*)(wf + h * D) + lane + zo; float da = 0.f, db = 0.f;
; #pragma unroll
;                 for (int jj = 0; jj < 4; ++jj) { const f32x4 w = wr[64 * jj]; da += (va[jj].x * w.x + va[jj].y * w.y) + (va[jj].z * w.z + va[jj].w * w.w); db += (vb[jj].x * w.x + vb[jj].y * w.y) + (vb[jj].z * w.z + vb[jj].w * w.w); }
;                 r[h] = da; r[8 + h] = db; }
	v_fmac_f32_e32 v21, v159, v249
	v_fmac_f32_e32 v22, v159, v233
	v_fmac_f32_e32 v23, v159, v217
	v_fmac_f32_e32 v24, v159, v201
	v_fmac_f32_e32 v25, v159, v183
	v_fmac_f32_e32 v26, v159, v167
	v_fmac_f32_e32 v27, v159, v147
	v_fmac_f32_e32 v40, v159, v131
	v_fmac_f32_e32 v58, v187, v187
	v_fmac_f32_e32 v21, v187, v250
	v_fmac_f32_e32 v22, v187, v234
	v_fmac_f32_e32 v23, v187, v218
	v_fmac_f32_e32 v24, v187, v202
	v_fmac_f32_e32 v25, v187, v184
	v_fmac_f32_e32 v26, v187, v168
	v_fmac_f32_e32 v27, v187, v148
	v_fmac_f32_e32 v40, v187, v132
	v_fmac_f32_e32 v58, v0, v0
	v_fmac_f32_e32 v21, v0, v251
	v_fmac_f32_e32 v22, v0, v235
	v_fmac_f32_e32 v23, v0, v219
	v_fmac_f32_e32 v24, v0, v203
	v_fmac_f32_e32 v25, v0, v185
	v_fmac_f32_e32 v26, v0, v169
	v_fmac_f32_e32 v27, v0, v149
	v_fmac_f32_e32 v40, v0, v133
	v_fmac_f32_e32 v58, v1, v1
	v_fmac_f32_e32 v21, v1, v244
	v_fmac_f32_e32 v22, v1, v228
	v_fmac_f32_e32 v23, v1, v212
	v_fmac_f32_e32 v24, v1, v196
	v_fmac_f32_e32 v25, v1, v178
	v_fmac_f32_e32 v26, v1, v162
	v_fmac_f32_e32 v27, v1, v142
	v_fmac_f32_e32 v40, v1, v124
	v_fmac_f32_e32 v58, v2, v2
	v_fmac_f32_e32 v21, v2, v245
	v_fmac_f32_e32 v22, v2, v229
	v_fmac_f32_e32 v23, v2, v213
	v_fmac_f32_e32 v24, v2, v197
	v_fmac_f32_e32 v25, v2, v179
	v_fmac_f32_e32 v26, v2, v163
	v_fmac_f32_e32 v27, v2, v143
	v_fmac_f32_e32 v40, v2, v125
	v_fmac_f32_e32 v58, v3, v3
	v_fmac_f32_e32 v21, v3, v246
	v_fmac_f32_e32 v22, v3, v230
	v_fmac_f32_e32 v23, v3, v214
	v_fmac_f32_e32 v24, v3, v198
	v_fmac_f32_e32 v25, v3, v180
	v_fmac_f32_e32 v26, v3, v164
	v_fmac_f32_e32 v27, v3, v144
	v_fmac_f32_e32 v40, v3, v126
	v_fmac_f32_e32 v58, v4, v4
	v_fmac_f32_e32 v21, v4, v247
	v_fmac_f32_e32 v22, v4, v231
	v_fmac_f32_e32 v23, v4, v215
	v_fmac_f32_e32 v24, v4, v199
	v_fmac_f32_e32 v25, v4, v181
	v_fmac_f32_e32 v26, v4, v165
	v_fmac_f32_e32 v27, v4, v145
	v_fmac_f32_e32 v40, v4, v127
	v_fmac_f32_e32 v58, v5, v5
	v_fmac_f32_e32 v21, v5, v240
	v_fmac_f32_e32 v22, v5, v224
	v_fmac_f32_e32 v23, v5, v208
	v_fmac_f32_e32 v24, v5, v192
	v_fmac_f32_e32 v25, v5, v174
	v_fmac_f32_e32 v26, v5, v154
	v_fmac_f32_e32 v27, v5, v138
	v_fmac_f32_e32 v40, v5, v120
	v_fmac_f32_e32 v58, v6, v6
	v_fmac_f32_e32 v21, v6, v241
	v_fmac_f32_e32 v22, v6, v225
	v_fmac_f32_e32 v23, v6, v209
	v_fmac_f32_e32 v24, v6, v193
	v_fmac_f32_e32 v25, v6, v175
	v_fmac_f32_e32 v26, v6, v155
	v_fmac_f32_e32 v27, v6, v139
	v_fmac_f32_e32 v40, v6, v121
	v_fmac_f32_e32 v58, v7, v7
	v_fmac_f32_e32 v21, v7, v242
	v_fmac_f32_e32 v22, v7, v226
	v_fmac_f32_e32 v23, v7, v210
	v_fmac_f32_e32 v24, v7, v194
	v_fmac_f32_e32 v25, v7, v176
	v_fmac_f32_e32 v26, v7, v156
	v_fmac_f32_e32 v27, v7, v140
	v_fmac_f32_e32 v40, v7, v122
	v_fmac_f32_e32 v58, v8, v8
	v_fmac_f32_e32 v21, v8, v243
	v_fmac_f32_e32 v22, v8, v227
	v_fmac_f32_e32 v23, v8, v211
	v_fmac_f32_e32 v24, v8, v195
	v_fmac_f32_e32 v25, v8, v177
	v_fmac_f32_e32 v26, v8, v157
	v_fmac_f32_e32 v27, v8, v141
	v_fmac_f32_e32 v40, v8, v123
	v_fmac_f32_e32 v58, v9, v9
	v_fmac_f32_e32 v21, v9, v236
	v_fmac_f32_e32 v22, v9, v220
	v_fmac_f32_e32 v23, v9, v204
	v_fmac_f32_e32 v24, v9, v188
	v_fmac_f32_e32 v25, v9, v170
	v_fmac_f32_e32 v26, v9, v150
	v_fmac_f32_e32 v27, v9, v134
	v_fmac_f32_e32 v40, v9, v116
	v_fmac_f32_e32 v58, v10, v10
	v_fmac_f32_e32 v21, v10, v237
	v_fmac_f32_e32 v22, v10, v221
	v_fmac_f32_e32 v23, v10, v205
	v_fmac_f32_e32 v24, v10, v189
	v_fmac_f32_e32 v25, v10, v171
	v_fmac_f32_e32 v26, v10, v151
	v_fmac_f32_e32 v27, v10, v135
	v_fmac_f32_e32 v40, v10, v117
	v_fmac_f32_e32 v58, v11, v11
	v_fmac_f32_e32 v21, v11, v238
	v_fmac_f32_e32 v22, v11, v222
	v_fmac_f32_e32 v23, v11, v206
	v_fmac_f32_e32 v24, v11, v190
	v_fmac_f32_e32 v25, v11, v172
	v_fmac_f32_e32 v26, v11, v152
	v_fmac_f32_e32 v27, v11, v136
	v_fmac_f32_e32 v40, v11, v118
	v_fmac_f32_e32 v58, v12, v12
	v_fmac_f32_e32 v21, v12, v239
	v_fmac_f32_e32 v22, v12, v223
	v_fmac_f32_e32 v23, v12, v207
	v_fmac_f32_e32 v24, v12, v191
	v_fmac_f32_e32 v25, v12, v173
	v_fmac_f32_e32 v26, v12, v153
	v_fmac_f32_e32 v27, v12, v137
	v_fmac_f32_e32 v40, v12, v119
	v_lshlrev_b32_e32 v97, 16, v84
	v_and_b32_e32 v159, s40, v84
	v_lshlrev_b32_e32 v187, 16, v85
	v_and_b32_e32 v0, s40, v85
	v_lshlrev_b32_e32 v1, 16, v86
	v_and_b32_e32 v2, s40, v86
	v_lshlrev_b32_e32 v3, 16, v87
	v_and_b32_e32 v4, s40, v87
	v_lshlrev_b32_e32 v5, 16, v80
	v_and_b32_e32 v6, s40, v80
	v_lshlrev_b32_e32 v7, 16, v81
	v_and_b32_e32 v8, s40, v81
	v_lshlrev_b32_e32 v9, 16, v82
	v_and_b32_e32 v10, s40, v82
	v_lshlrev_b32_e32 v11, 16, v83
	v_and_b32_e32 v12, s40, v83
	v_mul_f32_e32 v59, v97, v97
	v_mul_f32_e32 v41, v97, v248
	v_mul_f32_e32 v42, v97, v232
	v_mul_f32_e32 v43, v97, v216
	v_mul_f32_e32 v44, v97, v200
	v_mul_f32_e32 v45, v97, v182
	v_mul_f32_e32 v46, v97, v166
	v_mul_f32_e32 v47, v97, v146
	v_mul_f32_e32 v48, v97, v130
	v_fmac_f32_e32 v59, v159, v159
	v_fmac_f32_e32 v41, v159, v249
	v_fmac_f32_e32 v42, v159, v233
	v_fmac_f32_e32 v43, v159, v217
	v_fmac_f32_e32 v44, v159, v201
	v_fmac_f32_e32 v45, v159, v183
	v_fmac_f32_e32 v46, v159, v167
	v_fmac_f32_e32 v47, v159, v147
	v_fmac_f32_e32 v48, v159, v131
	v_fmac_f32_e32 v59, v187, v187
	v_fmac_f32_e32 v41, v187, v250
	v_fmac_f32_e32 v42, v187, v234
	v_fmac_f32_e32 v43, v187, v218
	v_fmac_f32_e32 v44, v187, v202
	v_fmac_f32_e32 v45, v187, v184
	v_fmac_f32_e32 v46, v187, v168
	v_fmac_f32_e32 v47, v187, v148
	v_fmac_f32_e32 v48, v187, v132
	v_fmac_f32_e32 v59, v0, v0
	v_fmac_f32_e32 v41, v0, v251
	v_fmac_f32_e32 v42, v0, v235
	v_fmac_f32_e32 v43, v0, v219
	v_fmac_f32_e32 v44, v0, v203
	v_fmac_f32_e32 v45, v0, v185
	v_fmac_f32_e32 v46, v0, v169
	v_fmac_f32_e32 v47, v0, v149
	v_fmac_f32_e32 v48, v0, v133
; __device__ __forceinline__ void fgate_phase(const bfr* x, const float* wf, const float* bfg, float* cl, float* ctot, LAS float* scr, int bx, int G, int tid, int lane, int wave) {
;     ...
;             for (int jj = 0; jj < 4; ++jj) { const u32x2 wa = xa[64 * jj], wb = xb2[64 * jj]; va[jj] = (f32x4){bf_lo(wa.x), bf_hi(wa.x), bf_lo(wa.y), bf_hi(wa.y)}; vb[jj] = (f32x4){bf_lo(wb.x), bf_hi(wb.x), bf_lo(wb.y), bf_hi(wb.y)}; }
;             r[16] = 0.f; r[17] = 0.f;
; #pragma unroll
;             for (int jj = 0; jj < 4; ++jj) { r[16] += (va[jj].x * va[jj].x + va[jj].y * va[jj].y) + (va[jj].z * va[jj].z + va[jj].w * va[jj].w); r[17] += (vb[jj].x * vb[jj].x + vb[jj].y * vb[jj].y) + (vb[jj].z * vb[jj].z + vb[jj].w * vb[jj].w); }
; #pragma unroll
;             for (int h = 0; h < NH; ++h) { const f32x4* wr = (const f32x4*)(wf + h * D) + lane + zo; float da = 0.f, db = 0.f;
; #pragma unroll
;                 for (int jj = 0; jj < 4; ++jj) { const f32x4 w = wr[64 * jj]; da += (va[jj].x * w.x + va[jj].y * w.y) + (va[jj].z * w.z + va[jj].w * w.w); db += (vb[jj].x * w.x + vb[jj].y * w.y) + (vb[jj].z * w.z + vb[jj].w * w.w); }
;                 r[h] = da; r[8 + h] = db; }
	v_fmac_f32_e32 v59, v1, v1
	v_fmac_f32_e32 v41, v1, v244
	v_fmac_f32_e32 v42, v1, v228
	v_fmac_f32_e32 v43, v1, v212
	v_fmac_f32_e32 v44, v1, v196
	v_fmac_f32_e32 v45, v1, v178
	v_fmac_f32_e32 v46, v1, v162
	v_fmac_f32_e32 v47, v1, v142
	v_fmac_f32_e32 v48, v1, v124
	v_fmac_f32_e32 v59, v2, v2
	v_fmac_f32_e32 v41, v2, v245
	v_fmac_f32_e32 v42, v2, v229
	v_fmac_f32_e32 v43, v2, v213
	v_fmac_f32_e32 v44, v2, v197
	v_fmac_f32_e32 v45, v2, v179
	v_fmac_f32_e32 v46, v2, v163
	v_fmac_f32_e32 v47, v2, v143
	v_fmac_f32_e32 v48, v2, v125
	v_fmac_f32_e32 v59, v3, v3
	v_fmac_f32_e32 v41, v3, v246
	v_fmac_f32_e32 v42, v3, v230
	v_fmac_f32_e32 v43, v3, v214
	v_fmac_f32_e32 v44, v3, v198
	v_fmac_f32_e32 v45, v3, v180
	v_fmac_f32_e32 v46, v3, v164
	v_fmac_f32_e32 v47, v3, v144
	v_fmac_f32_e32 v48, v3, v126
	v_fmac_f32_e32 v59, v4, v4
	v_fmac_f32_e32 v41, v4, v247
	v_fmac_f32_e32 v42, v4, v231
	v_fmac_f32_e32 v43, v4, v215
	v_fmac_f32_e32 v44, v4, v199
	v_fmac_f32_e32 v45, v4, v181
	v_fmac_f32_e32 v46, v4, v165
	v_fmac_f32_e32 v47, v4, v145
	v_fmac_f32_e32 v48, v4, v127
	v_fmac_f32_e32 v59, v5, v5
	v_fmac_f32_e32 v41, v5, v240
	v_fmac_f32_e32 v42, v5, v224
	v_fmac_f32_e32 v43, v5, v208
	v_fmac_f32_e32 v44, v5, v192
	v_fmac_f32_e32 v45, v5, v174
	v_fmac_f32_e32 v46, v5, v154
	v_fmac_f32_e32 v47, v5, v138
	v_fmac_f32_e32 v48, v5, v120
	v_fmac_f32_e32 v59, v6, v6
	v_fmac_f32_e32 v41, v6, v241
	v_fmac_f32_e32 v42, v6, v225
	v_fmac_f32_e32 v43, v6, v209
	v_fmac_f32_e32 v44, v6, v193
	v_fmac_f32_e32 v45, v6, v175
	v_fmac_f32_e32 v46, v6, v155
	v_fmac_f32_e32 v47, v6, v139
	v_fmac_f32_e32 v48, v6, v121
	v_fmac_f32_e32 v59, v7, v7
	v_fmac_f32_e32 v41, v7, v242
	v_fmac_f32_e32 v42, v7, v226
	v_fmac_f32_e32 v43, v7, v210
	v_fmac_f32_e32 v44, v7, v194
	v_fmac_f32_e32 v45, v7, v176
	v_fmac_f32_e32 v46, v7, v156
	v_fmac_f32_e32 v47, v7, v140
	v_fmac_f32_e32 v48, v7, v122
	v_fmac_f32_e32 v59, v8, v8
	v_fmac_f32_e32 v41, v8, v243
	v_fmac_f32_e32 v42, v8, v227
	v_fmac_f32_e32 v43, v8, v211
	v_fmac_f32_e32 v44, v8, v195
	v_fmac_f32_e32 v45, v8, v177
	v_fmac_f32_e32 v46, v8, v157
	v_fmac_f32_e32 v47, v8, v141
	v_fmac_f32_e32 v48, v8, v123
	v_fmac_f32_e32 v59, v9, v9
	v_fmac_f32_e32 v41, v9, v236
	v_fmac_f32_e32 v42, v9, v220
	v_fmac_f32_e32 v43, v9, v204
	v_fmac_f32_e32 v44, v9, v188
	v_fmac_f32_e32 v45, v9, v170
	v_fmac_f32_e32 v46, v9, v150
	v_fmac_f32_e32 v47, v9, v134
	v_fmac_f32_e32 v48, v9, v116
	v_fmac_f32_e32 v59, v10, v10
	v_fmac_f32_e32 v41, v10, v237
	v_fmac_f32_e32 v42, v10, v221
	v_fmac_f32_e32 v43, v10, v205
	v_fmac_f32_e32 v44, v10, v189
	v_fmac_f32_e32 v45, v10, v171
	v_fmac_f32_e32 v46, v10, v151
	v_fmac_f32_e32 v47, v10, v135
	v_fmac_f32_e32 v48, v10, v117
	v_fmac_f32_e32 v59, v11, v11
	v_fmac_f32_e32 v41, v11, v238
	v_fmac_f32_e32 v42, v11, v222
	v_fmac_f32_e32 v43, v11, v206
	v_fmac_f32_e32 v44, v11, v190
	v_fmac_f32_e32 v45, v11, v172
	v_fmac_f32_e32 v46, v11, v152
	v_fmac_f32_e32 v47, v11, v136
	v_fmac_f32_e32 v48, v11, v118
	v_fmac_f32_e32 v59, v12, v12
	v_fmac_f32_e32 v41, v12, v239
	v_fmac_f32_e32 v42, v12, v223
	v_fmac_f32_e32 v43, v12, v207
	v_fmac_f32_e32 v44, v12, v191
	v_fmac_f32_e32 v45, v12, v173
	v_fmac_f32_e32 v46, v12, v153
	v_fmac_f32_e32 v47, v12, v137
	v_fmac_f32_e32 v48, v12, v119
	v_lshlrev_b32_e32 v97, 16, v76
	v_and_b32_e32 v159, s40, v76
	v_lshlrev_b32_e32 v187, 16, v77
	v_and_b32_e32 v0, s40, v77
	v_lshlrev_b32_e32 v1, 16, v78
	v_and_b32_e32 v2, s40, v78
	v_lshlrev_b32_e32 v3, 16, v79
	v_and_b32_e32 v4, s40, v79
	v_lshlrev_b32_e32 v5, 16, v72
	v_and_b32_e32 v6, s40, v72
	v_lshlrev_b32_e32 v7, 16, v73
	v_and_b32_e32 v8, s40, v73
	v_lshlrev_b32_e32 v9, 16, v74
	v_and_b32_e32 v10, s40, v74
	v_lshlrev_b32_e32 v11, 16, v75
	v_and_b32_e32 v12, s40, v75
	v_mul_f32_e32 v60, v97, v97
	v_mul_f32_e32 v49, v97, v248
	v_mul_f32_e32 v50, v97, v232
	v_mul_f32_e32 v51, v97, v216
	v_mul_f32_e32 v52, v97, v200
	v_mul_f32_e32 v53, v97, v182
	v_mul_f32_e32 v54, v97, v166
	v_mul_f32_e32 v55, v97, v146
	v_mul_f32_e32 v56, v97, v130
	v_fmac_f32_e32 v60, v159, v159
	v_fmac_f32_e32 v49, v159, v249
	v_fmac_f32_e32 v50, v159, v233
	v_fmac_f32_e32 v51, v159, v217
	v_fmac_f32_e32 v52, v159, v201
	v_fmac_f32_e32 v53, v159, v183
	v_fmac_f32_e32 v54, v159, v167
	v_fmac_f32_e32 v55, v159, v147
	v_fmac_f32_e32 v56, v159, v131
	v_fmac_f32_e32 v60, v187, v187
	v_fmac_f32_e32 v49, v187, v250
	v_fmac_f32_e32 v50, v187, v234
	v_fmac_f32_e32 v51, v187, v218
	v_fmac_f32_e32 v52, v187, v202
	v_fmac_f32_e32 v53, v187, v184
	v_fmac_f32_e32 v54, v187, v168
	v_fmac_f32_e32 v55, v187, v148
	v_fmac_f32_e32 v56, v187, v132
	v_fmac_f32_e32 v60, v0, v0
	v_fmac_f32_e32 v49, v0, v251
	v_fmac_f32_e32 v50, v0, v235
	v_fmac_f32_e32 v51, v0, v219
	v_fmac_f32_e32 v52, v0, v203
	v_fmac_f32_e32 v53, v0, v185
	v_fmac_f32_e32 v54, v0, v169
	v_fmac_f32_e32 v55, v0, v149
	v_fmac_f32_e32 v56, v0, v133
	v_fmac_f32_e32 v60, v1, v1
	v_fmac_f32_e32 v49, v1, v244
	v_fmac_f32_e32 v50, v1, v228
	v_fmac_f32_e32 v51, v1, v212
	v_fmac_f32_e32 v52, v1, v196
	v_fmac_f32_e32 v53, v1, v178
	v_fmac_f32_e32 v54, v1, v162
	v_fmac_f32_e32 v55, v1, v142
	v_fmac_f32_e32 v56, v1, v124
	v_fmac_f32_e32 v60, v2, v2
	v_fmac_f32_e32 v49, v2, v245
	v_fmac_f32_e32 v50, v2, v229
	v_fmac_f32_e32 v51, v2, v213
	v_fmac_f32_e32 v52, v2, v197
	v_fmac_f32_e32 v53, v2, v179
	v_fmac_f32_e32 v54, v2, v163
	v_fmac_f32_e32 v55, v2, v143
	v_fmac_f32_e32 v56, v2, v125
	v_fmac_f32_e32 v60, v3, v3
	v_fmac_f32_e32 v49, v3, v246
	v_fmac_f32_e32 v50, v3, v230
	v_fmac_f32_e32 v51, v3, v214
	v_fmac_f32_e32 v52, v3, v198
	v_fmac_f32_e32 v53, v3, v180
	v_fmac_f32_e32 v54, v3, v164
	v_fmac_f32_e32 v55, v3, v144
	v_fmac_f32_e32 v56, v3, v126
; __device__ __forceinline__ float lane_get(float v, int src_lane) { return __builtin_bit_cast(float, __builtin_amdgcn_ds_bpermute(src_lane << 2, __builtin_bit_cast(int, v))); }
; __device__ __forceinline__ void fgate_phase(const bfr* x, const float* wf, const float* bfg, float* cl, float* ctot, LAS float* scr, int bx, int G, int tid, int lane, int wave) {
;     ...
;             for (int h = 0; h < NH; ++h) { const f32x4* wr = (const f32x4*)(wf + h * D) + lane + zo; float da = 0.f, db = 0.f;
; #pragma unroll
;                 for (int jj = 0; jj < 4; ++jj) { const f32x4 w = wr[64 * jj]; da += (va[jj].x * w.x + va[jj].y * w.y) + (va[jj].z * w.z + va[jj].w * w.w); db += (vb[jj].x * w.x + vb[jj].y * w.y) + (vb[jj].z * w.z + vb[jj].w * w.w); }
;                 r[h] = da; r[8 + h] = db; }
; #pragma unroll
;             for (int o = 1; o < 64; o <<= 1) {
; #pragma unroll
;                 for (int q = 0; q < 18; ++q) r[q] += lane_get(r[q], lane ^ o); }
	v_fmac_f32_e32 v60, v4, v4
	v_fmac_f32_e32 v49, v4, v247
	v_fmac_f32_e32 v50, v4, v231
	v_fmac_f32_e32 v51, v4, v215
	v_fmac_f32_e32 v52, v4, v199
	v_fmac_f32_e32 v53, v4, v181
	v_fmac_f32_e32 v54, v4, v165
	v_fmac_f32_e32 v55, v4, v145
	v_fmac_f32_e32 v56, v4, v127
	v_fmac_f32_e32 v60, v5, v5
	v_fmac_f32_e32 v49, v5, v240
	v_fmac_f32_e32 v50, v5, v224
	v_fmac_f32_e32 v51, v5, v208
	v_fmac_f32_e32 v52, v5, v192
	v_fmac_f32_e32 v53, v5, v174
	v_fmac_f32_e32 v54, v5, v154
	v_fmac_f32_e32 v55, v5, v138
	v_fmac_f32_e32 v56, v5, v120
	v_fmac_f32_e32 v60, v6, v6
	v_fmac_f32_e32 v49, v6, v241
	v_fmac_f32_e32 v50, v6, v225
	v_fmac_f32_e32 v51, v6, v209
	v_fmac_f32_e32 v52, v6, v193
	v_fmac_f32_e32 v53, v6, v175
	v_fmac_f32_e32 v54, v6, v155
	v_fmac_f32_e32 v55, v6, v139
	v_fmac_f32_e32 v56, v6, v121
	v_fmac_f32_e32 v60, v7, v7
	v_fmac_f32_e32 v49, v7, v242
	v_fmac_f32_e32 v50, v7, v226
	v_fmac_f32_e32 v51, v7, v210
	v_fmac_f32_e32 v52, v7, v194
	v_fmac_f32_e32 v53, v7, v176
	v_fmac_f32_e32 v54, v7, v156
	v_fmac_f32_e32 v55, v7, v140
	v_fmac_f32_e32 v56, v7, v122
	v_fmac_f32_e32 v60, v8, v8
	v_fmac_f32_e32 v49, v8, v243
	v_fmac_f32_e32 v50, v8, v227
	v_fmac_f32_e32 v51, v8, v211
	v_fmac_f32_e32 v52, v8, v195
	v_fmac_f32_e32 v53, v8, v177
	v_fmac_f32_e32 v54, v8, v157
	v_fmac_f32_e32 v55, v8, v141
	v_fmac_f32_e32 v56, v8, v123
	v_fmac_f32_e32 v60, v9, v9
	v_fmac_f32_e32 v49, v9, v236
	v_fmac_f32_e32 v50, v9, v220
	v_fmac_f32_e32 v51, v9, v204
	v_fmac_f32_e32 v52, v9, v188
	v_fmac_f32_e32 v53, v9, v170
	v_fmac_f32_e32 v54, v9, v150
	v_fmac_f32_e32 v55, v9, v134
	v_fmac_f32_e32 v56, v9, v116
	v_fmac_f32_e32 v60, v10, v10
	v_fmac_f32_e32 v49, v10, v237
	v_fmac_f32_e32 v50, v10, v221
	v_fmac_f32_e32 v51, v10, v205
	v_fmac_f32_e32 v52, v10, v189
	v_fmac_f32_e32 v53, v10, v171
	v_fmac_f32_e32 v54, v10, v151
	v_fmac_f32_e32 v55, v10, v135
	v_fmac_f32_e32 v56, v10, v117
	v_fmac_f32_e32 v60, v11, v11
	v_fmac_f32_e32 v49, v11, v238
	v_fmac_f32_e32 v50, v11, v222
	v_fmac_f32_e32 v51, v11, v206
	v_fmac_f32_e32 v52, v11, v190
	v_fmac_f32_e32 v53, v11, v172
	v_fmac_f32_e32 v54, v11, v152
	v_fmac_f32_e32 v55, v11, v136
	v_fmac_f32_e32 v56, v11, v118
	v_fmac_f32_e32 v60, v12, v12
	v_fmac_f32_e32 v49, v12, v239
	v_fmac_f32_e32 v50, v12, v223
	v_fmac_f32_e32 v51, v12, v207
	v_fmac_f32_e32 v52, v12, v191
	v_fmac_f32_e32 v53, v12, v173
	v_fmac_f32_e32 v54, v12, v153
	v_fmac_f32_e32 v55, v12, v137
	v_fmac_f32_e32 v56, v12, v119
	s_nop 1
	v_permlane32_swap_b32_e32 v13, v41
	v_permlane32_swap_b32_e32 v14, v42
	v_permlane32_swap_b32_e32 v15, v43
	v_permlane32_swap_b32_e32 v16, v44
	v_permlane32_swap_b32_e32 v17, v45
	v_permlane32_swap_b32_e32 v18, v46
	v_permlane32_swap_b32_e32 v19, v47
	v_permlane32_swap_b32_e32 v20, v48
	v_permlane32_swap_b32_e32 v21, v49
	v_permlane32_swap_b32_e32 v22, v50
	v_permlane32_swap_b32_e32 v23, v51
	v_permlane32_swap_b32_e32 v24, v52
	v_permlane32_swap_b32_e32 v25, v53
	v_permlane32_swap_b32_e32 v26, v54
	v_permlane32_swap_b32_e32 v27, v55
	v_permlane32_swap_b32_e32 v40, v56
	v_permlane32_swap_b32_e32 v57, v59
	v_permlane32_swap_b32_e32 v58, v60
	s_nop 1
	v_add_f32_e32 v13, v13, v41
	v_add_f32_e32 v14, v14, v42
	v_add_f32_e32 v15, v15, v43
	v_add_f32_e32 v16, v16, v44
	v_add_f32_e32 v17, v17, v45
	v_add_f32_e32 v18, v18, v46
	v_add_f32_e32 v19, v19, v47
	v_add_f32_e32 v20, v20, v48
	v_add_f32_e32 v21, v21, v49
	v_add_f32_e32 v22, v22, v50
	v_add_f32_e32 v23, v23, v51
	v_add_f32_e32 v24, v24, v52
	v_add_f32_e32 v25, v25, v53
	v_add_f32_e32 v26, v26, v54
	v_add_f32_e32 v27, v27, v55
	v_add_f32_e32 v40, v40, v56
	v_add_f32_e32 v57, v57, v59
	v_add_f32_e32 v58, v58, v60
	s_nop 1
	v_permlane16_swap_b32_e32 v13, v21
	v_permlane16_swap_b32_e32 v14, v22
	v_permlane16_swap_b32_e32 v15, v23
	v_permlane16_swap_b32_e32 v16, v24
	v_permlane16_swap_b32_e32 v17, v25
	v_permlane16_swap_b32_e32 v18, v26
; __device__ __forceinline__ float lane_get(float v, int src_lane) { return __builtin_bit_cast(float, __builtin_amdgcn_ds_bpermute(src_lane << 2, __builtin_bit_cast(int, v))); }
; __device__ __forceinline__ void fgate_phase(const bfr* x, const float* wf, const float* bfg, float* cl, float* ctot, LAS float* scr, int bx, int G, int tid, int lane, int wave) {
;     ...
;             for (int o = 1; o < 64; o <<= 1) {
; #pragma unroll
;                 for (int q = 0; q < 18; ++q) r[q] += lane_get(r[q], lane ^ o); }
;             const float rsa = rsqrtf(r[16] * (1.f / D) + EPS), rsb = rsqrtf(r[17] * (1.f / D) + EPS);
;             if (lane < 16) { const int h = lane & 7; float dsel = r[0];
; #pragma unroll
;                 for (int q = 1; q < 16; ++q) dsel = (lane == q) ? r[q] : dsel;
;                 const float zz = dsel * (lane < 8 ? rsa : rsb) + bfg[h]; const float lf = fminf(zz, 0.f) - 0.6931471805599453f * __builtin_amdgcn_logf(1.0f + __builtin_amdgcn_exp2f(-LOG2E * fabsf(zz)));
;                 scr[(wave * 8 + j + (lane >> 3)) * 8 + h] = lf; } }
	v_permlane16_swap_b32_e32 v19, v27
	v_permlane16_swap_b32_e32 v20, v40
	v_permlane16_swap_b32_e32 v57, v58
	s_nop 1
	v_add_f32_e32 v13, v13, v21
	v_add_f32_e32 v14, v14, v22
	v_add_f32_e32 v15, v15, v23
	v_add_f32_e32 v16, v16, v24
	v_add_f32_e32 v17, v17, v25
	v_add_f32_e32 v18, v18, v26
	v_add_f32_e32 v19, v19, v27
	v_add_f32_e32 v20, v20, v40
	v_add_f32_e32 v57, v57, v58
	s_nop 1
	v_add_f32_dpp v13, v13, v13 quad_perm:[1,0,3,2] row_mask:0xf bank_mask:0xf
	v_add_f32_dpp v14, v14, v14 quad_perm:[1,0,3,2] row_mask:0xf bank_mask:0xf
	v_add_f32_dpp v15, v15, v15 quad_perm:[1,0,3,2] row_mask:0xf bank_mask:0xf
	v_add_f32_dpp v16, v16, v16 quad_perm:[1,0,3,2] row_mask:0xf bank_mask:0xf
	v_add_f32_dpp v17, v17, v17 quad_perm:[1,0,3,2] row_mask:0xf bank_mask:0xf
	v_add_f32_dpp v18, v18, v18 quad_perm:[1,0,3,2] row_mask:0xf bank_mask:0xf
	v_add_f32_dpp v19, v19, v19 quad_perm:[1,0,3,2] row_mask:0xf bank_mask:0xf
	v_add_f32_dpp v20, v20, v20 quad_perm:[1,0,3,2] row_mask:0xf bank_mask:0xf
	v_add_f32_dpp v57, v57, v57 quad_perm:[1,0,3,2] row_mask:0xf bank_mask:0xf
	s_nop 1
	v_add_f32_dpp v13, v13, v13 quad_perm:[2,3,0,1] row_mask:0xf bank_mask:0xf
	v_add_f32_dpp v14, v14, v14 quad_perm:[2,3,0,1] row_mask:0xf bank_mask:0xf
	v_add_f32_dpp v15, v15, v15 quad_perm:[2,3,0,1] row_mask:0xf bank_mask:0xf
	v_add_f32_dpp v16, v16, v16 quad_perm:[2,3,0,1] row_mask:0xf bank_mask:0xf
	v_add_f32_dpp v17, v17, v17 quad_perm:[2,3,0,1] row_mask:0xf bank_mask:0xf
	v_add_f32_dpp v18, v18, v18 quad_perm:[2,3,0,1] row_mask:0xf bank_mask:0xf
	v_add_f32_dpp v19, v19, v19 quad_perm:[2,3,0,1] row_mask:0xf bank_mask:0xf
	v_add_f32_dpp v20, v20, v20 quad_perm:[2,3,0,1] row_mask:0xf bank_mask:0xf
	v_add_f32_dpp v57, v57, v57 quad_perm:[2,3,0,1] row_mask:0xf bank_mask:0xf
	s_nop 1
	v_add_f32_dpp v13, v13, v13 row_half_mirror row_mask:0xf bank_mask:0xf
	v_add_f32_dpp v14, v14, v14 row_half_mirror row_mask:0xf bank_mask:0xf
	v_add_f32_dpp v15, v15, v15 row_half_mirror row_mask:0xf bank_mask:0xf
	v_add_f32_dpp v16, v16, v16 row_half_mirror row_mask:0xf bank_mask:0xf
	v_add_f32_dpp v17, v17, v17 row_half_mirror row_mask:0xf bank_mask:0xf
	v_add_f32_dpp v18, v18, v18 row_half_mirror row_mask:0xf bank_mask:0xf
	v_add_f32_dpp v19, v19, v19 row_half_mirror row_mask:0xf bank_mask:0xf
	v_add_f32_dpp v20, v20, v20 row_half_mirror row_mask:0xf bank_mask:0xf
	v_add_f32_dpp v57, v57, v57 row_half_mirror row_mask:0xf bank_mask:0xf
	s_nop 1
	v_add_f32_dpp v13, v13, v13 row_mirror row_mask:0xf bank_mask:0xf
	v_add_f32_dpp v14, v14, v14 row_mirror row_mask:0xf bank_mask:0xf
	v_add_f32_dpp v15, v15, v15 row_mirror row_mask:0xf bank_mask:0xf
	v_add_f32_dpp v16, v16, v16 row_mirror row_mask:0xf bank_mask:0xf
	v_add_f32_dpp v17, v17, v17 row_mirror row_mask:0xf bank_mask:0xf
	v_add_f32_dpp v18, v18, v18 row_mirror row_mask:0xf bank_mask:0xf
	v_add_f32_dpp v19, v19, v19 row_mirror row_mask:0xf bank_mask:0xf
	v_add_f32_dpp v20, v20, v20 row_mirror row_mask:0xf bank_mask:0xf
	v_add_f32_dpp v57, v57, v57 row_mirror row_mask:0xf bank_mask:0xf
	s_nop 1
	v_mov_b32_e32 v62, v13
	v_cndmask_b32_e64 v62, v62, v14, s[6:7]
	v_cndmask_b32_e64 v62, v62, v15, s[8:9]
	v_cndmask_b32_e64 v62, v62, v16, s[10:11]
	v_cndmask_b32_e64 v62, v62, v17, s[12:13]
	v_cndmask_b32_e64 v62, v62, v18, s[14:15]
	v_cndmask_b32_e64 v62, v62, v19, s[16:17]
	v_cndmask_b32_e64 v62, v62, v20, s[18:19]
	v_mul_f32_e32 v63, 0x3a800000, v57
	v_add_f32_e32 v63, 0x358637bd, v63
	v_rsq_f32_e32 v63, v63
	s_nop 0
	v_fma_f32 v62, v62, v63, v61
	v_mul_f32_e64 v63, |v62|, s65
	v_exp_f32_e32 v63, v63
	v_min_f32_e32 v62, 0, v62
	v_add_f32_e32 v63, 1.0, v63
	v_log_f32_e32 v63, v63
	s_nop 0
	v_fmac_f32_e32 v62, 0xbf317218, v63
	s_mov_b64 s[54:55], exec
	s_mov_b32 exec_lo, 0xff00ff
	s_mov_b32 exec_hi, 0xff00ff
	ds_write_b32 v65, v62 offset:128
	s_mov_b64 exec, s[54:55]
